# K-loop load segments: M0 writes hoisted above the preceding VALU/DS instruction, 64 hazard s_nop removed
# speedup vs baseline: 1.0109x; 1.0109x over previous
; #define PG8_STAGE(bufoff, gbase, voff) do { _Pragma("unroll") for (int _i = 0; _i < 2; ++_i) \
;         __builtin_amdgcn_global_load_lds((const unsigned*)((const char*)(gbase) + (voff)[_i]), (LAS unsigned*)(lds + (bufoff) + ldsw + _i * 8192), 16, 0, 0); } while (0)
; #define PG8_LDA(dst, b, h) do { _Pragma("unroll") for (int m = 0; m < 4; ++m) _Pragma("unroll") for (int k = 0; k < 2; ++k) dst[m][k] = *(const LAS bf16x8*)(lds + PG8_SA(b, h) + aoff + m * 2048 + k * 1024); } while (0)
; #define PG8_LDB(dst, b, h) do { _Pragma("unroll") for (int n = 0; n < 2; ++n) _Pragma("unroll") for (int k = 0; k < 2; ++k) dst[n][k] = *(const LAS bf16x8*)(lds + PG8_SB(b, h) + boff + n * 2048 + k * 1024); } while (0)
; #define PG8_MMA(ai, bj, At, Bt) do { __builtin_amdgcn_s_setprio(1); _Pragma("unroll") for (int m = 0; m < 4; ++m) _Pragma("unroll") for (int n = 0; n < 2; ++n) _Pragma("unroll") for (int k = 0; k < 2; ++k) \
;         acc[ai][bj][m][n] = __builtin_amdgcn_mfma_f32_16x16x32_bf16(Bt[n][k], At[m][k], acc[ai][bj][m][n], 0, 0, 0); __builtin_amdgcn_s_setprio(0); } while (0)
; #define PG8_WAIT_V(n) asm volatile("s_waitcnt vmcnt(" #n ")" ::: "memory")
; #define PG8_WAIT_L(n) asm volatile("s_waitcnt lgkmcnt(" #n ")" ::: "memory")
; #define PG8_BAR __builtin_amdgcn_s_barrier()
; template <class Epi>
; __device__ __forceinline__ void gemm_phase(LAS unsigned char* lds, const Gemm g, const StaticOrder& S, const Epi& E, const int tid) {
;     ...
;             const char* a2 = last ? nA : (s2 ? cA2 + (size_t)(t + 2 - nt) * kstep : cA + (size_t)(t + 2) * kstep);
;             const char* b2 = last ? nB : (s2 ? cB2 + (size_t)(t + 2 - nt) * kstep : cB + (size_t)(t + 2) * kstep);
;             const char* a3 = a2 + kstep; const char* b3 = b2 + kstep;
;             if constexpr (Epi::TWO) { if (t == nt) E.mid(acc, cur, wr, wc, fr, fq); }
;             if constexpr (SP2) {
;             PG8_LDB(B0, 0, 0); PG8_LDB(B1, 0, 1); PG8_SCHED; PG8_LDA(At, 0, 0); PG8_STAGE(PG8_SA(1, 1), a1 + hstep, voffA);
;             PG8_WAIT_V(8); PG8_WAIT_L(0); PG8_BAR; PG8_MMA(0, 0, At, B0); PG8_MMA(0, 1, At, B1); PG8_BAR; PG8_SCHED;
;             PG8_LDA(At, 0, 1); PG8_STAGE(PG8_SB(0, 0), b2, voffB); PG8_STAGE(PG8_SB(0, 1), b2 + bhs, voffB); PG8_STAGE(PG8_SA(0, 0), a2, voffA);
;             PG8_WAIT_V(8); PG8_WAIT_L(0); PG8_BAR; PG8_MMA(1, 0, At, B0); PG8_MMA(1, 1, At, B1); PG8_BAR; PG8_SCHED;
.LBB0_126:
	s_add_u32 s30, s28, 0xffe00080
	s_addc_u32 s31, s29, -1
	s_add_i32 s52, 0, 0x10000
	s_cmpk_eq_i32 s51, 0x7c
	s_cselect_b32 s35, s17, s31
	s_cselect_b32 s34, s27, s30
	s_cselect_b32 s31, s15, s50
	s_cselect_b32 s30, s33, s49
	s_add_i32 s54, 0, 0x14000
	v_add_u32_e32 v30, s52, v193
	v_add_u32_e32 v54, s54, v193
	ds_read_b128 v[18:21], v30
	ds_read_b128 v[22:25], v30 offset:1024
	ds_read_b128 v[26:29], v30 offset:2048
	ds_read_b128 v[30:33], v30 offset:3072
	ds_read_b128 v[42:45], v54
	ds_read_b128 v[46:49], v54 offset:1024
	ds_read_b128 v[50:53], v54 offset:2048
	ds_read_b128 v[54:57], v54 offset:3072
	v_lshl_add_u64 v[172:173], s[28:29], 0, v[180:181]
	s_add_i32 m0, s37, 0xc000
	ds_read_b128 v[182:185], v199
	global_load_lds_dwordx4 v[172:173], off
	ds_read_b128 v[186:189], v199 offset:1024
	ds_read_b128 v[212:215], v199 offset:2048
	s_add_i32 m0, s37, 0xe000
	v_lshl_add_u64 v[172:173], s[28:29], 0, v[178:179]
	global_load_lds_dwordx4 v[172:173], off
	ds_read_b128 v[216:219], v199 offset:3072
	ds_read_b128 v[220:223], v199 offset:4096
	ds_read_b128 v[224:227], v199 offset:5120
	ds_read_b128 v[228:231], v199 offset:6144
	ds_read_b128 v[232:235], v199 offset:7168
	s_waitcnt vmcnt(8)
	s_waitcnt lgkmcnt(0)
	s_barrier
	s_setprio 1
	s_waitcnt lgkmcnt(0)
	v_mfma_f32_16x16x32_bf16 v[158:161], v[18:21], v[182:185], v[158:161]
	v_mfma_f32_16x16x32_bf16 v[154:157], v[26:29], v[182:185], v[154:157]
	v_mfma_f32_16x16x32_bf16 v[142:145], v[18:21], v[212:215], v[142:145]
	v_mfma_f32_16x16x32_bf16 v[138:141], v[26:29], v[212:215], v[138:141]
	v_mfma_f32_16x16x32_bf16 v[126:129], v[18:21], v[220:223], v[126:129]
	v_mfma_f32_16x16x32_bf16 v[122:125], v[26:29], v[220:223], v[122:125]
	v_mfma_f32_16x16x32_bf16 v[110:113], v[18:21], v[228:231], v[110:113]
	v_mfma_f32_16x16x32_bf16 v[106:109], v[26:29], v[228:231], v[106:109]
	v_mfma_f32_16x16x32_bf16 v[158:161], v[22:25], v[186:189], v[158:161]
	v_mfma_f32_16x16x32_bf16 v[154:157], v[30:33], v[186:189], v[154:157]
	v_mfma_f32_16x16x32_bf16 v[142:145], v[22:25], v[216:219], v[142:145]
	v_mfma_f32_16x16x32_bf16 v[138:141], v[30:33], v[216:219], v[138:141]
	v_mfma_f32_16x16x32_bf16 v[126:129], v[22:25], v[224:227], v[126:129]
	v_mfma_f32_16x16x32_bf16 v[122:125], v[30:33], v[224:227], v[122:125]
	v_mfma_f32_16x16x32_bf16 v[110:113], v[22:25], v[232:235], v[110:113]
	v_mfma_f32_16x16x32_bf16 v[106:109], v[30:33], v[232:235], v[106:109]
	s_setprio 0
	s_setprio 1
	v_mfma_f32_16x16x32_bf16 v[150:153], v[42:45], v[182:185], v[150:153]
	v_mfma_f32_16x16x32_bf16 v[146:149], v[50:53], v[182:185], v[146:149]
	v_mfma_f32_16x16x32_bf16 v[134:137], v[42:45], v[212:215], v[134:137]
	v_mfma_f32_16x16x32_bf16 v[130:133], v[50:53], v[212:215], v[130:133]
	v_mfma_f32_16x16x32_bf16 v[118:121], v[42:45], v[220:223], v[118:121]
	v_mfma_f32_16x16x32_bf16 v[114:117], v[50:53], v[220:223], v[114:117]
	v_mfma_f32_16x16x32_bf16 v[102:105], v[42:45], v[228:231], v[102:105]
	v_mfma_f32_16x16x32_bf16 v[98:101], v[50:53], v[228:231], v[98:101]
	v_mfma_f32_16x16x32_bf16 v[150:153], v[46:49], v[186:189], v[150:153]
	v_mfma_f32_16x16x32_bf16 v[146:149], v[54:57], v[186:189], v[146:149]
	v_mfma_f32_16x16x32_bf16 v[134:137], v[46:49], v[216:219], v[134:137]
	v_mfma_f32_16x16x32_bf16 v[130:133], v[54:57], v[216:219], v[130:133]
	v_mfma_f32_16x16x32_bf16 v[118:121], v[46:49], v[224:227], v[118:121]
	v_mfma_f32_16x16x32_bf16 v[114:117], v[54:57], v[224:227], v[114:117]
	v_mfma_f32_16x16x32_bf16 v[102:105], v[46:49], v[232:235], v[102:105]
	v_mfma_f32_16x16x32_bf16 v[98:101], v[54:57], v[232:235], v[98:101]
	s_setprio 0
	s_barrier
	s_add_i32 s52, s52, s36
	v_lshl_add_u64 v[172:173], s[30:31], 0, v[0:1]
	s_mov_b32 m0, s52
	ds_read_b128 v[182:185], v199 offset:16384
	global_load_lds_dwordx4 v[172:173], off
	ds_read_b128 v[186:189], v199 offset:17408
	ds_read_b128 v[212:215], v199 offset:18432
	s_add_i32 m0, s52, 0x2000
	s_add_u32 s52, s30, 0x20000
	v_lshl_add_u64 v[174:175], s[30:31], 0, v[166:167]
	s_addc_u32 s53, s31, 0
	s_add_i32 s54, s54, s36
	global_load_lds_dwordx4 v[174:175], off
	ds_read_b128 v[216:219], v199 offset:19456
	ds_read_b128 v[220:223], v199 offset:20480
	v_lshl_add_u64 v[176:177], s[52:53], 0, v[0:1]
	s_mov_b32 m0, s54
	v_lshl_add_u64 v[200:201], s[34:35], 0, v[164:165]
	global_load_lds_dwordx4 v[176:177], off
	ds_read_b128 v[224:227], v199 offset:21504
	ds_read_b128 v[228:231], v199 offset:22528
	s_add_i32 m0, s54, 0x2000
	v_lshl_add_u64 v[176:177], s[52:53], 0, v[166:167]
	global_load_lds_dwordx4 v[176:177], off
	ds_read_b128 v[232:235], v199 offset:23552
	s_mov_b32 m0, s37
	v_lshl_add_u64 v[176:177], s[34:35], 0, v[162:163]
	global_load_lds_dwordx4 v[176:177], off
	s_mov_b32 m0, s38
	s_nop 0
	global_load_lds_dwordx4 v[200:201], off
	s_waitcnt vmcnt(8)
	s_waitcnt lgkmcnt(0)
	s_barrier
; #define PG8_STAGE(bufoff, gbase, voff) do { _Pragma("unroll") for (int _i = 0; _i < 2; ++_i) \
;         __builtin_amdgcn_global_load_lds((const unsigned*)((const char*)(gbase) + (voff)[_i]), (LAS unsigned*)(lds + (bufoff) + ldsw + _i * 8192), 16, 0, 0); } while (0)
; #define PG8_LDA(dst, b, h) do { _Pragma("unroll") for (int m = 0; m < 4; ++m) _Pragma("unroll") for (int k = 0; k < 2; ++k) dst[m][k] = *(const LAS bf16x8*)(lds + PG8_SA(b, h) + aoff + m * 2048 + k * 1024); } while (0)
; #define PG8_LDB(dst, b, h) do { _Pragma("unroll") for (int n = 0; n < 2; ++n) _Pragma("unroll") for (int k = 0; k < 2; ++k) dst[n][k] = *(const LAS bf16x8*)(lds + PG8_SB(b, h) + boff + n * 2048 + k * 1024); } while (0)
; #define PG8_MMA(ai, bj, At, Bt) do { __builtin_amdgcn_s_setprio(1); _Pragma("unroll") for (int m = 0; m < 4; ++m) _Pragma("unroll") for (int n = 0; n < 2; ++n) _Pragma("unroll") for (int k = 0; k < 2; ++k) \
;         acc[ai][bj][m][n] = __builtin_amdgcn_mfma_f32_16x16x32_bf16(Bt[n][k], At[m][k], acc[ai][bj][m][n], 0, 0, 0); __builtin_amdgcn_s_setprio(0); } while (0)
; #define PG8_WAIT_V(n) asm volatile("s_waitcnt vmcnt(" #n ")" ::: "memory")
; #define PG8_WAIT_L(n) asm volatile("s_waitcnt lgkmcnt(" #n ")" ::: "memory")
; #define PG8_BAR __builtin_amdgcn_s_barrier()
; #define PG8_SCHED __builtin_amdgcn_sched_barrier(0)
; template <class Epi>
; __device__ __forceinline__ void gemm_phase(LAS unsigned char* lds, const Gemm g, const StaticOrder& S, const Epi& E, const int tid) {
;     ...
;             PG8_WAIT_V(8); PG8_WAIT_L(0); PG8_BAR; PG8_MMA(1, 0, At, B0); PG8_MMA(1, 1, At, B1); PG8_BAR; PG8_SCHED;
;             PG8_LDB(B0, 1, 0); PG8_LDB(B1, 1, 1); PG8_SCHED; PG8_LDA(At, 1, 0); PG8_STAGE(PG8_SA(0, 1), a2 + hstep, voffA);
;             PG8_WAIT_V(8); PG8_WAIT_L(0); PG8_BAR; PG8_MMA(0, 0, At, B0); PG8_MMA(0, 1, At, B1); PG8_BAR; PG8_SCHED;
	s_setprio 1
	s_waitcnt lgkmcnt(0)
	v_mfma_f32_16x16x32_bf16 v[94:97], v[18:21], v[182:185], v[94:97]
	v_mfma_f32_16x16x32_bf16 v[90:93], v[26:29], v[182:185], v[90:93]
	v_mfma_f32_16x16x32_bf16 v[78:81], v[18:21], v[212:215], v[78:81]
	v_mfma_f32_16x16x32_bf16 v[74:77], v[26:29], v[212:215], v[74:77]
	v_mfma_f32_16x16x32_bf16 v[62:65], v[18:21], v[220:223], v[62:65]
	v_mfma_f32_16x16x32_bf16 v[58:61], v[26:29], v[220:223], v[58:61]
	v_mfma_f32_16x16x32_bf16 v[14:17], v[18:21], v[228:231], v[14:17]
	v_mfma_f32_16x16x32_bf16 v[10:13], v[26:29], v[228:231], v[10:13]
	v_mfma_f32_16x16x32_bf16 v[94:97], v[22:25], v[186:189], v[94:97]
	v_mfma_f32_16x16x32_bf16 v[90:93], v[30:33], v[186:189], v[90:93]
	v_mfma_f32_16x16x32_bf16 v[78:81], v[22:25], v[216:219], v[78:81]
	v_mfma_f32_16x16x32_bf16 v[74:77], v[30:33], v[216:219], v[74:77]
	v_mfma_f32_16x16x32_bf16 v[62:65], v[22:25], v[224:227], v[62:65]
	v_mfma_f32_16x16x32_bf16 v[58:61], v[30:33], v[224:227], v[58:61]
	v_mfma_f32_16x16x32_bf16 v[14:17], v[22:25], v[232:235], v[14:17]
	v_mfma_f32_16x16x32_bf16 v[10:13], v[30:33], v[232:235], v[10:13]
	s_setprio 0
	s_setprio 1
	v_mfma_f32_16x16x32_bf16 v[38:41], v[42:45], v[220:223], v[38:41]
	v_mfma_f32_16x16x32_bf16 v[34:37], v[50:53], v[220:223], v[34:37]
	v_mfma_f32_16x16x32_bf16 v[6:9], v[42:45], v[228:231], v[6:9]
	v_mfma_f32_16x16x32_bf16 v[2:5], v[50:53], v[228:231], v[2:5]
	v_mfma_f32_16x16x32_bf16 v[18:21], v[42:45], v[182:185], v[86:89]
	v_mfma_f32_16x16x32_bf16 v[22:25], v[50:53], v[182:185], v[82:85]
	v_mfma_f32_16x16x32_bf16 v[26:29], v[42:45], v[212:215], v[70:73]
	v_mfma_f32_16x16x32_bf16 v[30:33], v[50:53], v[212:215], v[66:69]
	v_mfma_f32_16x16x32_bf16 v[38:41], v[46:49], v[224:227], v[38:41]
	v_mfma_f32_16x16x32_bf16 v[34:37], v[54:57], v[224:227], v[34:37]
	v_mfma_f32_16x16x32_bf16 v[6:9], v[46:49], v[232:235], v[6:9]
	v_mfma_f32_16x16x32_bf16 v[2:5], v[54:57], v[232:235], v[2:5]
	v_mfma_f32_16x16x32_bf16 v[18:21], v[46:49], v[186:189], v[18:21]
	v_mfma_f32_16x16x32_bf16 v[22:25], v[54:57], v[186:189], v[22:25]
	v_mfma_f32_16x16x32_bf16 v[26:29], v[46:49], v[216:219], v[26:29]
	v_mfma_f32_16x16x32_bf16 v[30:33], v[54:57], v[216:219], v[30:33]
	s_setprio 0
	s_barrier
	s_add_i32 s52, 0, 0x18000
	s_add_i32 s53, 0, 0x1c000
	v_add_u32_e32 v54, s52, v193
	v_add_u32_e32 v66, s53, v193
	ds_read_b128 v[42:45], v54
	ds_read_b128 v[46:49], v54 offset:1024
	ds_read_b128 v[50:53], v54 offset:2048
	ds_read_b128 v[54:57], v54 offset:3072
	ds_read_b128 v[182:185], v66
	ds_read_b128 v[186:189], v66 offset:1024
	ds_read_b128 v[212:215], v66 offset:2048
	ds_read_b128 v[216:219], v66 offset:3072
	s_add_u32 s34, s34, 0x200000
	s_addc_u32 s35, s35, 0
	s_mov_b32 m0, s39
	v_lshl_add_u64 v[236:237], s[34:35], 0, v[162:163]
	ds_read_b128 v[66:69], v199 offset:32768
	global_load_lds_dwordx4 v[236:237], off
	ds_read_b128 v[70:73], v199 offset:33792
	ds_read_b128 v[82:85], v199 offset:34816
	s_mov_b32 m0, s44
	v_lshl_add_u64 v[236:237], s[34:35], 0, v[164:165]
	global_load_lds_dwordx4 v[236:237], off
	ds_read_b128 v[86:89], v199 offset:35840
	ds_read_b128 v[220:223], v199 offset:36864
	ds_read_b128 v[224:227], v199 offset:37888
	ds_read_b128 v[228:231], v199 offset:38912
	ds_read_b128 v[232:235], v199 offset:39936
	s_waitcnt vmcnt(8)
	s_waitcnt lgkmcnt(0)
	s_barrier
	s_setprio 1
	s_waitcnt lgkmcnt(0)
	v_mfma_f32_16x16x32_bf16 v[158:161], v[42:45], v[66:69], v[158:161]
	v_mfma_f32_16x16x32_bf16 v[154:157], v[50:53], v[66:69], v[154:157]
	v_mfma_f32_16x16x32_bf16 v[142:145], v[42:45], v[82:85], v[142:145]
	v_mfma_f32_16x16x32_bf16 v[138:141], v[50:53], v[82:85], v[138:141]
	v_mfma_f32_16x16x32_bf16 v[126:129], v[42:45], v[220:223], v[126:129]
	v_mfma_f32_16x16x32_bf16 v[122:125], v[50:53], v[220:223], v[122:125]
	v_mfma_f32_16x16x32_bf16 v[110:113], v[42:45], v[228:231], v[110:113]
	v_mfma_f32_16x16x32_bf16 v[106:109], v[50:53], v[228:231], v[106:109]
	v_mfma_f32_16x16x32_bf16 v[158:161], v[46:49], v[70:73], v[158:161]
	v_mfma_f32_16x16x32_bf16 v[154:157], v[54:57], v[70:73], v[154:157]
	v_mfma_f32_16x16x32_bf16 v[142:145], v[46:49], v[86:89], v[142:145]
	v_mfma_f32_16x16x32_bf16 v[138:141], v[54:57], v[86:89], v[138:141]
	v_mfma_f32_16x16x32_bf16 v[126:129], v[46:49], v[224:227], v[126:129]
	v_mfma_f32_16x16x32_bf16 v[122:125], v[54:57], v[224:227], v[122:125]
	v_mfma_f32_16x16x32_bf16 v[110:113], v[46:49], v[232:235], v[110:113]
	v_mfma_f32_16x16x32_bf16 v[106:109], v[54:57], v[232:235], v[106:109]
	s_setprio 0
	s_setprio 1
	v_mfma_f32_16x16x32_bf16 v[150:153], v[182:185], v[66:69], v[150:153]
	v_mfma_f32_16x16x32_bf16 v[66:69], v[212:215], v[66:69], v[146:149]
	v_mfma_f32_16x16x32_bf16 v[146:149], v[216:219], v[70:73], v[66:69]
	v_mfma_f32_16x16x32_bf16 v[66:69], v[182:185], v[82:85], v[134:137]
	v_mfma_f32_16x16x32_bf16 v[134:137], v[186:189], v[86:89], v[66:69]
	v_mfma_f32_16x16x32_bf16 v[66:69], v[212:215], v[82:85], v[130:133]
	v_mfma_f32_16x16x32_bf16 v[130:133], v[216:219], v[86:89], v[66:69]
	v_mfma_f32_16x16x32_bf16 v[66:69], v[182:185], v[220:223], v[118:121]
	v_mfma_f32_16x16x32_bf16 v[118:121], v[186:189], v[224:227], v[66:69]
	v_mfma_f32_16x16x32_bf16 v[66:69], v[212:215], v[220:223], v[114:117]
	v_mfma_f32_16x16x32_bf16 v[114:117], v[216:219], v[224:227], v[66:69]
	v_mfma_f32_16x16x32_bf16 v[66:69], v[182:185], v[228:231], v[102:105]
	v_mfma_f32_16x16x32_bf16 v[102:105], v[186:189], v[232:235], v[66:69]
	v_mfma_f32_16x16x32_bf16 v[66:69], v[212:215], v[228:231], v[98:101]
	v_mfma_f32_16x16x32_bf16 v[150:153], v[186:189], v[70:73], v[150:153]
	v_mfma_f32_16x16x32_bf16 v[98:101], v[216:219], v[232:235], v[66:69]
	s_setprio 0
	s_barrier
; #define PG8_STAGE(bufoff, gbase, voff) do { _Pragma("unroll") for (int _i = 0; _i < 2; ++_i) \
;         __builtin_amdgcn_global_load_lds((const unsigned*)((const char*)(gbase) + (voff)[_i]), (LAS unsigned*)(lds + (bufoff) + ldsw + _i * 8192), 16, 0, 0); } while (0)
; #define PG8_LDA(dst, b, h) do { _Pragma("unroll") for (int m = 0; m < 4; ++m) _Pragma("unroll") for (int k = 0; k < 2; ++k) dst[m][k] = *(const LAS bf16x8*)(lds + PG8_SA(b, h) + aoff + m * 2048 + k * 1024); } while (0)
; #define PG8_MMA(ai, bj, At, Bt) do { __builtin_amdgcn_s_setprio(1); _Pragma("unroll") for (int m = 0; m < 4; ++m) _Pragma("unroll") for (int n = 0; n < 2; ++n) _Pragma("unroll") for (int k = 0; k < 2; ++k) \
;         acc[ai][bj][m][n] = __builtin_amdgcn_mfma_f32_16x16x32_bf16(Bt[n][k], At[m][k], acc[ai][bj][m][n], 0, 0, 0); __builtin_amdgcn_s_setprio(0); } while (0)
; #define PG8_WAIT_V(n) asm volatile("s_waitcnt vmcnt(" #n ")" ::: "memory")
; #define PG8_WAIT_L(n) asm volatile("s_waitcnt lgkmcnt(" #n ")" ::: "memory")
; #define PG8_BAR __builtin_amdgcn_s_barrier()
; #define PG8_SCHED __builtin_amdgcn_sched_barrier(0)
; template <class Epi>
; __device__ __forceinline__ void gemm_phase(LAS unsigned char* lds, const Gemm g, const StaticOrder& S, const Epi& E, const int tid) {
;     ...
;             PG8_LDA(At, 1, 1); PG8_STAGE(PG8_SB(1, 0), b3, voffB); PG8_STAGE(PG8_SB(1, 1), b3 + bhs, voffB); PG8_STAGE(PG8_SA(1, 0), a3, voffA);
;             PG8_WAIT_V(8); PG8_WAIT_L(0); PG8_BAR; PG8_MMA(1, 0, At, B0); PG8_MMA(1, 1, At, B1); PG8_BAR; PG8_SCHED;
;     ...
;         if (ALIGN_EPI) { if (wr == 0) PG8_BAR; }
	s_add_i32 s34, s52, s36
	v_lshl_add_u64 v[82:83], v[172:173], 0, s[70:71]
	s_mov_b32 m0, s34
	s_nop 0
	ds_read_b128 v[66:69], v199 offset:49152
	global_load_lds_dwordx4 v[82:83], off
	ds_read_b128 v[70:73], v199 offset:50176
	ds_read_b128 v[220:223], v199 offset:51200
	s_add_i32 m0, s34, 0x2000
	s_add_u32 s30, s30, 0x20080
	v_lshl_add_u64 v[82:83], v[174:175], 0, s[70:71]
	s_addc_u32 s31, s31, 0
	s_add_i32 s34, s53, s36
	global_load_lds_dwordx4 v[82:83], off
	ds_read_b128 v[224:227], v199 offset:52224
	ds_read_b128 v[228:231], v199 offset:53248
	s_mov_b32 m0, s34
	v_lshl_add_u64 v[82:83], s[30:31], 0, v[0:1]
	global_load_lds_dwordx4 v[82:83], off
	ds_read_b128 v[232:235], v199 offset:54272
	ds_read_b128 v[236:239], v199 offset:55296
	s_add_i32 m0, s34, 0x2000
	v_lshl_add_u64 v[82:83], s[30:31], 0, v[166:167]
	global_load_lds_dwordx4 v[82:83], off
	ds_read_b128 v[240:243], v199 offset:56320
	s_mov_b32 m0, s45
	v_lshl_add_u64 v[82:83], v[176:177], 0, s[70:71]
	global_load_lds_dwordx4 v[82:83], off
	s_mov_b32 m0, s46
	v_lshl_add_u64 v[82:83], v[200:201], 0, s[70:71]
	global_load_lds_dwordx4 v[82:83], off
	s_waitcnt vmcnt(8)
	s_waitcnt lgkmcnt(0)
	s_barrier
	s_setprio 1
	s_waitcnt lgkmcnt(0)
	v_mfma_f32_16x16x32_bf16 v[82:85], v[42:45], v[66:69], v[94:97]
	v_mfma_f32_16x16x32_bf16 v[94:97], v[46:49], v[70:73], v[82:85]
	v_mfma_f32_16x16x32_bf16 v[82:85], v[50:53], v[66:69], v[90:93]
	v_mfma_f32_16x16x32_bf16 v[78:81], v[42:45], v[220:223], v[78:81]
	v_mfma_f32_16x16x32_bf16 v[74:77], v[50:53], v[220:223], v[74:77]
	v_mfma_f32_16x16x32_bf16 v[62:65], v[42:45], v[228:231], v[62:65]
	v_mfma_f32_16x16x32_bf16 v[58:61], v[50:53], v[228:231], v[58:61]
	v_mfma_f32_16x16x32_bf16 v[14:17], v[42:45], v[236:239], v[14:17]
	v_mfma_f32_16x16x32_bf16 v[10:13], v[50:53], v[236:239], v[10:13]
	v_mfma_f32_16x16x32_bf16 v[90:93], v[54:57], v[70:73], v[82:85]
	v_mfma_f32_16x16x32_bf16 v[78:81], v[46:49], v[224:227], v[78:81]
	v_mfma_f32_16x16x32_bf16 v[74:77], v[54:57], v[224:227], v[74:77]
	v_mfma_f32_16x16x32_bf16 v[62:65], v[46:49], v[232:235], v[62:65]
	v_mfma_f32_16x16x32_bf16 v[58:61], v[54:57], v[232:235], v[58:61]
	v_mfma_f32_16x16x32_bf16 v[14:17], v[46:49], v[240:243], v[14:17]
	v_mfma_f32_16x16x32_bf16 v[10:13], v[54:57], v[240:243], v[10:13]
	s_setprio 0
	s_setprio 1
	v_mfma_f32_16x16x32_bf16 v[18:21], v[182:185], v[66:69], v[18:21]
	v_mfma_f32_16x16x32_bf16 v[86:89], v[186:189], v[70:73], v[18:21]
	v_mfma_f32_16x16x32_bf16 v[18:21], v[212:215], v[66:69], v[22:25]
	v_mfma_f32_16x16x32_bf16 v[82:85], v[216:219], v[70:73], v[18:21]
	v_mfma_f32_16x16x32_bf16 v[18:21], v[182:185], v[220:223], v[26:29]
	v_mfma_f32_16x16x32_bf16 v[70:73], v[186:189], v[224:227], v[18:21]
	v_mfma_f32_16x16x32_bf16 v[18:21], v[212:215], v[220:223], v[30:33]
	v_mfma_f32_16x16x32_bf16 v[66:69], v[216:219], v[224:227], v[18:21]
	v_mfma_f32_16x16x32_bf16 v[18:21], v[182:185], v[228:231], v[38:41]
	v_mfma_f32_16x16x32_bf16 v[38:41], v[186:189], v[232:235], v[18:21]
	v_mfma_f32_16x16x32_bf16 v[18:21], v[212:215], v[228:231], v[34:37]
	v_mfma_f32_16x16x32_bf16 v[6:9], v[182:185], v[236:239], v[6:9]
	v_mfma_f32_16x16x32_bf16 v[2:5], v[212:215], v[236:239], v[2:5]
	v_mfma_f32_16x16x32_bf16 v[34:37], v[216:219], v[232:235], v[18:21]
	v_mfma_f32_16x16x32_bf16 v[6:9], v[186:189], v[240:243], v[6:9]
	v_mfma_f32_16x16x32_bf16 v[2:5], v[216:219], v[240:243], v[2:5]
	s_setprio 0
	s_barrier
	s_add_i32 s51, s51, 2
	s_add_u32 s49, s49, 0x100
	s_addc_u32 s50, s50, 0
	s_add_u32 s28, s28, 0x100
	s_addc_u32 s29, s29, 0
	s_cmpk_gt_u32 s51, 0x7d
	s_cbranch_scc0 .LBB0_126
	s_and_b64 vcc, exec, s[12:13]
	s_cbranch_vccz .LBB0_129
	s_barrier

; #define PG8_STAGE(bufoff, gbase, voff) do { _Pragma("unroll") for (int _i = 0; _i < 2; ++_i) \
;         __builtin_amdgcn_global_load_lds((const unsigned*)((const char*)(gbase) + (voff)[_i]), (LAS unsigned*)(lds + (bufoff) + ldsw + _i * 8192), 16, 0, 0); } while (0)
; #define PG8_LDA(dst, b, h) do { _Pragma("unroll") for (int m = 0; m < 4; ++m) _Pragma("unroll") for (int k = 0; k < 2; ++k) dst[m][k] = *(const LAS bf16x8*)(lds + PG8_SA(b, h) + aoff + m * 2048 + k * 1024); } while (0)
; #define PG8_LDB(dst, b, h) do { _Pragma("unroll") for (int n = 0; n < 2; ++n) _Pragma("unroll") for (int k = 0; k < 2; ++k) dst[n][k] = *(const LAS bf16x8*)(lds + PG8_SB(b, h) + boff + n * 2048 + k * 1024); } while (0)
; #define PG8_MMA(ai, bj, At, Bt) do { __builtin_amdgcn_s_setprio(1); _Pragma("unroll") for (int m = 0; m < 4; ++m) _Pragma("unroll") for (int n = 0; n < 2; ++n) _Pragma("unroll") for (int k = 0; k < 2; ++k) \
;         acc[ai][bj][m][n] = __builtin_amdgcn_mfma_f32_16x16x32_bf16(Bt[n][k], At[m][k], acc[ai][bj][m][n], 0, 0, 0); __builtin_amdgcn_s_setprio(0); } while (0)
; #define PG8_WAIT_V(n) asm volatile("s_waitcnt vmcnt(" #n ")" ::: "memory")
; #define PG8_WAIT_L(n) asm volatile("s_waitcnt lgkmcnt(" #n ")" ::: "memory")
; #define PG8_BAR __builtin_amdgcn_s_barrier()
; template <class Epi>
; __device__ __forceinline__ void gemm_phase(LAS unsigned char* lds, const Gemm g, const StaticOrder& S, const Epi& E, const int tid) {
;     ...
;             const char* a2 = last ? nA : (s2 ? cA2 + (size_t)(t + 2 - nt) * kstep : cA + (size_t)(t + 2) * kstep);
;             const char* b2 = last ? nB : (s2 ? cB2 + (size_t)(t + 2 - nt) * kstep : cB + (size_t)(t + 2) * kstep);
;             const char* a3 = a2 + kstep; const char* b3 = b2 + kstep;
;             if constexpr (Epi::TWO) { if (t == nt) E.mid(acc, cur, wr, wc, fr, fq); }
;             if constexpr (SP2) {
;             PG8_LDB(B0, 0, 0); PG8_LDB(B1, 0, 1); PG8_SCHED; PG8_LDA(At, 0, 0); PG8_STAGE(PG8_SA(1, 1), a1 + hstep, voffA);
;             PG8_WAIT_V(8); PG8_WAIT_L(0); PG8_BAR; PG8_MMA(0, 0, At, B0); PG8_MMA(0, 1, At, B1); PG8_BAR; PG8_SCHED;
;             PG8_LDA(At, 0, 1); PG8_STAGE(PG8_SB(0, 0), b2, voffB); PG8_STAGE(PG8_SB(0, 1), b2 + bhs, voffB); PG8_STAGE(PG8_SA(0, 0), a2, voffA);
;             PG8_WAIT_V(8); PG8_WAIT_L(0); PG8_BAR; PG8_MMA(1, 0, At, B0); PG8_MMA(1, 1, At, B1); PG8_BAR; PG8_SCHED;
.LBB0_173:
	s_add_u32 s28, s26, 0xfff80080
	s_addc_u32 s29, s27, -1
	s_add_i32 s47, 0, 0x10000
	s_cmp_eq_u32 s46, 28
	s_cselect_b32 s31, s17, s29
	s_cselect_b32 s30, s42, s28
	v_add_u32_e32 v142, s47, v149
	s_cselect_b32 s29, s15, s45
	s_cselect_b32 s28, s43, s44
	s_add_i32 s50, 0, 0x14000
	ds_read_b128 v[156:159], v142
	ds_read_b128 v[160:163], v142 offset:1024
	ds_read_b128 v[164:167], v142 offset:2048
	ds_read_b128 v[178:181], v142 offset:3072
	v_add_u32_e32 v142, s50, v149
	ds_read_b128 v[182:185], v142
	ds_read_b128 v[186:189], v142 offset:1024
	ds_read_b128 v[190:193], v142 offset:2048
	ds_read_b128 v[194:197], v142 offset:3072
	v_lshl_add_u64 v[142:143], s[26:27], 0, v[140:141]
	s_add_i32 m0, s2, 0xc000
	ds_read_b128 v[198:201], v154
	global_load_lds_dwordx4 v[142:143], off
	ds_read_b128 v[212:215], v154 offset:1024
	ds_read_b128 v[216:219], v154 offset:2048
	s_add_i32 m0, s2, 0xe000
	v_lshl_add_u64 v[142:143], s[26:27], 0, v[138:139]
	global_load_lds_dwordx4 v[142:143], off
	ds_read_b128 v[220:223], v154 offset:3072
	ds_read_b128 v[224:227], v154 offset:4096
	ds_read_b128 v[228:231], v154 offset:5120
	ds_read_b128 v[232:235], v154 offset:6144
	ds_read_b128 v[236:239], v154 offset:7168
	s_waitcnt vmcnt(8)
	s_waitcnt lgkmcnt(0)
	s_barrier
	s_setprio 1
	s_waitcnt lgkmcnt(0)
	v_mfma_f32_16x16x32_bf16 v[126:129], v[156:159], v[198:201], v[126:129]
	v_mfma_f32_16x16x32_bf16 v[122:125], v[164:167], v[198:201], v[122:125]
	v_mfma_f32_16x16x32_bf16 v[110:113], v[156:159], v[216:219], v[110:113]
	v_mfma_f32_16x16x32_bf16 v[106:109], v[164:167], v[216:219], v[106:109]
	v_mfma_f32_16x16x32_bf16 v[94:97], v[156:159], v[224:227], v[94:97]
	v_mfma_f32_16x16x32_bf16 v[90:93], v[164:167], v[224:227], v[90:93]
	v_mfma_f32_16x16x32_bf16 v[78:81], v[156:159], v[232:235], v[78:81]
	v_mfma_f32_16x16x32_bf16 v[74:77], v[164:167], v[232:235], v[74:77]
	v_mfma_f32_16x16x32_bf16 v[126:129], v[160:163], v[212:215], v[126:129]
	v_mfma_f32_16x16x32_bf16 v[122:125], v[178:181], v[212:215], v[122:125]
	v_mfma_f32_16x16x32_bf16 v[110:113], v[160:163], v[220:223], v[110:113]
	v_mfma_f32_16x16x32_bf16 v[106:109], v[178:181], v[220:223], v[106:109]
	v_mfma_f32_16x16x32_bf16 v[94:97], v[160:163], v[228:231], v[94:97]
	v_mfma_f32_16x16x32_bf16 v[90:93], v[178:181], v[228:231], v[90:93]
	v_mfma_f32_16x16x32_bf16 v[78:81], v[160:163], v[236:239], v[78:81]
	v_mfma_f32_16x16x32_bf16 v[74:77], v[178:181], v[236:239], v[74:77]
	s_setprio 0
	s_setprio 1
	v_mfma_f32_16x16x32_bf16 v[118:121], v[182:185], v[198:201], v[118:121]
	v_mfma_f32_16x16x32_bf16 v[114:117], v[190:193], v[198:201], v[114:117]
	v_mfma_f32_16x16x32_bf16 v[102:105], v[182:185], v[216:219], v[102:105]
	v_mfma_f32_16x16x32_bf16 v[98:101], v[190:193], v[216:219], v[98:101]
	v_mfma_f32_16x16x32_bf16 v[86:89], v[182:185], v[224:227], v[86:89]
	v_mfma_f32_16x16x32_bf16 v[82:85], v[190:193], v[224:227], v[82:85]
	v_mfma_f32_16x16x32_bf16 v[70:73], v[182:185], v[232:235], v[70:73]
	v_mfma_f32_16x16x32_bf16 v[66:69], v[190:193], v[232:235], v[66:69]
	v_mfma_f32_16x16x32_bf16 v[118:121], v[186:189], v[212:215], v[118:121]
	v_mfma_f32_16x16x32_bf16 v[114:117], v[194:197], v[212:215], v[114:117]
	v_mfma_f32_16x16x32_bf16 v[102:105], v[186:189], v[220:223], v[102:105]
	v_mfma_f32_16x16x32_bf16 v[98:101], v[194:197], v[220:223], v[98:101]
	v_mfma_f32_16x16x32_bf16 v[86:89], v[186:189], v[228:231], v[86:89]
	v_mfma_f32_16x16x32_bf16 v[82:85], v[194:197], v[228:231], v[82:85]
	v_mfma_f32_16x16x32_bf16 v[70:73], v[186:189], v[236:239], v[70:73]
	v_mfma_f32_16x16x32_bf16 v[66:69], v[194:197], v[236:239], v[66:69]
	s_setprio 0
	s_barrier
	s_add_i32 s47, s47, s34
	v_lshl_add_u64 v[142:143], s[28:29], 0, v[0:1]
	s_mov_b32 m0, s47
	ds_read_b128 v[198:201], v154 offset:16384
	global_load_lds_dwordx4 v[142:143], off
	ds_read_b128 v[212:215], v154 offset:17408
	ds_read_b128 v[216:219], v154 offset:18432
	s_add_i32 m0, s47, 0x2000
	s_add_u32 s48, s28, 0x8000
	v_lshl_add_u64 v[168:169], s[28:29], 0, v[134:135]
	s_addc_u32 s49, s29, 0
	s_add_i32 s47, s50, s34
	global_load_lds_dwordx4 v[168:169], off
	ds_read_b128 v[220:223], v154 offset:19456
	ds_read_b128 v[224:227], v154 offset:20480
	v_lshl_add_u64 v[172:173], s[48:49], 0, v[0:1]
	s_mov_b32 m0, s47
	v_lshl_add_u64 v[174:175], s[30:31], 0, v[132:133]
	global_load_lds_dwordx4 v[172:173], off
	ds_read_b128 v[228:231], v154 offset:21504
	ds_read_b128 v[232:235], v154 offset:22528
	s_add_i32 m0, s47, 0x2000
	v_lshl_add_u64 v[172:173], s[48:49], 0, v[134:135]
	global_load_lds_dwordx4 v[172:173], off
	ds_read_b128 v[236:239], v154 offset:23552
	s_mov_b32 m0, s2
	v_lshl_add_u64 v[172:173], s[30:31], 0, v[130:131]
	global_load_lds_dwordx4 v[172:173], off
	s_mov_b32 m0, s25
	s_nop 0
	global_load_lds_dwordx4 v[174:175], off
	s_waitcnt vmcnt(8)
	s_waitcnt lgkmcnt(0)
	s_barrier
; #define PG8_STAGE(bufoff, gbase, voff) do { _Pragma("unroll") for (int _i = 0; _i < 2; ++_i) \
;         __builtin_amdgcn_global_load_lds((const unsigned*)((const char*)(gbase) + (voff)[_i]), (LAS unsigned*)(lds + (bufoff) + ldsw + _i * 8192), 16, 0, 0); } while (0)
; #define PG8_LDA(dst, b, h) do { _Pragma("unroll") for (int m = 0; m < 4; ++m) _Pragma("unroll") for (int k = 0; k < 2; ++k) dst[m][k] = *(const LAS bf16x8*)(lds + PG8_SA(b, h) + aoff + m * 2048 + k * 1024); } while (0)
; #define PG8_LDB(dst, b, h) do { _Pragma("unroll") for (int n = 0; n < 2; ++n) _Pragma("unroll") for (int k = 0; k < 2; ++k) dst[n][k] = *(const LAS bf16x8*)(lds + PG8_SB(b, h) + boff + n * 2048 + k * 1024); } while (0)
; #define PG8_MMA(ai, bj, At, Bt) do { __builtin_amdgcn_s_setprio(1); _Pragma("unroll") for (int m = 0; m < 4; ++m) _Pragma("unroll") for (int n = 0; n < 2; ++n) _Pragma("unroll") for (int k = 0; k < 2; ++k) \
;         acc[ai][bj][m][n] = __builtin_amdgcn_mfma_f32_16x16x32_bf16(Bt[n][k], At[m][k], acc[ai][bj][m][n], 0, 0, 0); __builtin_amdgcn_s_setprio(0); } while (0)
; #define PG8_WAIT_V(n) asm volatile("s_waitcnt vmcnt(" #n ")" ::: "memory")
; #define PG8_WAIT_L(n) asm volatile("s_waitcnt lgkmcnt(" #n ")" ::: "memory")
; #define PG8_BAR __builtin_amdgcn_s_barrier()
; #define PG8_SCHED __builtin_amdgcn_sched_barrier(0)
; template <class Epi>
; __device__ __forceinline__ void gemm_phase(LAS unsigned char* lds, const Gemm g, const StaticOrder& S, const Epi& E, const int tid) {
;     ...
;             PG8_WAIT_V(8); PG8_WAIT_L(0); PG8_BAR; PG8_MMA(1, 0, At, B0); PG8_MMA(1, 1, At, B1); PG8_BAR; PG8_SCHED;
;             PG8_LDB(B0, 1, 0); PG8_LDB(B1, 1, 1); PG8_SCHED; PG8_LDA(At, 1, 0); PG8_STAGE(PG8_SA(0, 1), a2 + hstep, voffA);
;             PG8_WAIT_V(8); PG8_WAIT_L(0); PG8_BAR; PG8_MMA(0, 0, At, B0); PG8_MMA(0, 1, At, B1); PG8_BAR; PG8_SCHED;
	s_setprio 1
	s_waitcnt lgkmcnt(0)
	v_mfma_f32_16x16x32_bf16 v[62:65], v[156:159], v[198:201], v[62:65]
	v_mfma_f32_16x16x32_bf16 v[58:61], v[164:167], v[198:201], v[58:61]
	v_mfma_f32_16x16x32_bf16 v[46:49], v[156:159], v[216:219], v[46:49]
	v_mfma_f32_16x16x32_bf16 v[42:45], v[164:167], v[216:219], v[42:45]
	v_mfma_f32_16x16x32_bf16 v[30:33], v[156:159], v[224:227], v[30:33]
	v_mfma_f32_16x16x32_bf16 v[26:29], v[164:167], v[224:227], v[26:29]
	v_mfma_f32_16x16x32_bf16 v[14:17], v[156:159], v[232:235], v[14:17]
	v_mfma_f32_16x16x32_bf16 v[10:13], v[164:167], v[232:235], v[10:13]
	v_mfma_f32_16x16x32_bf16 v[62:65], v[160:163], v[212:215], v[62:65]
	v_mfma_f32_16x16x32_bf16 v[58:61], v[178:181], v[212:215], v[58:61]
	v_mfma_f32_16x16x32_bf16 v[46:49], v[160:163], v[220:223], v[46:49]
	v_mfma_f32_16x16x32_bf16 v[42:45], v[178:181], v[220:223], v[42:45]
	v_mfma_f32_16x16x32_bf16 v[30:33], v[160:163], v[228:231], v[30:33]
	v_mfma_f32_16x16x32_bf16 v[26:29], v[178:181], v[228:231], v[26:29]
	v_mfma_f32_16x16x32_bf16 v[14:17], v[160:163], v[236:239], v[14:17]
	v_mfma_f32_16x16x32_bf16 v[10:13], v[178:181], v[236:239], v[10:13]
	s_setprio 0
	s_setprio 1
	v_mfma_f32_16x16x32_bf16 v[54:57], v[182:185], v[198:201], v[54:57]
	v_mfma_f32_16x16x32_bf16 v[50:53], v[190:193], v[198:201], v[50:53]
	v_mfma_f32_16x16x32_bf16 v[38:41], v[182:185], v[216:219], v[38:41]
	v_mfma_f32_16x16x32_bf16 v[34:37], v[190:193], v[216:219], v[34:37]
	v_mfma_f32_16x16x32_bf16 v[22:25], v[182:185], v[224:227], v[22:25]
	v_mfma_f32_16x16x32_bf16 v[18:21], v[190:193], v[224:227], v[18:21]
	v_mfma_f32_16x16x32_bf16 v[6:9], v[182:185], v[232:235], v[6:9]
	v_mfma_f32_16x16x32_bf16 v[2:5], v[190:193], v[232:235], v[2:5]
	v_mfma_f32_16x16x32_bf16 v[54:57], v[186:189], v[212:215], v[54:57]
	v_mfma_f32_16x16x32_bf16 v[50:53], v[194:197], v[212:215], v[50:53]
	v_mfma_f32_16x16x32_bf16 v[38:41], v[186:189], v[220:223], v[38:41]
	v_mfma_f32_16x16x32_bf16 v[34:37], v[194:197], v[220:223], v[34:37]
	v_mfma_f32_16x16x32_bf16 v[22:25], v[186:189], v[228:231], v[22:25]
	v_mfma_f32_16x16x32_bf16 v[18:21], v[194:197], v[228:231], v[18:21]
	v_mfma_f32_16x16x32_bf16 v[6:9], v[186:189], v[236:239], v[6:9]
	v_mfma_f32_16x16x32_bf16 v[2:5], v[194:197], v[236:239], v[2:5]
	s_setprio 0
	s_barrier
	s_add_i32 s47, 0, 0x18000
	v_add_u32_e32 v155, s47, v149
	s_add_i32 s48, 0, 0x1c000
	ds_read_b128 v[156:159], v155
	ds_read_b128 v[160:163], v155 offset:1024
	ds_read_b128 v[164:167], v155 offset:2048
	ds_read_b128 v[178:181], v155 offset:3072
	v_add_u32_e32 v155, s48, v149
	ds_read_b128 v[182:185], v155
	ds_read_b128 v[186:189], v155 offset:1024
	ds_read_b128 v[190:193], v155 offset:2048
	ds_read_b128 v[194:197], v155 offset:3072
	s_add_u32 s30, s30, 0x80000
	s_addc_u32 s31, s31, 0
	s_mov_b32 m0, s35
	v_lshl_add_u64 v[176:177], s[30:31], 0, v[130:131]
	ds_read_b128 v[198:201], v154 offset:32768
	global_load_lds_dwordx4 v[176:177], off
	ds_read_b128 v[212:215], v154 offset:33792
	ds_read_b128 v[216:219], v154 offset:34816
	s_mov_b32 m0, s36
	v_lshl_add_u64 v[176:177], s[30:31], 0, v[132:133]
	global_load_lds_dwordx4 v[176:177], off
	ds_read_b128 v[220:223], v154 offset:35840
	ds_read_b128 v[224:227], v154 offset:36864
	ds_read_b128 v[228:231], v154 offset:37888
	ds_read_b128 v[232:235], v154 offset:38912
	ds_read_b128 v[236:239], v154 offset:39936
	s_waitcnt vmcnt(8)
	s_waitcnt lgkmcnt(0)
	s_barrier
	s_setprio 1
	s_waitcnt lgkmcnt(0)
	v_mfma_f32_16x16x32_bf16 v[126:129], v[156:159], v[198:201], v[126:129]
	v_mfma_f32_16x16x32_bf16 v[122:125], v[164:167], v[198:201], v[122:125]
	v_mfma_f32_16x16x32_bf16 v[110:113], v[156:159], v[216:219], v[110:113]
	v_mfma_f32_16x16x32_bf16 v[106:109], v[164:167], v[216:219], v[106:109]
	v_mfma_f32_16x16x32_bf16 v[94:97], v[156:159], v[224:227], v[94:97]
	v_mfma_f32_16x16x32_bf16 v[90:93], v[164:167], v[224:227], v[90:93]
	v_mfma_f32_16x16x32_bf16 v[78:81], v[156:159], v[232:235], v[78:81]
	v_mfma_f32_16x16x32_bf16 v[74:77], v[164:167], v[232:235], v[74:77]
	v_mfma_f32_16x16x32_bf16 v[126:129], v[160:163], v[212:215], v[126:129]
	v_mfma_f32_16x16x32_bf16 v[122:125], v[178:181], v[212:215], v[122:125]
	v_mfma_f32_16x16x32_bf16 v[110:113], v[160:163], v[220:223], v[110:113]
	v_mfma_f32_16x16x32_bf16 v[106:109], v[178:181], v[220:223], v[106:109]
	v_mfma_f32_16x16x32_bf16 v[94:97], v[160:163], v[228:231], v[94:97]
	v_mfma_f32_16x16x32_bf16 v[90:93], v[178:181], v[228:231], v[90:93]
	v_mfma_f32_16x16x32_bf16 v[78:81], v[160:163], v[236:239], v[78:81]
	v_mfma_f32_16x16x32_bf16 v[74:77], v[178:181], v[236:239], v[74:77]
	s_setprio 0
	s_setprio 1
	v_mfma_f32_16x16x32_bf16 v[118:121], v[182:185], v[198:201], v[118:121]
	v_mfma_f32_16x16x32_bf16 v[114:117], v[190:193], v[198:201], v[114:117]
	v_mfma_f32_16x16x32_bf16 v[102:105], v[182:185], v[216:219], v[102:105]
	v_mfma_f32_16x16x32_bf16 v[98:101], v[190:193], v[216:219], v[98:101]
	v_mfma_f32_16x16x32_bf16 v[86:89], v[182:185], v[224:227], v[86:89]
	v_mfma_f32_16x16x32_bf16 v[82:85], v[190:193], v[224:227], v[82:85]
	v_mfma_f32_16x16x32_bf16 v[70:73], v[182:185], v[232:235], v[70:73]
	v_mfma_f32_16x16x32_bf16 v[66:69], v[190:193], v[232:235], v[66:69]
	v_mfma_f32_16x16x32_bf16 v[118:121], v[186:189], v[212:215], v[118:121]
	v_mfma_f32_16x16x32_bf16 v[114:117], v[194:197], v[212:215], v[114:117]
	v_mfma_f32_16x16x32_bf16 v[102:105], v[186:189], v[220:223], v[102:105]
	v_mfma_f32_16x16x32_bf16 v[98:101], v[194:197], v[220:223], v[98:101]
	v_mfma_f32_16x16x32_bf16 v[86:89], v[186:189], v[228:231], v[86:89]
	v_mfma_f32_16x16x32_bf16 v[82:85], v[194:197], v[228:231], v[82:85]
	v_mfma_f32_16x16x32_bf16 v[70:73], v[186:189], v[236:239], v[70:73]
	v_mfma_f32_16x16x32_bf16 v[66:69], v[194:197], v[236:239], v[66:69]
	s_setprio 0
	s_barrier
; #define PG8_STAGE(bufoff, gbase, voff) do { _Pragma("unroll") for (int _i = 0; _i < 2; ++_i) \
;         __builtin_amdgcn_global_load_lds((const unsigned*)((const char*)(gbase) + (voff)[_i]), (LAS unsigned*)(lds + (bufoff) + ldsw + _i * 8192), 16, 0, 0); } while (0)
; #define PG8_LDA(dst, b, h) do { _Pragma("unroll") for (int m = 0; m < 4; ++m) _Pragma("unroll") for (int k = 0; k < 2; ++k) dst[m][k] = *(const LAS bf16x8*)(lds + PG8_SA(b, h) + aoff + m * 2048 + k * 1024); } while (0)
; #define PG8_MMA(ai, bj, At, Bt) do { __builtin_amdgcn_s_setprio(1); _Pragma("unroll") for (int m = 0; m < 4; ++m) _Pragma("unroll") for (int n = 0; n < 2; ++n) _Pragma("unroll") for (int k = 0; k < 2; ++k) \
;         acc[ai][bj][m][n] = __builtin_amdgcn_mfma_f32_16x16x32_bf16(Bt[n][k], At[m][k], acc[ai][bj][m][n], 0, 0, 0); __builtin_amdgcn_s_setprio(0); } while (0)
; #define PG8_WAIT_V(n) asm volatile("s_waitcnt vmcnt(" #n ")" ::: "memory")
; #define PG8_WAIT_L(n) asm volatile("s_waitcnt lgkmcnt(" #n ")" ::: "memory")
; #define PG8_BAR __builtin_amdgcn_s_barrier()
; #define PG8_SCHED __builtin_amdgcn_sched_barrier(0)
; template <class Epi>
; __device__ __forceinline__ void gemm_phase(LAS unsigned char* lds, const Gemm g, const StaticOrder& S, const Epi& E, const int tid) {
;     ...
;             PG8_LDA(At, 1, 1); PG8_STAGE(PG8_SB(1, 0), b3, voffB); PG8_STAGE(PG8_SB(1, 1), b3 + bhs, voffB); PG8_STAGE(PG8_SA(1, 0), a3, voffA);
;             PG8_WAIT_V(8); PG8_WAIT_L(0); PG8_BAR; PG8_MMA(1, 0, At, B0); PG8_MMA(1, 1, At, B1); PG8_BAR; PG8_SCHED;
;     ...
;         if (ALIGN_EPI) { if (wr == 0) PG8_BAR; }
	s_add_i32 s30, s47, s34
	v_lshl_add_u64 v[142:143], v[142:143], 0, s[70:71]
	s_mov_b32 m0, s30
	ds_read_b128 v[198:201], v154 offset:49152
	global_load_lds_dwordx4 v[142:143], off
	ds_read_b128 v[212:215], v154 offset:50176
	ds_read_b128 v[216:219], v154 offset:51200
	s_add_i32 m0, s30, 0x2000
	s_add_u32 s28, s28, 0x8080
	v_lshl_add_u64 v[142:143], v[168:169], 0, s[70:71]
	s_addc_u32 s29, s29, 0
	s_add_i32 s30, s48, s34
	global_load_lds_dwordx4 v[142:143], off
	ds_read_b128 v[220:223], v154 offset:52224
	ds_read_b128 v[224:227], v154 offset:53248
	s_mov_b32 m0, s30
	v_lshl_add_u64 v[142:143], s[28:29], 0, v[0:1]
	global_load_lds_dwordx4 v[142:143], off
	ds_read_b128 v[228:231], v154 offset:54272
	ds_read_b128 v[232:235], v154 offset:55296
	s_add_i32 m0, s30, 0x2000
	v_lshl_add_u64 v[142:143], s[28:29], 0, v[134:135]
	global_load_lds_dwordx4 v[142:143], off
	ds_read_b128 v[236:239], v154 offset:56320
	s_mov_b32 m0, s37
	v_lshl_add_u64 v[142:143], v[172:173], 0, s[70:71]
	global_load_lds_dwordx4 v[142:143], off
	s_mov_b32 m0, s38
	v_lshl_add_u64 v[142:143], v[174:175], 0, s[70:71]
	global_load_lds_dwordx4 v[142:143], off
	s_waitcnt vmcnt(8)
	s_waitcnt lgkmcnt(0)
	s_barrier
	s_setprio 1
	s_waitcnt lgkmcnt(0)
	v_mfma_f32_16x16x32_bf16 v[62:65], v[156:159], v[198:201], v[62:65]
	v_mfma_f32_16x16x32_bf16 v[58:61], v[164:167], v[198:201], v[58:61]
	v_mfma_f32_16x16x32_bf16 v[46:49], v[156:159], v[216:219], v[46:49]
	v_mfma_f32_16x16x32_bf16 v[42:45], v[164:167], v[216:219], v[42:45]
	v_mfma_f32_16x16x32_bf16 v[30:33], v[156:159], v[224:227], v[30:33]
	v_mfma_f32_16x16x32_bf16 v[26:29], v[164:167], v[224:227], v[26:29]
	v_mfma_f32_16x16x32_bf16 v[14:17], v[156:159], v[232:235], v[14:17]
	v_mfma_f32_16x16x32_bf16 v[10:13], v[164:167], v[232:235], v[10:13]
	v_mfma_f32_16x16x32_bf16 v[62:65], v[160:163], v[212:215], v[62:65]
	v_mfma_f32_16x16x32_bf16 v[58:61], v[178:181], v[212:215], v[58:61]
	v_mfma_f32_16x16x32_bf16 v[46:49], v[160:163], v[220:223], v[46:49]
	v_mfma_f32_16x16x32_bf16 v[42:45], v[178:181], v[220:223], v[42:45]
	v_mfma_f32_16x16x32_bf16 v[30:33], v[160:163], v[228:231], v[30:33]
	v_mfma_f32_16x16x32_bf16 v[26:29], v[178:181], v[228:231], v[26:29]
	v_mfma_f32_16x16x32_bf16 v[14:17], v[160:163], v[236:239], v[14:17]
	v_mfma_f32_16x16x32_bf16 v[10:13], v[178:181], v[236:239], v[10:13]
	s_setprio 0
	s_setprio 1
	v_mfma_f32_16x16x32_bf16 v[54:57], v[182:185], v[198:201], v[54:57]
	v_mfma_f32_16x16x32_bf16 v[50:53], v[190:193], v[198:201], v[50:53]
	v_mfma_f32_16x16x32_bf16 v[38:41], v[182:185], v[216:219], v[38:41]
	v_mfma_f32_16x16x32_bf16 v[34:37], v[190:193], v[216:219], v[34:37]
	v_mfma_f32_16x16x32_bf16 v[22:25], v[182:185], v[224:227], v[22:25]
	v_mfma_f32_16x16x32_bf16 v[18:21], v[190:193], v[224:227], v[18:21]
	v_mfma_f32_16x16x32_bf16 v[6:9], v[182:185], v[232:235], v[6:9]
	v_mfma_f32_16x16x32_bf16 v[2:5], v[190:193], v[232:235], v[2:5]
	v_mfma_f32_16x16x32_bf16 v[54:57], v[186:189], v[212:215], v[54:57]
	v_mfma_f32_16x16x32_bf16 v[50:53], v[194:197], v[212:215], v[50:53]
	v_mfma_f32_16x16x32_bf16 v[38:41], v[186:189], v[220:223], v[38:41]
	v_mfma_f32_16x16x32_bf16 v[34:37], v[194:197], v[220:223], v[34:37]
	v_mfma_f32_16x16x32_bf16 v[22:25], v[186:189], v[228:231], v[22:25]
	v_mfma_f32_16x16x32_bf16 v[18:21], v[194:197], v[228:231], v[18:21]
	v_mfma_f32_16x16x32_bf16 v[6:9], v[186:189], v[236:239], v[6:9]
	v_mfma_f32_16x16x32_bf16 v[2:5], v[194:197], v[236:239], v[2:5]
	s_setprio 0
	s_barrier
	s_add_i32 s46, s46, 2
	s_add_u32 s44, s44, 0x100
	s_addc_u32 s45, s45, 0
	s_add_u32 s26, s26, 0x100
	s_addc_u32 s27, s27, 0
	s_cmp_gt_u32 s46, 29
	s_cbranch_scc0 .LBB0_173
	v_readlane_b32 s42, v251, 53
	s_and_b64 vcc, exec, s[12:13]
	v_readlane_b32 s43, v251, 54
	s_cbranch_vccz .LBB0_176
	s_barrier

; #define PG8_STAGE(bufoff, gbase, voff) do { _Pragma("unroll") for (int _i = 0; _i < 2; ++_i) \
;         __builtin_amdgcn_global_load_lds((const unsigned*)((const char*)(gbase) + (voff)[_i]), (LAS unsigned*)(lds + (bufoff) + ldsw + _i * 8192), 16, 0, 0); } while (0)
; #define PG8_LDA(dst, b, h) do { _Pragma("unroll") for (int m = 0; m < 4; ++m) _Pragma("unroll") for (int k = 0; k < 2; ++k) dst[m][k] = *(const LAS bf16x8*)(lds + PG8_SA(b, h) + aoff + m * 2048 + k * 1024); } while (0)
; #define PG8_LDB(dst, b, h) do { _Pragma("unroll") for (int n = 0; n < 2; ++n) _Pragma("unroll") for (int k = 0; k < 2; ++k) dst[n][k] = *(const LAS bf16x8*)(lds + PG8_SB(b, h) + boff + n * 2048 + k * 1024); } while (0)
; #define PG8_MMA(ai, bj, At, Bt) do { __builtin_amdgcn_s_setprio(1); _Pragma("unroll") for (int m = 0; m < 4; ++m) _Pragma("unroll") for (int n = 0; n < 2; ++n) _Pragma("unroll") for (int k = 0; k < 2; ++k) \
;         acc[ai][bj][m][n] = __builtin_amdgcn_mfma_f32_16x16x32_bf16(Bt[n][k], At[m][k], acc[ai][bj][m][n], 0, 0, 0); __builtin_amdgcn_s_setprio(0); } while (0)
; #define PG8_WAIT_V(n) asm volatile("s_waitcnt vmcnt(" #n ")" ::: "memory")
; #define PG8_WAIT_L(n) asm volatile("s_waitcnt lgkmcnt(" #n ")" ::: "memory")
; #define PG8_BAR __builtin_amdgcn_s_barrier()
; template <class Epi>
; __device__ __forceinline__ void gemm_phase(LAS unsigned char* lds, const Gemm g, const StaticOrder& S, const Epi& E, const int tid) {
;     ...
;             const char* a2 = last ? nA : (s2 ? cA2 + (size_t)(t + 2 - nt) * kstep : cA + (size_t)(t + 2) * kstep);
;             const char* b2 = last ? nB : (s2 ? cB2 + (size_t)(t + 2 - nt) * kstep : cB + (size_t)(t + 2) * kstep);
;             const char* a3 = a2 + kstep; const char* b3 = b2 + kstep;
;             if constexpr (Epi::TWO) { if (t == nt) E.mid(acc, cur, wr, wc, fr, fq); }
;             if constexpr (SP2) {
;             PG8_LDB(B0, 0, 0); PG8_LDB(B1, 0, 1); PG8_SCHED; PG8_LDA(At, 0, 0); PG8_STAGE(PG8_SA(1, 1), a1 + hstep, voffA);
;             PG8_WAIT_V(8); PG8_WAIT_L(0); PG8_BAR; PG8_MMA(0, 0, At, B0); PG8_MMA(0, 1, At, B1); PG8_BAR; PG8_SCHED;
;             PG8_LDA(At, 0, 1); PG8_STAGE(PG8_SB(0, 0), b2, voffB); PG8_STAGE(PG8_SB(0, 1), b2 + bhs, voffB); PG8_STAGE(PG8_SA(0, 0), a2, voffA);
;             PG8_WAIT_V(8); PG8_WAIT_L(0); PG8_BAR; PG8_MMA(1, 0, At, B0); PG8_MMA(1, 1, At, B1); PG8_BAR; PG8_SCHED;
.LBB0_206:
	s_add_u32 s30, s28, 0xfffe0080
	s_addc_u32 s31, s29, -1
	s_add_i32 s52, 0, 0x10000
	s_cmp_eq_u32 s51, 4
	s_cselect_b32 s35, s17, s31
	s_cselect_b32 s34, s27, s30
	s_cselect_b32 s31, s15, s50
	s_cselect_b32 s30, s33, s49
	s_add_i32 s54, 0, 0x14000
	v_add_u32_e32 v30, s52, v193
	v_add_u32_e32 v54, s54, v193
	ds_read_b128 v[18:21], v30
	ds_read_b128 v[22:25], v30 offset:1024
	ds_read_b128 v[26:29], v30 offset:2048
	ds_read_b128 v[30:33], v30 offset:3072
	ds_read_b128 v[42:45], v54
	ds_read_b128 v[46:49], v54 offset:1024
	ds_read_b128 v[50:53], v54 offset:2048
	ds_read_b128 v[54:57], v54 offset:3072
	v_lshl_add_u64 v[172:173], s[28:29], 0, v[180:181]
	s_add_i32 m0, s37, 0xc000
	ds_read_b128 v[182:185], v199
	global_load_lds_dwordx4 v[172:173], off
	ds_read_b128 v[186:189], v199 offset:1024
	ds_read_b128 v[212:215], v199 offset:2048
	s_add_i32 m0, s37, 0xe000
	v_lshl_add_u64 v[172:173], s[28:29], 0, v[178:179]
	global_load_lds_dwordx4 v[172:173], off
	ds_read_b128 v[216:219], v199 offset:3072
	ds_read_b128 v[220:223], v199 offset:4096
	ds_read_b128 v[224:227], v199 offset:5120
	ds_read_b128 v[228:231], v199 offset:6144
	ds_read_b128 v[232:235], v199 offset:7168
	s_waitcnt vmcnt(8)
	s_waitcnt lgkmcnt(0)
	s_barrier
	s_setprio 1
	s_waitcnt lgkmcnt(0)
	v_mfma_f32_16x16x32_bf16 v[158:161], v[18:21], v[182:185], v[158:161]
	v_mfma_f32_16x16x32_bf16 v[154:157], v[26:29], v[182:185], v[154:157]
	v_mfma_f32_16x16x32_bf16 v[142:145], v[18:21], v[212:215], v[142:145]
	v_mfma_f32_16x16x32_bf16 v[138:141], v[26:29], v[212:215], v[138:141]
	v_mfma_f32_16x16x32_bf16 v[126:129], v[18:21], v[220:223], v[126:129]
	v_mfma_f32_16x16x32_bf16 v[122:125], v[26:29], v[220:223], v[122:125]
	v_mfma_f32_16x16x32_bf16 v[110:113], v[18:21], v[228:231], v[110:113]
	v_mfma_f32_16x16x32_bf16 v[106:109], v[26:29], v[228:231], v[106:109]
	v_mfma_f32_16x16x32_bf16 v[158:161], v[22:25], v[186:189], v[158:161]
	v_mfma_f32_16x16x32_bf16 v[154:157], v[30:33], v[186:189], v[154:157]
	v_mfma_f32_16x16x32_bf16 v[142:145], v[22:25], v[216:219], v[142:145]
	v_mfma_f32_16x16x32_bf16 v[138:141], v[30:33], v[216:219], v[138:141]
	v_mfma_f32_16x16x32_bf16 v[126:129], v[22:25], v[224:227], v[126:129]
	v_mfma_f32_16x16x32_bf16 v[122:125], v[30:33], v[224:227], v[122:125]
	v_mfma_f32_16x16x32_bf16 v[110:113], v[22:25], v[232:235], v[110:113]
	v_mfma_f32_16x16x32_bf16 v[106:109], v[30:33], v[232:235], v[106:109]
	s_setprio 0
	s_setprio 1
	v_mfma_f32_16x16x32_bf16 v[150:153], v[42:45], v[182:185], v[150:153]
	v_mfma_f32_16x16x32_bf16 v[146:149], v[50:53], v[182:185], v[146:149]
	v_mfma_f32_16x16x32_bf16 v[134:137], v[42:45], v[212:215], v[134:137]
	v_mfma_f32_16x16x32_bf16 v[130:133], v[50:53], v[212:215], v[130:133]
	v_mfma_f32_16x16x32_bf16 v[118:121], v[42:45], v[220:223], v[118:121]
	v_mfma_f32_16x16x32_bf16 v[114:117], v[50:53], v[220:223], v[114:117]
	v_mfma_f32_16x16x32_bf16 v[102:105], v[42:45], v[228:231], v[102:105]
	v_mfma_f32_16x16x32_bf16 v[98:101], v[50:53], v[228:231], v[98:101]
	v_mfma_f32_16x16x32_bf16 v[150:153], v[46:49], v[186:189], v[150:153]
	v_mfma_f32_16x16x32_bf16 v[146:149], v[54:57], v[186:189], v[146:149]
	v_mfma_f32_16x16x32_bf16 v[134:137], v[46:49], v[216:219], v[134:137]
	v_mfma_f32_16x16x32_bf16 v[130:133], v[54:57], v[216:219], v[130:133]
	v_mfma_f32_16x16x32_bf16 v[118:121], v[46:49], v[224:227], v[118:121]
	v_mfma_f32_16x16x32_bf16 v[114:117], v[54:57], v[224:227], v[114:117]
	v_mfma_f32_16x16x32_bf16 v[102:105], v[46:49], v[232:235], v[102:105]
	v_mfma_f32_16x16x32_bf16 v[98:101], v[54:57], v[232:235], v[98:101]
	s_setprio 0
	s_barrier
	s_add_i32 s52, s52, s36
	v_lshl_add_u64 v[172:173], s[30:31], 0, v[0:1]
	s_mov_b32 m0, s52
	ds_read_b128 v[182:185], v199 offset:16384
	global_load_lds_dwordx4 v[172:173], off
	ds_read_b128 v[186:189], v199 offset:17408
	ds_read_b128 v[212:215], v199 offset:18432
	s_add_i32 m0, s52, 0x2000
	s_add_u32 s52, s30, 0x2000
	v_lshl_add_u64 v[174:175], s[30:31], 0, v[166:167]
	s_addc_u32 s53, s31, 0
	s_add_i32 s54, s54, s36
	global_load_lds_dwordx4 v[174:175], off
	ds_read_b128 v[216:219], v199 offset:19456
	ds_read_b128 v[220:223], v199 offset:20480
	v_lshl_add_u64 v[176:177], s[52:53], 0, v[0:1]
	s_mov_b32 m0, s54
	v_lshl_add_u64 v[200:201], s[34:35], 0, v[164:165]
	global_load_lds_dwordx4 v[176:177], off
	ds_read_b128 v[224:227], v199 offset:21504
	ds_read_b128 v[228:231], v199 offset:22528
	s_add_i32 m0, s54, 0x2000
	v_lshl_add_u64 v[176:177], s[52:53], 0, v[166:167]
	global_load_lds_dwordx4 v[176:177], off
	ds_read_b128 v[232:235], v199 offset:23552
	s_mov_b32 m0, s37
	v_lshl_add_u64 v[176:177], s[34:35], 0, v[162:163]
	global_load_lds_dwordx4 v[176:177], off
	s_mov_b32 m0, s38
	s_nop 0
	global_load_lds_dwordx4 v[200:201], off
	s_waitcnt vmcnt(8)
	s_waitcnt lgkmcnt(0)
	s_barrier
; #define PG8_STAGE(bufoff, gbase, voff) do { _Pragma("unroll") for (int _i = 0; _i < 2; ++_i) \
;         __builtin_amdgcn_global_load_lds((const unsigned*)((const char*)(gbase) + (voff)[_i]), (LAS unsigned*)(lds + (bufoff) + ldsw + _i * 8192), 16, 0, 0); } while (0)
; #define PG8_LDA(dst, b, h) do { _Pragma("unroll") for (int m = 0; m < 4; ++m) _Pragma("unroll") for (int k = 0; k < 2; ++k) dst[m][k] = *(const LAS bf16x8*)(lds + PG8_SA(b, h) + aoff + m * 2048 + k * 1024); } while (0)
; #define PG8_LDB(dst, b, h) do { _Pragma("unroll") for (int n = 0; n < 2; ++n) _Pragma("unroll") for (int k = 0; k < 2; ++k) dst[n][k] = *(const LAS bf16x8*)(lds + PG8_SB(b, h) + boff + n * 2048 + k * 1024); } while (0)
; #define PG8_MMA(ai, bj, At, Bt) do { __builtin_amdgcn_s_setprio(1); _Pragma("unroll") for (int m = 0; m < 4; ++m) _Pragma("unroll") for (int n = 0; n < 2; ++n) _Pragma("unroll") for (int k = 0; k < 2; ++k) \
;         acc[ai][bj][m][n] = __builtin_amdgcn_mfma_f32_16x16x32_bf16(Bt[n][k], At[m][k], acc[ai][bj][m][n], 0, 0, 0); __builtin_amdgcn_s_setprio(0); } while (0)
; #define PG8_WAIT_V(n) asm volatile("s_waitcnt vmcnt(" #n ")" ::: "memory")
; #define PG8_WAIT_L(n) asm volatile("s_waitcnt lgkmcnt(" #n ")" ::: "memory")
; #define PG8_BAR __builtin_amdgcn_s_barrier()
; #define PG8_SCHED __builtin_amdgcn_sched_barrier(0)
; template <class Epi>
; __device__ __forceinline__ void gemm_phase(LAS unsigned char* lds, const Gemm g, const StaticOrder& S, const Epi& E, const int tid) {
;     ...
;             PG8_WAIT_V(8); PG8_WAIT_L(0); PG8_BAR; PG8_MMA(1, 0, At, B0); PG8_MMA(1, 1, At, B1); PG8_BAR; PG8_SCHED;
;             PG8_LDB(B0, 1, 0); PG8_LDB(B1, 1, 1); PG8_SCHED; PG8_LDA(At, 1, 0); PG8_STAGE(PG8_SA(0, 1), a2 + hstep, voffA);
;             PG8_WAIT_V(8); PG8_WAIT_L(0); PG8_BAR; PG8_MMA(0, 0, At, B0); PG8_MMA(0, 1, At, B1); PG8_BAR; PG8_SCHED;
	s_setprio 1
	s_waitcnt lgkmcnt(0)
	v_mfma_f32_16x16x32_bf16 v[94:97], v[18:21], v[182:185], v[94:97]
	v_mfma_f32_16x16x32_bf16 v[90:93], v[26:29], v[182:185], v[90:93]
	v_mfma_f32_16x16x32_bf16 v[78:81], v[18:21], v[212:215], v[78:81]
	v_mfma_f32_16x16x32_bf16 v[74:77], v[26:29], v[212:215], v[74:77]
	v_mfma_f32_16x16x32_bf16 v[62:65], v[18:21], v[220:223], v[62:65]
	v_mfma_f32_16x16x32_bf16 v[58:61], v[26:29], v[220:223], v[58:61]
	v_mfma_f32_16x16x32_bf16 v[14:17], v[18:21], v[228:231], v[14:17]
	v_mfma_f32_16x16x32_bf16 v[10:13], v[26:29], v[228:231], v[10:13]
	v_mfma_f32_16x16x32_bf16 v[94:97], v[22:25], v[186:189], v[94:97]
	v_mfma_f32_16x16x32_bf16 v[90:93], v[30:33], v[186:189], v[90:93]
	v_mfma_f32_16x16x32_bf16 v[78:81], v[22:25], v[216:219], v[78:81]
	v_mfma_f32_16x16x32_bf16 v[74:77], v[30:33], v[216:219], v[74:77]
	v_mfma_f32_16x16x32_bf16 v[62:65], v[22:25], v[224:227], v[62:65]
	v_mfma_f32_16x16x32_bf16 v[58:61], v[30:33], v[224:227], v[58:61]
	v_mfma_f32_16x16x32_bf16 v[14:17], v[22:25], v[232:235], v[14:17]
	v_mfma_f32_16x16x32_bf16 v[10:13], v[30:33], v[232:235], v[10:13]
	s_setprio 0
	s_setprio 1
	v_mfma_f32_16x16x32_bf16 v[38:41], v[42:45], v[220:223], v[38:41]
	v_mfma_f32_16x16x32_bf16 v[34:37], v[50:53], v[220:223], v[34:37]
	v_mfma_f32_16x16x32_bf16 v[6:9], v[42:45], v[228:231], v[6:9]
	v_mfma_f32_16x16x32_bf16 v[2:5], v[50:53], v[228:231], v[2:5]
	v_mfma_f32_16x16x32_bf16 v[18:21], v[42:45], v[182:185], v[86:89]
	v_mfma_f32_16x16x32_bf16 v[22:25], v[50:53], v[182:185], v[82:85]
	v_mfma_f32_16x16x32_bf16 v[26:29], v[42:45], v[212:215], v[70:73]
	v_mfma_f32_16x16x32_bf16 v[30:33], v[50:53], v[212:215], v[66:69]
	v_mfma_f32_16x16x32_bf16 v[38:41], v[46:49], v[224:227], v[38:41]
	v_mfma_f32_16x16x32_bf16 v[34:37], v[54:57], v[224:227], v[34:37]
	v_mfma_f32_16x16x32_bf16 v[6:9], v[46:49], v[232:235], v[6:9]
	v_mfma_f32_16x16x32_bf16 v[2:5], v[54:57], v[232:235], v[2:5]
	v_mfma_f32_16x16x32_bf16 v[18:21], v[46:49], v[186:189], v[18:21]
	v_mfma_f32_16x16x32_bf16 v[22:25], v[54:57], v[186:189], v[22:25]
	v_mfma_f32_16x16x32_bf16 v[26:29], v[46:49], v[216:219], v[26:29]
	v_mfma_f32_16x16x32_bf16 v[30:33], v[54:57], v[216:219], v[30:33]
	s_setprio 0
	s_barrier
	s_add_i32 s52, 0, 0x18000
	s_add_i32 s53, 0, 0x1c000
	v_add_u32_e32 v54, s52, v193
	v_add_u32_e32 v66, s53, v193
	ds_read_b128 v[42:45], v54
	ds_read_b128 v[46:49], v54 offset:1024
	ds_read_b128 v[50:53], v54 offset:2048
	ds_read_b128 v[54:57], v54 offset:3072
	ds_read_b128 v[182:185], v66
	ds_read_b128 v[186:189], v66 offset:1024
	ds_read_b128 v[212:215], v66 offset:2048
	ds_read_b128 v[216:219], v66 offset:3072
	s_add_u32 s34, s34, 0x20000
	s_addc_u32 s35, s35, 0
	s_mov_b32 m0, s39
	v_lshl_add_u64 v[236:237], s[34:35], 0, v[162:163]
	ds_read_b128 v[66:69], v199 offset:32768
	global_load_lds_dwordx4 v[236:237], off
	ds_read_b128 v[70:73], v199 offset:33792
	ds_read_b128 v[82:85], v199 offset:34816
	s_mov_b32 m0, s44
	v_lshl_add_u64 v[236:237], s[34:35], 0, v[164:165]
	global_load_lds_dwordx4 v[236:237], off
	ds_read_b128 v[86:89], v199 offset:35840
	ds_read_b128 v[220:223], v199 offset:36864
	ds_read_b128 v[224:227], v199 offset:37888
	ds_read_b128 v[228:231], v199 offset:38912
	ds_read_b128 v[232:235], v199 offset:39936
	s_waitcnt vmcnt(8)
	s_waitcnt lgkmcnt(0)
	s_barrier
	s_setprio 1
	s_waitcnt lgkmcnt(0)
	v_mfma_f32_16x16x32_bf16 v[158:161], v[42:45], v[66:69], v[158:161]
	v_mfma_f32_16x16x32_bf16 v[154:157], v[50:53], v[66:69], v[154:157]
	v_mfma_f32_16x16x32_bf16 v[142:145], v[42:45], v[82:85], v[142:145]
	v_mfma_f32_16x16x32_bf16 v[138:141], v[50:53], v[82:85], v[138:141]
	v_mfma_f32_16x16x32_bf16 v[126:129], v[42:45], v[220:223], v[126:129]
	v_mfma_f32_16x16x32_bf16 v[122:125], v[50:53], v[220:223], v[122:125]
	v_mfma_f32_16x16x32_bf16 v[110:113], v[42:45], v[228:231], v[110:113]
	v_mfma_f32_16x16x32_bf16 v[106:109], v[50:53], v[228:231], v[106:109]
	v_mfma_f32_16x16x32_bf16 v[158:161], v[46:49], v[70:73], v[158:161]
	v_mfma_f32_16x16x32_bf16 v[154:157], v[54:57], v[70:73], v[154:157]
	v_mfma_f32_16x16x32_bf16 v[142:145], v[46:49], v[86:89], v[142:145]
	v_mfma_f32_16x16x32_bf16 v[138:141], v[54:57], v[86:89], v[138:141]
	v_mfma_f32_16x16x32_bf16 v[126:129], v[46:49], v[224:227], v[126:129]
	v_mfma_f32_16x16x32_bf16 v[122:125], v[54:57], v[224:227], v[122:125]
	v_mfma_f32_16x16x32_bf16 v[110:113], v[46:49], v[232:235], v[110:113]
	v_mfma_f32_16x16x32_bf16 v[106:109], v[54:57], v[232:235], v[106:109]
	s_setprio 0
	s_setprio 1
	v_mfma_f32_16x16x32_bf16 v[150:153], v[182:185], v[66:69], v[150:153]
	v_mfma_f32_16x16x32_bf16 v[66:69], v[212:215], v[66:69], v[146:149]
	v_mfma_f32_16x16x32_bf16 v[146:149], v[216:219], v[70:73], v[66:69]
	v_mfma_f32_16x16x32_bf16 v[66:69], v[182:185], v[82:85], v[134:137]
	v_mfma_f32_16x16x32_bf16 v[134:137], v[186:189], v[86:89], v[66:69]
	v_mfma_f32_16x16x32_bf16 v[66:69], v[212:215], v[82:85], v[130:133]
	v_mfma_f32_16x16x32_bf16 v[130:133], v[216:219], v[86:89], v[66:69]
	v_mfma_f32_16x16x32_bf16 v[66:69], v[182:185], v[220:223], v[118:121]
	v_mfma_f32_16x16x32_bf16 v[118:121], v[186:189], v[224:227], v[66:69]
	v_mfma_f32_16x16x32_bf16 v[66:69], v[212:215], v[220:223], v[114:117]
	v_mfma_f32_16x16x32_bf16 v[114:117], v[216:219], v[224:227], v[66:69]
	v_mfma_f32_16x16x32_bf16 v[66:69], v[182:185], v[228:231], v[102:105]
	v_mfma_f32_16x16x32_bf16 v[102:105], v[186:189], v[232:235], v[66:69]
	v_mfma_f32_16x16x32_bf16 v[66:69], v[212:215], v[228:231], v[98:101]
	v_mfma_f32_16x16x32_bf16 v[150:153], v[186:189], v[70:73], v[150:153]
	v_mfma_f32_16x16x32_bf16 v[98:101], v[216:219], v[232:235], v[66:69]
	s_setprio 0
	s_barrier
; #define PG8_STAGE(bufoff, gbase, voff) do { _Pragma("unroll") for (int _i = 0; _i < 2; ++_i) \
;         __builtin_amdgcn_global_load_lds((const unsigned*)((const char*)(gbase) + (voff)[_i]), (LAS unsigned*)(lds + (bufoff) + ldsw + _i * 8192), 16, 0, 0); } while (0)
; #define PG8_LDA(dst, b, h) do { _Pragma("unroll") for (int m = 0; m < 4; ++m) _Pragma("unroll") for (int k = 0; k < 2; ++k) dst[m][k] = *(const LAS bf16x8*)(lds + PG8_SA(b, h) + aoff + m * 2048 + k * 1024); } while (0)
; #define PG8_MMA(ai, bj, At, Bt) do { __builtin_amdgcn_s_setprio(1); _Pragma("unroll") for (int m = 0; m < 4; ++m) _Pragma("unroll") for (int n = 0; n < 2; ++n) _Pragma("unroll") for (int k = 0; k < 2; ++k) \
;         acc[ai][bj][m][n] = __builtin_amdgcn_mfma_f32_16x16x32_bf16(Bt[n][k], At[m][k], acc[ai][bj][m][n], 0, 0, 0); __builtin_amdgcn_s_setprio(0); } while (0)
; #define PG8_WAIT_V(n) asm volatile("s_waitcnt vmcnt(" #n ")" ::: "memory")
; #define PG8_WAIT_L(n) asm volatile("s_waitcnt lgkmcnt(" #n ")" ::: "memory")
; #define PG8_BAR __builtin_amdgcn_s_barrier()
; #define PG8_SCHED __builtin_amdgcn_sched_barrier(0)
; template <class Epi>
; __device__ __forceinline__ void gemm_phase(LAS unsigned char* lds, const Gemm g, const StaticOrder& S, const Epi& E, const int tid) {
;     ...
;             PG8_LDA(At, 1, 1); PG8_STAGE(PG8_SB(1, 0), b3, voffB); PG8_STAGE(PG8_SB(1, 1), b3 + bhs, voffB); PG8_STAGE(PG8_SA(1, 0), a3, voffA);
;             PG8_WAIT_V(8); PG8_WAIT_L(0); PG8_BAR; PG8_MMA(1, 0, At, B0); PG8_MMA(1, 1, At, B1); PG8_BAR; PG8_SCHED;
;     ...
;         if (ALIGN_EPI) { if (wr == 0) PG8_BAR; }
	s_add_i32 s34, s52, s36
	v_lshl_add_u64 v[82:83], v[172:173], 0, s[70:71]
	s_mov_b32 m0, s34
	s_nop 0
	ds_read_b128 v[66:69], v199 offset:49152
	global_load_lds_dwordx4 v[82:83], off
	ds_read_b128 v[70:73], v199 offset:50176
	ds_read_b128 v[220:223], v199 offset:51200
	s_add_i32 m0, s34, 0x2000
	s_add_u32 s30, s30, 0x2080
	v_lshl_add_u64 v[82:83], v[174:175], 0, s[70:71]
	s_addc_u32 s31, s31, 0
	s_add_i32 s34, s53, s36
	global_load_lds_dwordx4 v[82:83], off
	ds_read_b128 v[224:227], v199 offset:52224
	ds_read_b128 v[228:231], v199 offset:53248
	s_mov_b32 m0, s34
	v_lshl_add_u64 v[82:83], s[30:31], 0, v[0:1]
	global_load_lds_dwordx4 v[82:83], off
	ds_read_b128 v[232:235], v199 offset:54272
	ds_read_b128 v[236:239], v199 offset:55296
	s_add_i32 m0, s34, 0x2000
	v_lshl_add_u64 v[82:83], s[30:31], 0, v[166:167]
	global_load_lds_dwordx4 v[82:83], off
	ds_read_b128 v[240:243], v199 offset:56320
	s_mov_b32 m0, s45
	v_lshl_add_u64 v[82:83], v[176:177], 0, s[70:71]
	global_load_lds_dwordx4 v[82:83], off
	s_mov_b32 m0, s46
	v_lshl_add_u64 v[82:83], v[200:201], 0, s[70:71]
	global_load_lds_dwordx4 v[82:83], off
	s_waitcnt vmcnt(8)
	s_waitcnt lgkmcnt(0)
	s_barrier
	s_setprio 1
	s_waitcnt lgkmcnt(0)
	v_mfma_f32_16x16x32_bf16 v[82:85], v[42:45], v[66:69], v[94:97]
	v_mfma_f32_16x16x32_bf16 v[94:97], v[46:49], v[70:73], v[82:85]
	v_mfma_f32_16x16x32_bf16 v[82:85], v[50:53], v[66:69], v[90:93]
	v_mfma_f32_16x16x32_bf16 v[78:81], v[42:45], v[220:223], v[78:81]
	v_mfma_f32_16x16x32_bf16 v[74:77], v[50:53], v[220:223], v[74:77]
	v_mfma_f32_16x16x32_bf16 v[62:65], v[42:45], v[228:231], v[62:65]
	v_mfma_f32_16x16x32_bf16 v[58:61], v[50:53], v[228:231], v[58:61]
	v_mfma_f32_16x16x32_bf16 v[14:17], v[42:45], v[236:239], v[14:17]
	v_mfma_f32_16x16x32_bf16 v[10:13], v[50:53], v[236:239], v[10:13]
	v_mfma_f32_16x16x32_bf16 v[90:93], v[54:57], v[70:73], v[82:85]
	v_mfma_f32_16x16x32_bf16 v[78:81], v[46:49], v[224:227], v[78:81]
	v_mfma_f32_16x16x32_bf16 v[74:77], v[54:57], v[224:227], v[74:77]
	v_mfma_f32_16x16x32_bf16 v[62:65], v[46:49], v[232:235], v[62:65]
	v_mfma_f32_16x16x32_bf16 v[58:61], v[54:57], v[232:235], v[58:61]
	v_mfma_f32_16x16x32_bf16 v[14:17], v[46:49], v[240:243], v[14:17]
	v_mfma_f32_16x16x32_bf16 v[10:13], v[54:57], v[240:243], v[10:13]
	s_setprio 0
	s_setprio 1
	v_mfma_f32_16x16x32_bf16 v[18:21], v[182:185], v[66:69], v[18:21]
	v_mfma_f32_16x16x32_bf16 v[86:89], v[186:189], v[70:73], v[18:21]
	v_mfma_f32_16x16x32_bf16 v[18:21], v[212:215], v[66:69], v[22:25]
	v_mfma_f32_16x16x32_bf16 v[82:85], v[216:219], v[70:73], v[18:21]
	v_mfma_f32_16x16x32_bf16 v[18:21], v[182:185], v[220:223], v[26:29]
	v_mfma_f32_16x16x32_bf16 v[70:73], v[186:189], v[224:227], v[18:21]
	v_mfma_f32_16x16x32_bf16 v[18:21], v[212:215], v[220:223], v[30:33]
	v_mfma_f32_16x16x32_bf16 v[66:69], v[216:219], v[224:227], v[18:21]
	v_mfma_f32_16x16x32_bf16 v[18:21], v[182:185], v[228:231], v[38:41]
	v_mfma_f32_16x16x32_bf16 v[38:41], v[186:189], v[232:235], v[18:21]
	v_mfma_f32_16x16x32_bf16 v[18:21], v[212:215], v[228:231], v[34:37]
	v_mfma_f32_16x16x32_bf16 v[6:9], v[182:185], v[236:239], v[6:9]
	v_mfma_f32_16x16x32_bf16 v[2:5], v[212:215], v[236:239], v[2:5]
	v_mfma_f32_16x16x32_bf16 v[34:37], v[216:219], v[232:235], v[18:21]
	v_mfma_f32_16x16x32_bf16 v[6:9], v[186:189], v[240:243], v[6:9]
	v_mfma_f32_16x16x32_bf16 v[2:5], v[216:219], v[240:243], v[2:5]
	s_setprio 0
	s_barrier
	s_add_i32 s51, s51, 2
	s_add_u32 s49, s49, 0x100
	s_addc_u32 s50, s50, 0
	s_add_u32 s28, s28, 0x100
	s_addc_u32 s29, s29, 0
	s_cmp_gt_u32 s51, 5
	s_cbranch_scc0 .LBB0_206
	s_and_b64 vcc, exec, s[12:13]
	s_cbranch_vccz .LBB0_209
	s_barrier

; #define PG8_STAGE(bufoff, gbase, voff) do { _Pragma("unroll") for (int _i = 0; _i < 2; ++_i) \
;         __builtin_amdgcn_global_load_lds((const unsigned*)((const char*)(gbase) + (voff)[_i]), (LAS unsigned*)(lds + (bufoff) + ldsw + _i * 8192), 16, 0, 0); } while (0)
; #define PG8_LDA(dst, b, h) do { _Pragma("unroll") for (int m = 0; m < 4; ++m) _Pragma("unroll") for (int k = 0; k < 2; ++k) dst[m][k] = *(const LAS bf16x8*)(lds + PG8_SA(b, h) + aoff + m * 2048 + k * 1024); } while (0)
; #define PG8_LDB(dst, b, h) do { _Pragma("unroll") for (int n = 0; n < 2; ++n) _Pragma("unroll") for (int k = 0; k < 2; ++k) dst[n][k] = *(const LAS bf16x8*)(lds + PG8_SB(b, h) + boff + n * 2048 + k * 1024); } while (0)
; #define PG8_MMA(ai, bj, At, Bt) do { __builtin_amdgcn_s_setprio(1); _Pragma("unroll") for (int m = 0; m < 4; ++m) _Pragma("unroll") for (int n = 0; n < 2; ++n) _Pragma("unroll") for (int k = 0; k < 2; ++k) \
;         acc[ai][bj][m][n] = __builtin_amdgcn_mfma_f32_16x16x32_bf16(Bt[n][k], At[m][k], acc[ai][bj][m][n], 0, 0, 0); __builtin_amdgcn_s_setprio(0); } while (0)
; #define PG8_WAIT_V(n) asm volatile("s_waitcnt vmcnt(" #n ")" ::: "memory")
; #define PG8_WAIT_L(n) asm volatile("s_waitcnt lgkmcnt(" #n ")" ::: "memory")
; #define PG8_BAR __builtin_amdgcn_s_barrier()
; template <class Epi>
; __device__ __forceinline__ void gemm_phase(LAS unsigned char* lds, const Gemm g, const StaticOrder& S, const Epi& E, const int tid) {
;     ...
;             const char* a2 = last ? nA : (s2 ? cA2 + (size_t)(t + 2 - nt) * kstep : cA + (size_t)(t + 2) * kstep);
;             const char* b2 = last ? nB : (s2 ? cB2 + (size_t)(t + 2 - nt) * kstep : cB + (size_t)(t + 2) * kstep);
;             const char* a3 = a2 + kstep; const char* b3 = b2 + kstep;
;             if constexpr (Epi::TWO) { if (t == nt) E.mid(acc, cur, wr, wc, fr, fq); }
;             if constexpr (SP2) {
;             PG8_LDB(B0, 0, 0); PG8_LDB(B1, 0, 1); PG8_SCHED; PG8_LDA(At, 0, 0); PG8_STAGE(PG8_SA(1, 1), a1 + hstep, voffA);
;             PG8_WAIT_V(8); PG8_WAIT_L(0); PG8_BAR; PG8_MMA(0, 0, At, B0); PG8_MMA(0, 1, At, B1); PG8_BAR; PG8_SCHED;
;             PG8_LDA(At, 0, 1); PG8_STAGE(PG8_SB(0, 0), b2, voffB); PG8_STAGE(PG8_SB(0, 1), b2 + bhs, voffB); PG8_STAGE(PG8_SA(0, 0), a2, voffA);
;             PG8_WAIT_V(8); PG8_WAIT_L(0); PG8_BAR; PG8_MMA(1, 0, At, B0); PG8_MMA(1, 1, At, B1); PG8_BAR; PG8_SCHED;
.LBB0_261:
	s_add_u32 s30, s28, 0xfff80080
	s_addc_u32 s31, s29, -1
	s_add_i32 s49, 0, 0x10000
	s_cmp_eq_u32 s48, 28
	s_cselect_b32 s35, s19, s31
	s_cselect_b32 s34, s44, s30
	v_add_u32_e32 v142, s49, v149
	s_cselect_b32 s31, s17, s47
	s_cselect_b32 s30, s45, s46
	s_add_i32 s52, 0, 0x14000
	ds_read_b128 v[156:159], v142
	ds_read_b128 v[160:163], v142 offset:1024
	ds_read_b128 v[164:167], v142 offset:2048
	ds_read_b128 v[178:181], v142 offset:3072
	v_add_u32_e32 v142, s52, v149
	ds_read_b128 v[182:185], v142
	ds_read_b128 v[186:189], v142 offset:1024
	ds_read_b128 v[190:193], v142 offset:2048
	ds_read_b128 v[194:197], v142 offset:3072
	v_lshl_add_u64 v[142:143], s[28:29], 0, v[140:141]
	s_add_i32 m0, s2, 0xc000
	ds_read_b128 v[198:201], v154
	global_load_lds_dwordx4 v[142:143], off
	ds_read_b128 v[212:215], v154 offset:1024
	ds_read_b128 v[216:219], v154 offset:2048
	s_add_i32 m0, s2, 0xe000
	v_lshl_add_u64 v[142:143], s[28:29], 0, v[138:139]
	global_load_lds_dwordx4 v[142:143], off
	ds_read_b128 v[220:223], v154 offset:3072
	ds_read_b128 v[224:227], v154 offset:4096
	ds_read_b128 v[228:231], v154 offset:5120
	ds_read_b128 v[232:235], v154 offset:6144
	ds_read_b128 v[236:239], v154 offset:7168
	s_waitcnt vmcnt(8)
	s_waitcnt lgkmcnt(0)
	s_barrier
	s_setprio 1
	s_waitcnt lgkmcnt(0)
	v_mfma_f32_16x16x32_bf16 v[126:129], v[156:159], v[198:201], v[126:129]
	v_mfma_f32_16x16x32_bf16 v[122:125], v[164:167], v[198:201], v[122:125]
	v_mfma_f32_16x16x32_bf16 v[110:113], v[156:159], v[216:219], v[110:113]
	v_mfma_f32_16x16x32_bf16 v[106:109], v[164:167], v[216:219], v[106:109]
	v_mfma_f32_16x16x32_bf16 v[94:97], v[156:159], v[224:227], v[94:97]
	v_mfma_f32_16x16x32_bf16 v[90:93], v[164:167], v[224:227], v[90:93]
	v_mfma_f32_16x16x32_bf16 v[78:81], v[156:159], v[232:235], v[78:81]
	v_mfma_f32_16x16x32_bf16 v[74:77], v[164:167], v[232:235], v[74:77]
	v_mfma_f32_16x16x32_bf16 v[126:129], v[160:163], v[212:215], v[126:129]
	v_mfma_f32_16x16x32_bf16 v[122:125], v[178:181], v[212:215], v[122:125]
	v_mfma_f32_16x16x32_bf16 v[110:113], v[160:163], v[220:223], v[110:113]
	v_mfma_f32_16x16x32_bf16 v[106:109], v[178:181], v[220:223], v[106:109]
	v_mfma_f32_16x16x32_bf16 v[94:97], v[160:163], v[228:231], v[94:97]
	v_mfma_f32_16x16x32_bf16 v[90:93], v[178:181], v[228:231], v[90:93]
	v_mfma_f32_16x16x32_bf16 v[78:81], v[160:163], v[236:239], v[78:81]
	v_mfma_f32_16x16x32_bf16 v[74:77], v[178:181], v[236:239], v[74:77]
	s_setprio 0
	s_setprio 1
	v_mfma_f32_16x16x32_bf16 v[118:121], v[182:185], v[198:201], v[118:121]
	v_mfma_f32_16x16x32_bf16 v[114:117], v[190:193], v[198:201], v[114:117]
	v_mfma_f32_16x16x32_bf16 v[102:105], v[182:185], v[216:219], v[102:105]
	v_mfma_f32_16x16x32_bf16 v[98:101], v[190:193], v[216:219], v[98:101]
	v_mfma_f32_16x16x32_bf16 v[86:89], v[182:185], v[224:227], v[86:89]
	v_mfma_f32_16x16x32_bf16 v[82:85], v[190:193], v[224:227], v[82:85]
	v_mfma_f32_16x16x32_bf16 v[70:73], v[182:185], v[232:235], v[70:73]
	v_mfma_f32_16x16x32_bf16 v[66:69], v[190:193], v[232:235], v[66:69]
	v_mfma_f32_16x16x32_bf16 v[118:121], v[186:189], v[212:215], v[118:121]
	v_mfma_f32_16x16x32_bf16 v[114:117], v[194:197], v[212:215], v[114:117]
	v_mfma_f32_16x16x32_bf16 v[102:105], v[186:189], v[220:223], v[102:105]
	v_mfma_f32_16x16x32_bf16 v[98:101], v[194:197], v[220:223], v[98:101]
	v_mfma_f32_16x16x32_bf16 v[86:89], v[186:189], v[228:231], v[86:89]
	v_mfma_f32_16x16x32_bf16 v[82:85], v[194:197], v[228:231], v[82:85]
	v_mfma_f32_16x16x32_bf16 v[70:73], v[186:189], v[236:239], v[70:73]
	v_mfma_f32_16x16x32_bf16 v[66:69], v[194:197], v[236:239], v[66:69]
	s_setprio 0
	s_barrier
	s_add_i32 s49, s49, s36
	v_lshl_add_u64 v[142:143], s[30:31], 0, v[0:1]
	s_mov_b32 m0, s49
	ds_read_b128 v[198:201], v154 offset:16384
	global_load_lds_dwordx4 v[142:143], off
	ds_read_b128 v[212:215], v154 offset:17408
	ds_read_b128 v[216:219], v154 offset:18432
	s_add_i32 m0, s49, 0x2000
	s_add_u32 s50, s30, 0x8000
	v_lshl_add_u64 v[168:169], s[30:31], 0, v[134:135]
	s_addc_u32 s51, s31, 0
	s_add_i32 s49, s52, s36
	global_load_lds_dwordx4 v[168:169], off
	ds_read_b128 v[220:223], v154 offset:19456
	ds_read_b128 v[224:227], v154 offset:20480
	v_lshl_add_u64 v[172:173], s[50:51], 0, v[0:1]
	s_mov_b32 m0, s49
	v_lshl_add_u64 v[174:175], s[34:35], 0, v[132:133]
	global_load_lds_dwordx4 v[172:173], off
	ds_read_b128 v[228:231], v154 offset:21504
	ds_read_b128 v[232:235], v154 offset:22528
	s_add_i32 m0, s49, 0x2000
	v_lshl_add_u64 v[172:173], s[50:51], 0, v[134:135]
	global_load_lds_dwordx4 v[172:173], off
	ds_read_b128 v[236:239], v154 offset:23552
	s_mov_b32 m0, s2
	v_lshl_add_u64 v[172:173], s[34:35], 0, v[130:131]
	global_load_lds_dwordx4 v[172:173], off
	s_mov_b32 m0, s27
	s_nop 0
	global_load_lds_dwordx4 v[174:175], off
	s_waitcnt vmcnt(8)
	s_waitcnt lgkmcnt(0)
	s_barrier
; #define PG8_STAGE(bufoff, gbase, voff) do { _Pragma("unroll") for (int _i = 0; _i < 2; ++_i) \
;         __builtin_amdgcn_global_load_lds((const unsigned*)((const char*)(gbase) + (voff)[_i]), (LAS unsigned*)(lds + (bufoff) + ldsw + _i * 8192), 16, 0, 0); } while (0)
; #define PG8_LDA(dst, b, h) do { _Pragma("unroll") for (int m = 0; m < 4; ++m) _Pragma("unroll") for (int k = 0; k < 2; ++k) dst[m][k] = *(const LAS bf16x8*)(lds + PG8_SA(b, h) + aoff + m * 2048 + k * 1024); } while (0)
; #define PG8_LDB(dst, b, h) do { _Pragma("unroll") for (int n = 0; n < 2; ++n) _Pragma("unroll") for (int k = 0; k < 2; ++k) dst[n][k] = *(const LAS bf16x8*)(lds + PG8_SB(b, h) + boff + n * 2048 + k * 1024); } while (0)
; #define PG8_MMA(ai, bj, At, Bt) do { __builtin_amdgcn_s_setprio(1); _Pragma("unroll") for (int m = 0; m < 4; ++m) _Pragma("unroll") for (int n = 0; n < 2; ++n) _Pragma("unroll") for (int k = 0; k < 2; ++k) \
;         acc[ai][bj][m][n] = __builtin_amdgcn_mfma_f32_16x16x32_bf16(Bt[n][k], At[m][k], acc[ai][bj][m][n], 0, 0, 0); __builtin_amdgcn_s_setprio(0); } while (0)
; #define PG8_WAIT_V(n) asm volatile("s_waitcnt vmcnt(" #n ")" ::: "memory")
; #define PG8_WAIT_L(n) asm volatile("s_waitcnt lgkmcnt(" #n ")" ::: "memory")
; #define PG8_BAR __builtin_amdgcn_s_barrier()
; #define PG8_SCHED __builtin_amdgcn_sched_barrier(0)
; template <class Epi>
; __device__ __forceinline__ void gemm_phase(LAS unsigned char* lds, const Gemm g, const StaticOrder& S, const Epi& E, const int tid) {
;     ...
;             PG8_WAIT_V(8); PG8_WAIT_L(0); PG8_BAR; PG8_MMA(1, 0, At, B0); PG8_MMA(1, 1, At, B1); PG8_BAR; PG8_SCHED;
;             PG8_LDB(B0, 1, 0); PG8_LDB(B1, 1, 1); PG8_SCHED; PG8_LDA(At, 1, 0); PG8_STAGE(PG8_SA(0, 1), a2 + hstep, voffA);
;             PG8_WAIT_V(8); PG8_WAIT_L(0); PG8_BAR; PG8_MMA(0, 0, At, B0); PG8_MMA(0, 1, At, B1); PG8_BAR; PG8_SCHED;
	s_setprio 1
	s_waitcnt lgkmcnt(0)
	v_mfma_f32_16x16x32_bf16 v[62:65], v[156:159], v[198:201], v[62:65]
	v_mfma_f32_16x16x32_bf16 v[58:61], v[164:167], v[198:201], v[58:61]
	v_mfma_f32_16x16x32_bf16 v[46:49], v[156:159], v[216:219], v[46:49]
	v_mfma_f32_16x16x32_bf16 v[42:45], v[164:167], v[216:219], v[42:45]
	v_mfma_f32_16x16x32_bf16 v[30:33], v[156:159], v[224:227], v[30:33]
	v_mfma_f32_16x16x32_bf16 v[26:29], v[164:167], v[224:227], v[26:29]
	v_mfma_f32_16x16x32_bf16 v[14:17], v[156:159], v[232:235], v[14:17]
	v_mfma_f32_16x16x32_bf16 v[10:13], v[164:167], v[232:235], v[10:13]
	v_mfma_f32_16x16x32_bf16 v[62:65], v[160:163], v[212:215], v[62:65]
	v_mfma_f32_16x16x32_bf16 v[58:61], v[178:181], v[212:215], v[58:61]
	v_mfma_f32_16x16x32_bf16 v[46:49], v[160:163], v[220:223], v[46:49]
	v_mfma_f32_16x16x32_bf16 v[42:45], v[178:181], v[220:223], v[42:45]
	v_mfma_f32_16x16x32_bf16 v[30:33], v[160:163], v[228:231], v[30:33]
	v_mfma_f32_16x16x32_bf16 v[26:29], v[178:181], v[228:231], v[26:29]
	v_mfma_f32_16x16x32_bf16 v[14:17], v[160:163], v[236:239], v[14:17]
	v_mfma_f32_16x16x32_bf16 v[10:13], v[178:181], v[236:239], v[10:13]
	s_setprio 0
	s_setprio 1
	v_mfma_f32_16x16x32_bf16 v[54:57], v[182:185], v[198:201], v[54:57]
	v_mfma_f32_16x16x32_bf16 v[50:53], v[190:193], v[198:201], v[50:53]
	v_mfma_f32_16x16x32_bf16 v[38:41], v[182:185], v[216:219], v[38:41]
	v_mfma_f32_16x16x32_bf16 v[34:37], v[190:193], v[216:219], v[34:37]
	v_mfma_f32_16x16x32_bf16 v[22:25], v[182:185], v[224:227], v[22:25]
	v_mfma_f32_16x16x32_bf16 v[18:21], v[190:193], v[224:227], v[18:21]
	v_mfma_f32_16x16x32_bf16 v[6:9], v[182:185], v[232:235], v[6:9]
	v_mfma_f32_16x16x32_bf16 v[2:5], v[190:193], v[232:235], v[2:5]
	v_mfma_f32_16x16x32_bf16 v[54:57], v[186:189], v[212:215], v[54:57]
	v_mfma_f32_16x16x32_bf16 v[50:53], v[194:197], v[212:215], v[50:53]
	v_mfma_f32_16x16x32_bf16 v[38:41], v[186:189], v[220:223], v[38:41]
	v_mfma_f32_16x16x32_bf16 v[34:37], v[194:197], v[220:223], v[34:37]
	v_mfma_f32_16x16x32_bf16 v[22:25], v[186:189], v[228:231], v[22:25]
	v_mfma_f32_16x16x32_bf16 v[18:21], v[194:197], v[228:231], v[18:21]
	v_mfma_f32_16x16x32_bf16 v[6:9], v[186:189], v[236:239], v[6:9]
	v_mfma_f32_16x16x32_bf16 v[2:5], v[194:197], v[236:239], v[2:5]
	s_setprio 0
	s_barrier
	s_add_i32 s49, 0, 0x18000
	v_add_u32_e32 v155, s49, v149
	s_add_i32 s50, 0, 0x1c000
	ds_read_b128 v[156:159], v155
	ds_read_b128 v[160:163], v155 offset:1024
	ds_read_b128 v[164:167], v155 offset:2048
	ds_read_b128 v[178:181], v155 offset:3072
	v_add_u32_e32 v155, s50, v149
	ds_read_b128 v[182:185], v155
	ds_read_b128 v[186:189], v155 offset:1024
	ds_read_b128 v[190:193], v155 offset:2048
	ds_read_b128 v[194:197], v155 offset:3072
	s_add_u32 s34, s34, 0x80000
	s_addc_u32 s35, s35, 0
	s_mov_b32 m0, s37
	v_lshl_add_u64 v[176:177], s[34:35], 0, v[130:131]
	ds_read_b128 v[198:201], v154 offset:32768
	global_load_lds_dwordx4 v[176:177], off
	ds_read_b128 v[212:215], v154 offset:33792
	ds_read_b128 v[216:219], v154 offset:34816
	s_mov_b32 m0, s38
	v_lshl_add_u64 v[176:177], s[34:35], 0, v[132:133]
	global_load_lds_dwordx4 v[176:177], off
	ds_read_b128 v[220:223], v154 offset:35840
	ds_read_b128 v[224:227], v154 offset:36864
	ds_read_b128 v[228:231], v154 offset:37888
	ds_read_b128 v[232:235], v154 offset:38912
	ds_read_b128 v[236:239], v154 offset:39936
	s_waitcnt vmcnt(8)
	s_waitcnt lgkmcnt(0)
	s_barrier
	s_setprio 1
	s_waitcnt lgkmcnt(0)
	v_mfma_f32_16x16x32_bf16 v[126:129], v[156:159], v[198:201], v[126:129]
	v_mfma_f32_16x16x32_bf16 v[122:125], v[164:167], v[198:201], v[122:125]
	v_mfma_f32_16x16x32_bf16 v[110:113], v[156:159], v[216:219], v[110:113]
	v_mfma_f32_16x16x32_bf16 v[106:109], v[164:167], v[216:219], v[106:109]
	v_mfma_f32_16x16x32_bf16 v[94:97], v[156:159], v[224:227], v[94:97]
	v_mfma_f32_16x16x32_bf16 v[90:93], v[164:167], v[224:227], v[90:93]
	v_mfma_f32_16x16x32_bf16 v[78:81], v[156:159], v[232:235], v[78:81]
	v_mfma_f32_16x16x32_bf16 v[74:77], v[164:167], v[232:235], v[74:77]
	v_mfma_f32_16x16x32_bf16 v[126:129], v[160:163], v[212:215], v[126:129]
	v_mfma_f32_16x16x32_bf16 v[122:125], v[178:181], v[212:215], v[122:125]
	v_mfma_f32_16x16x32_bf16 v[110:113], v[160:163], v[220:223], v[110:113]
	v_mfma_f32_16x16x32_bf16 v[106:109], v[178:181], v[220:223], v[106:109]
	v_mfma_f32_16x16x32_bf16 v[94:97], v[160:163], v[228:231], v[94:97]
	v_mfma_f32_16x16x32_bf16 v[90:93], v[178:181], v[228:231], v[90:93]
	v_mfma_f32_16x16x32_bf16 v[78:81], v[160:163], v[236:239], v[78:81]
	v_mfma_f32_16x16x32_bf16 v[74:77], v[178:181], v[236:239], v[74:77]
	s_setprio 0
	s_setprio 1
	v_mfma_f32_16x16x32_bf16 v[118:121], v[182:185], v[198:201], v[118:121]
	v_mfma_f32_16x16x32_bf16 v[114:117], v[190:193], v[198:201], v[114:117]
	v_mfma_f32_16x16x32_bf16 v[102:105], v[182:185], v[216:219], v[102:105]
	v_mfma_f32_16x16x32_bf16 v[98:101], v[190:193], v[216:219], v[98:101]
	v_mfma_f32_16x16x32_bf16 v[86:89], v[182:185], v[224:227], v[86:89]
	v_mfma_f32_16x16x32_bf16 v[82:85], v[190:193], v[224:227], v[82:85]
	v_mfma_f32_16x16x32_bf16 v[70:73], v[182:185], v[232:235], v[70:73]
	v_mfma_f32_16x16x32_bf16 v[66:69], v[190:193], v[232:235], v[66:69]
	v_mfma_f32_16x16x32_bf16 v[118:121], v[186:189], v[212:215], v[118:121]
	v_mfma_f32_16x16x32_bf16 v[114:117], v[194:197], v[212:215], v[114:117]
	v_mfma_f32_16x16x32_bf16 v[102:105], v[186:189], v[220:223], v[102:105]
	v_mfma_f32_16x16x32_bf16 v[98:101], v[194:197], v[220:223], v[98:101]
	v_mfma_f32_16x16x32_bf16 v[86:89], v[186:189], v[228:231], v[86:89]
	v_mfma_f32_16x16x32_bf16 v[82:85], v[194:197], v[228:231], v[82:85]
	v_mfma_f32_16x16x32_bf16 v[70:73], v[186:189], v[236:239], v[70:73]
	v_mfma_f32_16x16x32_bf16 v[66:69], v[194:197], v[236:239], v[66:69]
	s_setprio 0
	s_barrier
; #define PG8_STAGE(bufoff, gbase, voff) do { _Pragma("unroll") for (int _i = 0; _i < 2; ++_i) \
;         __builtin_amdgcn_global_load_lds((const unsigned*)((const char*)(gbase) + (voff)[_i]), (LAS unsigned*)(lds + (bufoff) + ldsw + _i * 8192), 16, 0, 0); } while (0)
; #define PG8_LDA(dst, b, h) do { _Pragma("unroll") for (int m = 0; m < 4; ++m) _Pragma("unroll") for (int k = 0; k < 2; ++k) dst[m][k] = *(const LAS bf16x8*)(lds + PG8_SA(b, h) + aoff + m * 2048 + k * 1024); } while (0)
; #define PG8_MMA(ai, bj, At, Bt) do { __builtin_amdgcn_s_setprio(1); _Pragma("unroll") for (int m = 0; m < 4; ++m) _Pragma("unroll") for (int n = 0; n < 2; ++n) _Pragma("unroll") for (int k = 0; k < 2; ++k) \
;         acc[ai][bj][m][n] = __builtin_amdgcn_mfma_f32_16x16x32_bf16(Bt[n][k], At[m][k], acc[ai][bj][m][n], 0, 0, 0); __builtin_amdgcn_s_setprio(0); } while (0)
; #define PG8_WAIT_V(n) asm volatile("s_waitcnt vmcnt(" #n ")" ::: "memory")
; #define PG8_WAIT_L(n) asm volatile("s_waitcnt lgkmcnt(" #n ")" ::: "memory")
; #define PG8_BAR __builtin_amdgcn_s_barrier()
; #define PG8_SCHED __builtin_amdgcn_sched_barrier(0)
; template <class Epi>
; __device__ __forceinline__ void gemm_phase(LAS unsigned char* lds, const Gemm g, const StaticOrder& S, const Epi& E, const int tid) {
;     ...
;             PG8_LDA(At, 1, 1); PG8_STAGE(PG8_SB(1, 0), b3, voffB); PG8_STAGE(PG8_SB(1, 1), b3 + bhs, voffB); PG8_STAGE(PG8_SA(1, 0), a3, voffA);
;             PG8_WAIT_V(8); PG8_WAIT_L(0); PG8_BAR; PG8_MMA(1, 0, At, B0); PG8_MMA(1, 1, At, B1); PG8_BAR; PG8_SCHED;
;     ...
;         if (ALIGN_EPI) { if (wr == 0) PG8_BAR; }
	s_add_i32 s34, s49, s36
	v_lshl_add_u64 v[142:143], v[142:143], 0, s[70:71]
	s_mov_b32 m0, s34
	ds_read_b128 v[198:201], v154 offset:49152
	global_load_lds_dwordx4 v[142:143], off
	ds_read_b128 v[212:215], v154 offset:50176
	ds_read_b128 v[216:219], v154 offset:51200
	s_add_i32 m0, s34, 0x2000
	s_add_u32 s30, s30, 0x8080
	v_lshl_add_u64 v[142:143], v[168:169], 0, s[70:71]
	s_addc_u32 s31, s31, 0
	s_add_i32 s34, s50, s36
	global_load_lds_dwordx4 v[142:143], off
	ds_read_b128 v[220:223], v154 offset:52224
	ds_read_b128 v[224:227], v154 offset:53248
	s_mov_b32 m0, s34
	v_lshl_add_u64 v[142:143], s[30:31], 0, v[0:1]
	global_load_lds_dwordx4 v[142:143], off
	ds_read_b128 v[228:231], v154 offset:54272
	ds_read_b128 v[232:235], v154 offset:55296
	s_add_i32 m0, s34, 0x2000
	v_lshl_add_u64 v[142:143], s[30:31], 0, v[134:135]
	global_load_lds_dwordx4 v[142:143], off
	ds_read_b128 v[236:239], v154 offset:56320
	s_mov_b32 m0, s39
	v_lshl_add_u64 v[142:143], v[172:173], 0, s[70:71]
	global_load_lds_dwordx4 v[142:143], off
	s_mov_b32 m0, s40
	v_lshl_add_u64 v[142:143], v[174:175], 0, s[70:71]
	global_load_lds_dwordx4 v[142:143], off
	s_waitcnt vmcnt(8)
	s_waitcnt lgkmcnt(0)
	s_barrier
	s_setprio 1
	s_waitcnt lgkmcnt(0)
	v_mfma_f32_16x16x32_bf16 v[62:65], v[156:159], v[198:201], v[62:65]
	v_mfma_f32_16x16x32_bf16 v[58:61], v[164:167], v[198:201], v[58:61]
	v_mfma_f32_16x16x32_bf16 v[46:49], v[156:159], v[216:219], v[46:49]
	v_mfma_f32_16x16x32_bf16 v[42:45], v[164:167], v[216:219], v[42:45]
	v_mfma_f32_16x16x32_bf16 v[30:33], v[156:159], v[224:227], v[30:33]
	v_mfma_f32_16x16x32_bf16 v[26:29], v[164:167], v[224:227], v[26:29]
	v_mfma_f32_16x16x32_bf16 v[14:17], v[156:159], v[232:235], v[14:17]
	v_mfma_f32_16x16x32_bf16 v[10:13], v[164:167], v[232:235], v[10:13]
	v_mfma_f32_16x16x32_bf16 v[62:65], v[160:163], v[212:215], v[62:65]
	v_mfma_f32_16x16x32_bf16 v[58:61], v[178:181], v[212:215], v[58:61]
	v_mfma_f32_16x16x32_bf16 v[46:49], v[160:163], v[220:223], v[46:49]
	v_mfma_f32_16x16x32_bf16 v[42:45], v[178:181], v[220:223], v[42:45]
	v_mfma_f32_16x16x32_bf16 v[30:33], v[160:163], v[228:231], v[30:33]
	v_mfma_f32_16x16x32_bf16 v[26:29], v[178:181], v[228:231], v[26:29]
	v_mfma_f32_16x16x32_bf16 v[14:17], v[160:163], v[236:239], v[14:17]
	v_mfma_f32_16x16x32_bf16 v[10:13], v[178:181], v[236:239], v[10:13]
	s_setprio 0
	s_setprio 1
	v_mfma_f32_16x16x32_bf16 v[54:57], v[182:185], v[198:201], v[54:57]
	v_mfma_f32_16x16x32_bf16 v[50:53], v[190:193], v[198:201], v[50:53]
	v_mfma_f32_16x16x32_bf16 v[38:41], v[182:185], v[216:219], v[38:41]
	v_mfma_f32_16x16x32_bf16 v[34:37], v[190:193], v[216:219], v[34:37]
	v_mfma_f32_16x16x32_bf16 v[22:25], v[182:185], v[224:227], v[22:25]
	v_mfma_f32_16x16x32_bf16 v[18:21], v[190:193], v[224:227], v[18:21]
	v_mfma_f32_16x16x32_bf16 v[6:9], v[182:185], v[232:235], v[6:9]
	v_mfma_f32_16x16x32_bf16 v[2:5], v[190:193], v[232:235], v[2:5]
	v_mfma_f32_16x16x32_bf16 v[54:57], v[186:189], v[212:215], v[54:57]
	v_mfma_f32_16x16x32_bf16 v[50:53], v[194:197], v[212:215], v[50:53]
	v_mfma_f32_16x16x32_bf16 v[38:41], v[186:189], v[220:223], v[38:41]
	v_mfma_f32_16x16x32_bf16 v[34:37], v[194:197], v[220:223], v[34:37]
	v_mfma_f32_16x16x32_bf16 v[22:25], v[186:189], v[228:231], v[22:25]
	v_mfma_f32_16x16x32_bf16 v[18:21], v[194:197], v[228:231], v[18:21]
	v_mfma_f32_16x16x32_bf16 v[6:9], v[186:189], v[236:239], v[6:9]
	v_mfma_f32_16x16x32_bf16 v[2:5], v[194:197], v[236:239], v[2:5]
	s_setprio 0
	s_barrier
	s_add_i32 s48, s48, 2
	s_add_u32 s46, s46, 0x100
	s_addc_u32 s47, s47, 0
	s_add_u32 s28, s28, 0x100
	s_addc_u32 s29, s29, 0
	s_cmp_gt_u32 s48, 29
	s_cbranch_scc0 .LBB0_261
	s_and_b64 vcc, exec, s[14:15]
	s_cbranch_vccz .LBB0_264
	s_barrier

; #define PG8_STAGE(bufoff, gbase, voff) do { _Pragma("unroll") for (int _i = 0; _i < 2; ++_i) \
;         __builtin_amdgcn_global_load_lds((const unsigned*)((const char*)(gbase) + (voff)[_i]), (LAS unsigned*)(lds + (bufoff) + ldsw + _i * 8192), 16, 0, 0); } while (0)
; #define PG8_LDA(dst, b, h) do { _Pragma("unroll") for (int m = 0; m < 4; ++m) _Pragma("unroll") for (int k = 0; k < 2; ++k) dst[m][k] = *(const LAS bf16x8*)(lds + PG8_SA(b, h) + aoff + m * 2048 + k * 1024); } while (0)
; #define PG8_LDB(dst, b, h) do { _Pragma("unroll") for (int n = 0; n < 2; ++n) _Pragma("unroll") for (int k = 0; k < 2; ++k) dst[n][k] = *(const LAS bf16x8*)(lds + PG8_SB(b, h) + boff + n * 2048 + k * 1024); } while (0)
; #define PG8_MMA(ai, bj, At, Bt) do { __builtin_amdgcn_s_setprio(1); _Pragma("unroll") for (int m = 0; m < 4; ++m) _Pragma("unroll") for (int n = 0; n < 2; ++n) _Pragma("unroll") for (int k = 0; k < 2; ++k) \
;         acc[ai][bj][m][n] = __builtin_amdgcn_mfma_f32_16x16x32_bf16(Bt[n][k], At[m][k], acc[ai][bj][m][n], 0, 0, 0); __builtin_amdgcn_s_setprio(0); } while (0)
; #define PG8_WAIT_V(n) asm volatile("s_waitcnt vmcnt(" #n ")" ::: "memory")
; #define PG8_WAIT_L(n) asm volatile("s_waitcnt lgkmcnt(" #n ")" ::: "memory")
; #define PG8_BAR __builtin_amdgcn_s_barrier()
; template <class Epi>
; __device__ __forceinline__ void gemm_phase(LAS unsigned char* lds, const Gemm g, const StaticOrder& S, const Epi& E, const int tid) {
;     ...
;             const char* a2 = last ? nA : (s2 ? cA2 + (size_t)(t + 2 - nt) * kstep : cA + (size_t)(t + 2) * kstep);
;             const char* b2 = last ? nB : (s2 ? cB2 + (size_t)(t + 2 - nt) * kstep : cB + (size_t)(t + 2) * kstep);
;             const char* a3 = a2 + kstep; const char* b3 = b2 + kstep;
;             if constexpr (Epi::TWO) { if (t == nt) E.mid(acc, cur, wr, wc, fr, fq); }
;             if constexpr (SP2) {
;             PG8_LDB(B0, 0, 0); PG8_LDB(B1, 0, 1); PG8_SCHED; PG8_LDA(At, 0, 0); PG8_STAGE(PG8_SA(1, 1), a1 + hstep, voffA);
;             PG8_WAIT_V(8); PG8_WAIT_L(0); PG8_BAR; PG8_MMA(0, 0, At, B0); PG8_MMA(0, 1, At, B1); PG8_BAR; PG8_SCHED;
;             PG8_LDA(At, 0, 1); PG8_STAGE(PG8_SB(0, 0), b2, voffB); PG8_STAGE(PG8_SB(0, 1), b2 + bhs, voffB); PG8_STAGE(PG8_SA(0, 0), a2, voffA);
;             PG8_WAIT_V(8); PG8_WAIT_L(0); PG8_BAR; PG8_MMA(1, 0, At, B0); PG8_MMA(1, 1, At, B1); PG8_BAR; PG8_SCHED;
.LBB0_314:
	s_add_u32 s40, s6, 0xfff80080
	s_addc_u32 s41, s7, -1
	s_add_i32 s56, 0, 0x10000
	s_cmp_eq_u32 s55, 28
	s_cselect_b32 s43, s27, s41
	s_cselect_b32 s42, s39, s40
	s_cselect_b32 s41, s25, s54
	s_cselect_b32 s40, s52, s53
	s_add_i32 s58, 0, 0x14000
	v_add_u32_e32 v46, s56, v212
	v_add_u32_e32 v70, s58, v212
	ds_read_b128 v[34:37], v46
	ds_read_b128 v[38:41], v46 offset:1024
	ds_read_b128 v[42:45], v46 offset:2048
	ds_read_b128 v[46:49], v46 offset:3072
	ds_read_b128 v[58:61], v70
	ds_read_b128 v[62:65], v70 offset:1024
	ds_read_b128 v[66:69], v70 offset:2048
	ds_read_b128 v[70:73], v70 offset:3072
	v_lshl_add_u64 v[172:173], s[6:7], 0, v[188:189]
	s_add_i32 m0, s44, 0xc000
	ds_read_b128 v[162:165], v220
	global_load_lds_dwordx4 v[172:173], off
	ds_read_b128 v[166:169], v220 offset:1024
	ds_read_b128 v[190:193], v220 offset:2048
	s_add_i32 m0, s44, 0xe000
	v_lshl_add_u64 v[172:173], s[6:7], 0, v[186:187]
	global_load_lds_dwordx4 v[172:173], off
	ds_read_b128 v[194:197], v220 offset:3072
	ds_read_b128 v[198:201], v220 offset:4096
	ds_read_b128 v[222:225], v220 offset:5120
	ds_read_b128 v[226:229], v220 offset:6144
	ds_read_b128 v[230:233], v220 offset:7168
	s_waitcnt vmcnt(8)
	s_waitcnt lgkmcnt(0)
	s_barrier
	s_setprio 1
	s_waitcnt lgkmcnt(0)
	v_mfma_f32_16x16x32_bf16 v[158:161], v[34:37], v[162:165], v[158:161]
	v_mfma_f32_16x16x32_bf16 v[154:157], v[42:45], v[162:165], v[154:157]
	v_mfma_f32_16x16x32_bf16 v[142:145], v[34:37], v[190:193], v[142:145]
	v_mfma_f32_16x16x32_bf16 v[138:141], v[42:45], v[190:193], v[138:141]
	v_mfma_f32_16x16x32_bf16 v[126:129], v[34:37], v[198:201], v[126:129]
	v_mfma_f32_16x16x32_bf16 v[122:125], v[42:45], v[198:201], v[122:125]
	v_mfma_f32_16x16x32_bf16 v[110:113], v[34:37], v[226:229], v[110:113]
	v_mfma_f32_16x16x32_bf16 v[106:109], v[42:45], v[226:229], v[106:109]
	v_mfma_f32_16x16x32_bf16 v[158:161], v[38:41], v[166:169], v[158:161]
	v_mfma_f32_16x16x32_bf16 v[154:157], v[46:49], v[166:169], v[154:157]
	v_mfma_f32_16x16x32_bf16 v[142:145], v[38:41], v[194:197], v[142:145]
	v_mfma_f32_16x16x32_bf16 v[138:141], v[46:49], v[194:197], v[138:141]
	v_mfma_f32_16x16x32_bf16 v[126:129], v[38:41], v[222:225], v[126:129]
	v_mfma_f32_16x16x32_bf16 v[122:125], v[46:49], v[222:225], v[122:125]
	v_mfma_f32_16x16x32_bf16 v[110:113], v[38:41], v[230:233], v[110:113]
	v_mfma_f32_16x16x32_bf16 v[106:109], v[46:49], v[230:233], v[106:109]
	s_setprio 0
	s_setprio 1
	v_mfma_f32_16x16x32_bf16 v[150:153], v[58:61], v[162:165], v[150:153]
	v_mfma_f32_16x16x32_bf16 v[146:149], v[66:69], v[162:165], v[146:149]
	v_mfma_f32_16x16x32_bf16 v[134:137], v[58:61], v[190:193], v[134:137]
	v_mfma_f32_16x16x32_bf16 v[130:133], v[66:69], v[190:193], v[130:133]
	v_mfma_f32_16x16x32_bf16 v[118:121], v[58:61], v[198:201], v[118:121]
	v_mfma_f32_16x16x32_bf16 v[114:117], v[66:69], v[198:201], v[114:117]
	v_mfma_f32_16x16x32_bf16 v[102:105], v[58:61], v[226:229], v[102:105]
	v_mfma_f32_16x16x32_bf16 v[98:101], v[66:69], v[226:229], v[98:101]
	v_mfma_f32_16x16x32_bf16 v[150:153], v[62:65], v[166:169], v[150:153]
	v_mfma_f32_16x16x32_bf16 v[146:149], v[70:73], v[166:169], v[146:149]
	v_mfma_f32_16x16x32_bf16 v[134:137], v[62:65], v[194:197], v[134:137]
	v_mfma_f32_16x16x32_bf16 v[130:133], v[70:73], v[194:197], v[130:133]
	v_mfma_f32_16x16x32_bf16 v[118:121], v[62:65], v[222:225], v[118:121]
	v_mfma_f32_16x16x32_bf16 v[114:117], v[70:73], v[222:225], v[114:117]
	v_mfma_f32_16x16x32_bf16 v[102:105], v[62:65], v[230:233], v[102:105]
	v_mfma_f32_16x16x32_bf16 v[98:101], v[70:73], v[230:233], v[98:101]
	s_setprio 0
	s_barrier
	s_add_i32 s56, s56, s33
	v_lshl_add_u64 v[172:173], s[40:41], 0, v[0:1]
	s_mov_b32 m0, s56
	ds_read_b128 v[162:165], v220 offset:16384
	global_load_lds_dwordx4 v[172:173], off
	ds_read_b128 v[166:169], v220 offset:17408
	ds_read_b128 v[190:193], v220 offset:18432
	s_add_i32 m0, s56, 0x2000
	s_add_u32 s56, s40, 0x8000
	v_lshl_add_u64 v[174:175], s[40:41], 0, v[182:183]
	s_addc_u32 s57, s41, 0
	s_add_i32 s58, s58, s33
	global_load_lds_dwordx4 v[174:175], off
	ds_read_b128 v[194:197], v220 offset:19456
	ds_read_b128 v[198:201], v220 offset:20480
	v_lshl_add_u64 v[176:177], s[56:57], 0, v[0:1]
	s_mov_b32 m0, s58
	v_lshl_add_u64 v[238:239], s[42:43], 0, v[180:181]
	global_load_lds_dwordx4 v[176:177], off
	ds_read_b128 v[222:225], v220 offset:21504
	ds_read_b128 v[226:229], v220 offset:22528
	s_add_i32 m0, s58, 0x2000
	v_lshl_add_u64 v[176:177], s[56:57], 0, v[182:183]
	global_load_lds_dwordx4 v[176:177], off
	ds_read_b128 v[230:233], v220 offset:23552
	s_mov_b32 m0, s44
	v_lshl_add_u64 v[176:177], s[42:43], 0, v[178:179]
	global_load_lds_dwordx4 v[176:177], off
	s_mov_b32 m0, s45
	s_nop 0
	global_load_lds_dwordx4 v[238:239], off
	s_waitcnt vmcnt(8)
	s_waitcnt lgkmcnt(0)
	s_barrier
; #define PG8_STAGE(bufoff, gbase, voff) do { _Pragma("unroll") for (int _i = 0; _i < 2; ++_i) \
;         __builtin_amdgcn_global_load_lds((const unsigned*)((const char*)(gbase) + (voff)[_i]), (LAS unsigned*)(lds + (bufoff) + ldsw + _i * 8192), 16, 0, 0); } while (0)
; #define PG8_LDA(dst, b, h) do { _Pragma("unroll") for (int m = 0; m < 4; ++m) _Pragma("unroll") for (int k = 0; k < 2; ++k) dst[m][k] = *(const LAS bf16x8*)(lds + PG8_SA(b, h) + aoff + m * 2048 + k * 1024); } while (0)
; #define PG8_LDB(dst, b, h) do { _Pragma("unroll") for (int n = 0; n < 2; ++n) _Pragma("unroll") for (int k = 0; k < 2; ++k) dst[n][k] = *(const LAS bf16x8*)(lds + PG8_SB(b, h) + boff + n * 2048 + k * 1024); } while (0)
; #define PG8_MMA(ai, bj, At, Bt) do { __builtin_amdgcn_s_setprio(1); _Pragma("unroll") for (int m = 0; m < 4; ++m) _Pragma("unroll") for (int n = 0; n < 2; ++n) _Pragma("unroll") for (int k = 0; k < 2; ++k) \
;         acc[ai][bj][m][n] = __builtin_amdgcn_mfma_f32_16x16x32_bf16(Bt[n][k], At[m][k], acc[ai][bj][m][n], 0, 0, 0); __builtin_amdgcn_s_setprio(0); } while (0)
; #define PG8_WAIT_V(n) asm volatile("s_waitcnt vmcnt(" #n ")" ::: "memory")
; #define PG8_WAIT_L(n) asm volatile("s_waitcnt lgkmcnt(" #n ")" ::: "memory")
; #define PG8_BAR __builtin_amdgcn_s_barrier()
; #define PG8_SCHED __builtin_amdgcn_sched_barrier(0)
; template <class Epi>
; __device__ __forceinline__ void gemm_phase(LAS unsigned char* lds, const Gemm g, const StaticOrder& S, const Epi& E, const int tid) {
;     ...
;             PG8_WAIT_V(8); PG8_WAIT_L(0); PG8_BAR; PG8_MMA(0, 0, At, B0); PG8_MMA(0, 1, At, B1); PG8_BAR; PG8_SCHED;
;             PG8_LDA(At, 0, 1); PG8_STAGE(PG8_SB(0, 0), b2, voffB); PG8_STAGE(PG8_SB(0, 1), b2 + bhs, voffB); PG8_STAGE(PG8_SA(0, 0), a2, voffA);
;             PG8_WAIT_V(8); PG8_WAIT_L(0); PG8_BAR; PG8_MMA(1, 0, At, B0); PG8_MMA(1, 1, At, B1); PG8_BAR; PG8_SCHED;
;             PG8_LDB(B0, 1, 0); PG8_LDB(B1, 1, 1); PG8_SCHED; PG8_LDA(At, 1, 0); PG8_STAGE(PG8_SA(0, 1), a2 + hstep, voffA);
;             PG8_WAIT_V(8); PG8_WAIT_L(0); PG8_BAR; PG8_MMA(0, 0, At, B0); PG8_MMA(0, 1, At, B1); PG8_BAR; PG8_SCHED;
	s_setprio 1
	s_waitcnt lgkmcnt(0)
	v_mfma_f32_16x16x32_bf16 v[94:97], v[34:37], v[162:165], v[94:97]
	v_mfma_f32_16x16x32_bf16 v[90:93], v[42:45], v[162:165], v[90:93]
	v_mfma_f32_16x16x32_bf16 v[78:81], v[34:37], v[190:193], v[78:81]
	v_mfma_f32_16x16x32_bf16 v[74:77], v[42:45], v[190:193], v[74:77]
	v_mfma_f32_16x16x32_bf16 v[30:33], v[34:37], v[198:201], v[30:33]
	v_mfma_f32_16x16x32_bf16 v[26:29], v[42:45], v[198:201], v[26:29]
	v_mfma_f32_16x16x32_bf16 v[14:17], v[34:37], v[226:229], v[14:17]
	v_mfma_f32_16x16x32_bf16 v[10:13], v[42:45], v[226:229], v[10:13]
	v_mfma_f32_16x16x32_bf16 v[94:97], v[38:41], v[166:169], v[94:97]
	v_mfma_f32_16x16x32_bf16 v[90:93], v[46:49], v[166:169], v[90:93]
	v_mfma_f32_16x16x32_bf16 v[78:81], v[38:41], v[194:197], v[78:81]
	v_mfma_f32_16x16x32_bf16 v[74:77], v[46:49], v[194:197], v[74:77]
	v_mfma_f32_16x16x32_bf16 v[30:33], v[38:41], v[222:225], v[30:33]
	v_mfma_f32_16x16x32_bf16 v[26:29], v[46:49], v[222:225], v[26:29]
	v_mfma_f32_16x16x32_bf16 v[14:17], v[38:41], v[230:233], v[14:17]
	v_mfma_f32_16x16x32_bf16 v[10:13], v[46:49], v[230:233], v[10:13]
	s_setprio 0
	s_setprio 1
	v_mfma_f32_16x16x32_bf16 v[22:25], v[58:61], v[198:201], v[22:25]
	v_mfma_f32_16x16x32_bf16 v[18:21], v[66:69], v[198:201], v[18:21]
	v_mfma_f32_16x16x32_bf16 v[6:9], v[58:61], v[226:229], v[6:9]
	v_mfma_f32_16x16x32_bf16 v[2:5], v[66:69], v[226:229], v[2:5]
	v_mfma_f32_16x16x32_bf16 v[34:37], v[58:61], v[162:165], v[86:89]
	v_mfma_f32_16x16x32_bf16 v[38:41], v[66:69], v[162:165], v[82:85]
	v_mfma_f32_16x16x32_bf16 v[42:45], v[58:61], v[190:193], v[54:57]
	v_mfma_f32_16x16x32_bf16 v[46:49], v[66:69], v[190:193], v[50:53]
	v_mfma_f32_16x16x32_bf16 v[22:25], v[62:65], v[222:225], v[22:25]
	v_mfma_f32_16x16x32_bf16 v[18:21], v[70:73], v[222:225], v[18:21]
	v_mfma_f32_16x16x32_bf16 v[6:9], v[62:65], v[230:233], v[6:9]
	v_mfma_f32_16x16x32_bf16 v[2:5], v[70:73], v[230:233], v[2:5]
	v_mfma_f32_16x16x32_bf16 v[34:37], v[62:65], v[166:169], v[34:37]
	v_mfma_f32_16x16x32_bf16 v[38:41], v[70:73], v[166:169], v[38:41]
	v_mfma_f32_16x16x32_bf16 v[42:45], v[62:65], v[194:197], v[42:45]
	v_mfma_f32_16x16x32_bf16 v[46:49], v[70:73], v[194:197], v[46:49]
	s_setprio 0
	s_barrier
	s_add_i32 s56, 0, 0x18000
	s_add_i32 s57, 0, 0x1c000
	v_add_u32_e32 v62, s56, v212
	v_add_u32_e32 v82, s57, v212
	ds_read_b128 v[50:53], v62
	ds_read_b128 v[54:57], v62 offset:1024
	ds_read_b128 v[58:61], v62 offset:2048
	ds_read_b128 v[62:65], v62 offset:3072
	ds_read_b128 v[66:69], v82
	ds_read_b128 v[70:73], v82 offset:1024
	ds_read_b128 v[162:165], v82 offset:2048
	ds_read_b128 v[166:169], v82 offset:3072
	s_add_u32 s42, s42, 0x80000
	s_addc_u32 s43, s43, 0
	s_mov_b32 m0, s46
	v_lshl_add_u64 v[234:235], s[42:43], 0, v[178:179]
	ds_read_b128 v[82:85], v220 offset:32768
	global_load_lds_dwordx4 v[234:235], off
	ds_read_b128 v[86:89], v220 offset:33792
	ds_read_b128 v[190:193], v220 offset:34816
	s_mov_b32 m0, s47
	v_lshl_add_u64 v[234:235], s[42:43], 0, v[180:181]
	global_load_lds_dwordx4 v[234:235], off
	ds_read_b128 v[194:197], v220 offset:35840
	ds_read_b128 v[198:201], v220 offset:36864
	ds_read_b128 v[222:225], v220 offset:37888
	ds_read_b128 v[226:229], v220 offset:38912
	ds_read_b128 v[230:233], v220 offset:39936
	s_waitcnt vmcnt(8)
	s_waitcnt lgkmcnt(0)
	s_barrier
	s_setprio 1
	s_waitcnt lgkmcnt(0)
	v_mfma_f32_16x16x32_bf16 v[158:161], v[50:53], v[82:85], v[158:161]
	v_mfma_f32_16x16x32_bf16 v[154:157], v[58:61], v[82:85], v[154:157]
	v_mfma_f32_16x16x32_bf16 v[142:145], v[50:53], v[190:193], v[142:145]
	v_mfma_f32_16x16x32_bf16 v[138:141], v[58:61], v[190:193], v[138:141]
	v_mfma_f32_16x16x32_bf16 v[126:129], v[50:53], v[198:201], v[126:129]
	v_mfma_f32_16x16x32_bf16 v[122:125], v[58:61], v[198:201], v[122:125]
	v_mfma_f32_16x16x32_bf16 v[110:113], v[50:53], v[226:229], v[110:113]
	v_mfma_f32_16x16x32_bf16 v[106:109], v[58:61], v[226:229], v[106:109]
	v_mfma_f32_16x16x32_bf16 v[158:161], v[54:57], v[86:89], v[158:161]
	v_mfma_f32_16x16x32_bf16 v[154:157], v[62:65], v[86:89], v[154:157]
	v_mfma_f32_16x16x32_bf16 v[142:145], v[54:57], v[194:197], v[142:145]
	v_mfma_f32_16x16x32_bf16 v[138:141], v[62:65], v[194:197], v[138:141]
	v_mfma_f32_16x16x32_bf16 v[126:129], v[54:57], v[222:225], v[126:129]
	v_mfma_f32_16x16x32_bf16 v[122:125], v[62:65], v[222:225], v[122:125]
	v_mfma_f32_16x16x32_bf16 v[110:113], v[54:57], v[230:233], v[110:113]
	v_mfma_f32_16x16x32_bf16 v[106:109], v[62:65], v[230:233], v[106:109]
	s_setprio 0
	s_setprio 1
	v_mfma_f32_16x16x32_bf16 v[150:153], v[66:69], v[82:85], v[150:153]
	v_mfma_f32_16x16x32_bf16 v[82:85], v[162:165], v[82:85], v[146:149]
	v_mfma_f32_16x16x32_bf16 v[146:149], v[166:169], v[86:89], v[82:85]
	v_mfma_f32_16x16x32_bf16 v[82:85], v[66:69], v[190:193], v[134:137]
	v_mfma_f32_16x16x32_bf16 v[134:137], v[70:73], v[194:197], v[82:85]
	v_mfma_f32_16x16x32_bf16 v[82:85], v[162:165], v[190:193], v[130:133]
	v_mfma_f32_16x16x32_bf16 v[130:133], v[166:169], v[194:197], v[82:85]
	v_mfma_f32_16x16x32_bf16 v[82:85], v[66:69], v[198:201], v[118:121]
	v_mfma_f32_16x16x32_bf16 v[118:121], v[70:73], v[222:225], v[82:85]
	v_mfma_f32_16x16x32_bf16 v[82:85], v[162:165], v[198:201], v[114:117]
	v_mfma_f32_16x16x32_bf16 v[114:117], v[166:169], v[222:225], v[82:85]
	v_mfma_f32_16x16x32_bf16 v[82:85], v[66:69], v[226:229], v[102:105]
	v_mfma_f32_16x16x32_bf16 v[102:105], v[70:73], v[230:233], v[82:85]
	v_mfma_f32_16x16x32_bf16 v[82:85], v[162:165], v[226:229], v[98:101]
	v_mfma_f32_16x16x32_bf16 v[150:153], v[70:73], v[86:89], v[150:153]
	v_mfma_f32_16x16x32_bf16 v[98:101], v[166:169], v[230:233], v[82:85]
	s_setprio 0
	s_barrier
; #define PG8_STAGE(bufoff, gbase, voff) do { _Pragma("unroll") for (int _i = 0; _i < 2; ++_i) \
;         __builtin_amdgcn_global_load_lds((const unsigned*)((const char*)(gbase) + (voff)[_i]), (LAS unsigned*)(lds + (bufoff) + ldsw + _i * 8192), 16, 0, 0); } while (0)
; #define PG8_LDA(dst, b, h) do { _Pragma("unroll") for (int m = 0; m < 4; ++m) _Pragma("unroll") for (int k = 0; k < 2; ++k) dst[m][k] = *(const LAS bf16x8*)(lds + PG8_SA(b, h) + aoff + m * 2048 + k * 1024); } while (0)
; #define PG8_MMA(ai, bj, At, Bt) do { __builtin_amdgcn_s_setprio(1); _Pragma("unroll") for (int m = 0; m < 4; ++m) _Pragma("unroll") for (int n = 0; n < 2; ++n) _Pragma("unroll") for (int k = 0; k < 2; ++k) \
;         acc[ai][bj][m][n] = __builtin_amdgcn_mfma_f32_16x16x32_bf16(Bt[n][k], At[m][k], acc[ai][bj][m][n], 0, 0, 0); __builtin_amdgcn_s_setprio(0); } while (0)
; #define PG8_WAIT_V(n) asm volatile("s_waitcnt vmcnt(" #n ")" ::: "memory")
; #define PG8_WAIT_L(n) asm volatile("s_waitcnt lgkmcnt(" #n ")" ::: "memory")
; #define PG8_BAR __builtin_amdgcn_s_barrier()
; #define PG8_SCHED __builtin_amdgcn_sched_barrier(0)
; template <class Epi>
; __device__ __forceinline__ void gemm_phase(LAS unsigned char* lds, const Gemm g, const StaticOrder& S, const Epi& E, const int tid) {
;     ...
;         for (int t = 0; t < ntt; t += 2) {
;             const bool last = (t == ntt - 2);
;             const bool s1 = Epi::TWO && (t >= nt), s2 = Epi::TWO && (t + 2 >= nt);
;     ...
;             PG8_LDA(At, 1, 1); PG8_STAGE(PG8_SB(1, 0), b3, voffB); PG8_STAGE(PG8_SB(1, 1), b3 + bhs, voffB); PG8_STAGE(PG8_SA(1, 0), a3, voffA);
;             PG8_WAIT_V(8); PG8_WAIT_L(0); PG8_BAR; PG8_MMA(1, 0, At, B0); PG8_MMA(1, 1, At, B1); PG8_BAR; PG8_SCHED;
	s_add_i32 s42, s56, s33
	v_lshl_add_u64 v[86:87], v[172:173], 0, s[70:71]
	s_mov_b32 m0, s42
	s_nop 0
	ds_read_b128 v[82:85], v220 offset:49152
	global_load_lds_dwordx4 v[86:87], off
	ds_read_b128 v[190:193], v220 offset:50176
	ds_read_b128 v[194:197], v220 offset:51200
	s_add_i32 m0, s42, 0x2000
	s_add_u32 s40, s40, 0x8080
	v_lshl_add_u64 v[86:87], v[174:175], 0, s[70:71]
	s_addc_u32 s41, s41, 0
	s_add_i32 s42, s57, s33
	global_load_lds_dwordx4 v[86:87], off
	ds_read_b128 v[198:201], v220 offset:52224
	ds_read_b128 v[222:225], v220 offset:53248
	s_mov_b32 m0, s42
	v_lshl_add_u64 v[86:87], s[40:41], 0, v[0:1]
	global_load_lds_dwordx4 v[86:87], off
	ds_read_b128 v[226:229], v220 offset:54272
	ds_read_b128 v[230:233], v220 offset:55296
	s_add_i32 m0, s42, 0x2000
	v_lshl_add_u64 v[86:87], s[40:41], 0, v[182:183]
	global_load_lds_dwordx4 v[86:87], off
	ds_read_b128 v[234:237], v220 offset:56320
	s_mov_b32 m0, s48
	v_lshl_add_u64 v[86:87], v[176:177], 0, s[70:71]
	global_load_lds_dwordx4 v[86:87], off
	s_mov_b32 m0, s49
	v_lshl_add_u64 v[86:87], v[238:239], 0, s[70:71]
	global_load_lds_dwordx4 v[86:87], off
	s_waitcnt vmcnt(8)
	s_waitcnt lgkmcnt(0)
	s_barrier
	s_setprio 1
	s_waitcnt lgkmcnt(0)
	v_mfma_f32_16x16x32_bf16 v[86:89], v[50:53], v[82:85], v[94:97]
	v_mfma_f32_16x16x32_bf16 v[94:97], v[54:57], v[190:193], v[86:89]
	v_mfma_f32_16x16x32_bf16 v[86:89], v[58:61], v[82:85], v[90:93]
	v_mfma_f32_16x16x32_bf16 v[78:81], v[50:53], v[194:197], v[78:81]
	v_mfma_f32_16x16x32_bf16 v[74:77], v[58:61], v[194:197], v[74:77]
	v_mfma_f32_16x16x32_bf16 v[30:33], v[50:53], v[222:225], v[30:33]
	v_mfma_f32_16x16x32_bf16 v[26:29], v[58:61], v[222:225], v[26:29]
	v_mfma_f32_16x16x32_bf16 v[14:17], v[50:53], v[230:233], v[14:17]
	v_mfma_f32_16x16x32_bf16 v[10:13], v[58:61], v[230:233], v[10:13]
	v_mfma_f32_16x16x32_bf16 v[90:93], v[62:65], v[190:193], v[86:89]
	v_mfma_f32_16x16x32_bf16 v[78:81], v[54:57], v[198:201], v[78:81]
	v_mfma_f32_16x16x32_bf16 v[74:77], v[62:65], v[198:201], v[74:77]
	v_mfma_f32_16x16x32_bf16 v[30:33], v[54:57], v[226:229], v[30:33]
	v_mfma_f32_16x16x32_bf16 v[26:29], v[62:65], v[226:229], v[26:29]
	v_mfma_f32_16x16x32_bf16 v[14:17], v[54:57], v[234:237], v[14:17]
	v_mfma_f32_16x16x32_bf16 v[10:13], v[62:65], v[234:237], v[10:13]
	s_setprio 0
	s_setprio 1
	v_mfma_f32_16x16x32_bf16 v[34:37], v[66:69], v[82:85], v[34:37]
	v_mfma_f32_16x16x32_bf16 v[86:89], v[70:73], v[190:193], v[34:37]
	v_mfma_f32_16x16x32_bf16 v[34:37], v[162:165], v[82:85], v[38:41]
	v_mfma_f32_16x16x32_bf16 v[82:85], v[166:169], v[190:193], v[34:37]
	v_mfma_f32_16x16x32_bf16 v[34:37], v[66:69], v[194:197], v[42:45]
	v_mfma_f32_16x16x32_bf16 v[54:57], v[70:73], v[198:201], v[34:37]
	v_mfma_f32_16x16x32_bf16 v[34:37], v[162:165], v[194:197], v[46:49]
	v_mfma_f32_16x16x32_bf16 v[22:25], v[66:69], v[222:225], v[22:25]
	v_mfma_f32_16x16x32_bf16 v[18:21], v[162:165], v[222:225], v[18:21]
	v_mfma_f32_16x16x32_bf16 v[6:9], v[66:69], v[230:233], v[6:9]
	v_mfma_f32_16x16x32_bf16 v[2:5], v[162:165], v[230:233], v[2:5]
	v_mfma_f32_16x16x32_bf16 v[50:53], v[166:169], v[198:201], v[34:37]
	v_mfma_f32_16x16x32_bf16 v[22:25], v[70:73], v[226:229], v[22:25]
	v_mfma_f32_16x16x32_bf16 v[18:21], v[166:169], v[226:229], v[18:21]
	v_mfma_f32_16x16x32_bf16 v[6:9], v[70:73], v[234:237], v[6:9]
	v_mfma_f32_16x16x32_bf16 v[2:5], v[166:169], v[234:237], v[2:5]
	s_setprio 0
	s_barrier
	s_add_i32 s55, s55, 2
	s_add_u32 s53, s53, 0x100
	s_addc_u32 s54, s54, 0
	s_add_u32 s6, s6, 0x100
	s_addc_u32 s7, s7, 0
	s_cmp_gt_u32 s55, 29
	s_cbranch_scc0 .LBB0_314
	s_and_b64 vcc, exec, s[22:23]
	s_cbranch_vccz .LBB0_317
	s_barrier

; #define PG8_STAGE(bufoff, gbase, voff) do { _Pragma("unroll") for (int _i = 0; _i < 2; ++_i) \
;         __builtin_amdgcn_global_load_lds((const unsigned*)((const char*)(gbase) + (voff)[_i]), (LAS unsigned*)(lds + (bufoff) + ldsw + _i * 8192), 16, 0, 0); } while (0)
; #define PG8_LDA(dst, b, h) do { _Pragma("unroll") for (int m = 0; m < 4; ++m) _Pragma("unroll") for (int k = 0; k < 2; ++k) dst[m][k] = *(const LAS bf16x8*)(lds + PG8_SA(b, h) + aoff + m * 2048 + k * 1024); } while (0)
; #define PG8_LDB(dst, b, h) do { _Pragma("unroll") for (int n = 0; n < 2; ++n) _Pragma("unroll") for (int k = 0; k < 2; ++k) dst[n][k] = *(const LAS bf16x8*)(lds + PG8_SB(b, h) + boff + n * 2048 + k * 1024); } while (0)
; #define PG8_MMA(ai, bj, At, Bt) do { __builtin_amdgcn_s_setprio(1); _Pragma("unroll") for (int m = 0; m < 4; ++m) _Pragma("unroll") for (int n = 0; n < 2; ++n) _Pragma("unroll") for (int k = 0; k < 2; ++k) \
;         acc[ai][bj][m][n] = __builtin_amdgcn_mfma_f32_16x16x32_bf16(Bt[n][k], At[m][k], acc[ai][bj][m][n], 0, 0, 0); __builtin_amdgcn_s_setprio(0); } while (0)
; #define PG8_WAIT_V(n) asm volatile("s_waitcnt vmcnt(" #n ")" ::: "memory")
; #define PG8_WAIT_L(n) asm volatile("s_waitcnt lgkmcnt(" #n ")" ::: "memory")
; #define PG8_BAR __builtin_amdgcn_s_barrier()
; #define PG8_SCHED __builtin_amdgcn_sched_barrier(0)
; template <class Epi>
; __device__ __forceinline__ void gemm_phase(LAS unsigned char* lds, const Gemm g, const StaticOrder& S, const Epi& E, const int tid) {
;     ...
;             PG8_LDB(B0, 0, 0); PG8_LDB(B1, 0, 1); PG8_SCHED; PG8_LDA(At, 0, 0); PG8_STAGE(PG8_SA(1, 1), a1 + hstep, voffA);
;             PG8_WAIT_V(8); PG8_WAIT_L(0); PG8_BAR; PG8_MMA(0, 0, At, B0); PG8_MMA(0, 1, At, B1); PG8_BAR; PG8_SCHED;
;             PG8_LDA(At, 0, 1); PG8_STAGE(PG8_SB(0, 0), b2, voffB); PG8_STAGE(PG8_SB(0, 1), b2 + bhs, voffB); PG8_STAGE(PG8_SA(0, 0), a2, voffA);
;             PG8_WAIT_V(8); PG8_WAIT_L(0); PG8_BAR; PG8_MMA(1, 0, At, B0); PG8_MMA(1, 1, At, B1); PG8_BAR; PG8_SCHED;
.LBB0_546:
	s_add_u32 s28, s26, 0xfff80080
	s_addc_u32 s29, s27, -1
	s_add_i32 s44, 0, 0x10000
	s_cmp_eq_u32 s39, 28
	s_cselect_b32 s35, s19, s29
	s_cselect_b32 s34, s31, s28
	v_add_u32_e32 v0, s44, v149
	s_cselect_b32 s29, s17, s38
	s_cselect_b32 s28, s33, s37
	s_add_i32 s46, 0, 0x14000
	ds_read_b128 v[150:153], v0
	ds_read_b128 v[154:157], v0 offset:1024
	ds_read_b128 v[158:161], v0 offset:2048
	ds_read_b128 v[186:189], v0 offset:3072
	v_add_u32_e32 v0, s46, v149
	ds_read_b128 v[190:193], v0
	ds_read_b128 v[194:197], v0 offset:1024
	ds_read_b128 v[198:201], v0 offset:2048
	ds_read_b128 v[212:215], v0 offset:3072
	v_lshl_add_u64 v[162:163], s[26:27], 0, v[146:147]
	s_add_i32 m0, s57, 0xc000
	ds_read_b128 v[216:219], v184
	global_load_lds_dwordx4 v[162:163], off
	ds_read_b128 v[220:223], v184 offset:1024
	ds_read_b128 v[224:227], v184 offset:2048
	s_add_i32 m0, s57, 0xe000
	v_lshl_add_u64 v[162:163], s[26:27], 0, v[144:145]
	global_load_lds_dwordx4 v[162:163], off
	ds_read_b128 v[228:231], v184 offset:3072
	ds_read_b128 v[232:235], v184 offset:4096
	ds_read_b128 v[236:239], v184 offset:5120
	ds_read_b128 v[240:243], v184 offset:6144
	ds_read_b128 v[244:247], v184 offset:7168
	s_waitcnt vmcnt(8)
	s_waitcnt lgkmcnt(0)
	s_barrier
	s_setprio 1
	s_waitcnt lgkmcnt(0)
	v_mfma_f32_16x16x32_bf16 v[126:129], v[150:153], v[216:219], v[126:129]
	v_mfma_f32_16x16x32_bf16 v[122:125], v[158:161], v[216:219], v[122:125]
	v_mfma_f32_16x16x32_bf16 v[110:113], v[150:153], v[224:227], v[110:113]
	v_mfma_f32_16x16x32_bf16 v[106:109], v[158:161], v[224:227], v[106:109]
	v_mfma_f32_16x16x32_bf16 v[94:97], v[150:153], v[232:235], v[94:97]
	v_mfma_f32_16x16x32_bf16 v[90:93], v[158:161], v[232:235], v[90:93]
	v_mfma_f32_16x16x32_bf16 v[78:81], v[150:153], v[240:243], v[78:81]
	v_mfma_f32_16x16x32_bf16 v[74:77], v[158:161], v[240:243], v[74:77]
	v_mfma_f32_16x16x32_bf16 v[126:129], v[154:157], v[220:223], v[126:129]
	v_mfma_f32_16x16x32_bf16 v[122:125], v[186:189], v[220:223], v[122:125]
	v_mfma_f32_16x16x32_bf16 v[110:113], v[154:157], v[228:231], v[110:113]
	v_mfma_f32_16x16x32_bf16 v[106:109], v[186:189], v[228:231], v[106:109]
	v_mfma_f32_16x16x32_bf16 v[94:97], v[154:157], v[236:239], v[94:97]
	v_mfma_f32_16x16x32_bf16 v[90:93], v[186:189], v[236:239], v[90:93]
	v_mfma_f32_16x16x32_bf16 v[78:81], v[154:157], v[244:247], v[78:81]
	v_mfma_f32_16x16x32_bf16 v[74:77], v[186:189], v[244:247], v[74:77]
	s_setprio 0
	s_setprio 1
	v_mfma_f32_16x16x32_bf16 v[118:121], v[190:193], v[216:219], v[118:121]
	v_mfma_f32_16x16x32_bf16 v[114:117], v[198:201], v[216:219], v[114:117]
	v_mfma_f32_16x16x32_bf16 v[102:105], v[190:193], v[224:227], v[102:105]
	v_mfma_f32_16x16x32_bf16 v[98:101], v[198:201], v[224:227], v[98:101]
	v_mfma_f32_16x16x32_bf16 v[86:89], v[190:193], v[232:235], v[86:89]
	v_mfma_f32_16x16x32_bf16 v[82:85], v[198:201], v[232:235], v[82:85]
	v_mfma_f32_16x16x32_bf16 v[70:73], v[190:193], v[240:243], v[70:73]
	v_mfma_f32_16x16x32_bf16 v[66:69], v[198:201], v[240:243], v[66:69]
	v_mfma_f32_16x16x32_bf16 v[118:121], v[194:197], v[220:223], v[118:121]
	v_mfma_f32_16x16x32_bf16 v[114:117], v[212:215], v[220:223], v[114:117]
	v_mfma_f32_16x16x32_bf16 v[102:105], v[194:197], v[228:231], v[102:105]
	v_mfma_f32_16x16x32_bf16 v[98:101], v[212:215], v[228:231], v[98:101]
	v_mfma_f32_16x16x32_bf16 v[86:89], v[194:197], v[236:239], v[86:89]
	v_mfma_f32_16x16x32_bf16 v[82:85], v[212:215], v[236:239], v[82:85]
	v_mfma_f32_16x16x32_bf16 v[70:73], v[194:197], v[244:247], v[70:73]
	v_mfma_f32_16x16x32_bf16 v[66:69], v[212:215], v[244:247], v[66:69]
	s_setprio 0
	s_barrier
	s_add_i32 s44, s44, s56
	v_lshl_add_u64 v[162:163], s[28:29], 0, v[132:133]
	s_mov_b32 m0, s44
	ds_read_b128 v[216:219], v184 offset:16384
	global_load_lds_dwordx4 v[162:163], off
	ds_read_b128 v[220:223], v184 offset:17408
	ds_read_b128 v[224:227], v184 offset:18432
	s_add_i32 m0, s44, 0x2000
	s_add_u32 s44, s28, 0x8000
	v_lshl_add_u64 v[248:249], s[28:29], 0, v[136:137]
	s_addc_u32 s45, s29, 0
	s_add_i32 s46, s46, s56
	global_load_lds_dwordx4 v[248:249], off
	ds_read_b128 v[228:231], v184 offset:19456
	ds_read_b128 v[232:235], v184 offset:20480
	v_lshl_add_u64 v[172:173], s[44:45], 0, v[132:133]
	s_mov_b32 m0, s46
	v_lshl_add_u64 v[174:175], s[34:35], 0, v[134:135]
	global_load_lds_dwordx4 v[172:173], off
	ds_read_b128 v[236:239], v184 offset:21504
	ds_read_b128 v[240:243], v184 offset:22528
	s_add_i32 m0, s46, 0x2000
	v_lshl_add_u64 v[172:173], s[44:45], 0, v[136:137]
	global_load_lds_dwordx4 v[172:173], off
	ds_read_b128 v[244:247], v184 offset:23552
	s_mov_b32 m0, s57
	v_lshl_add_u64 v[172:173], s[34:35], 0, v[130:131]
	global_load_lds_dwordx4 v[172:173], off
	s_mov_b32 m0, s58
	s_nop 0
	global_load_lds_dwordx4 v[174:175], off
	s_waitcnt vmcnt(8)
	s_waitcnt lgkmcnt(0)
	s_barrier
; #define PG8_STAGE(bufoff, gbase, voff) do { _Pragma("unroll") for (int _i = 0; _i < 2; ++_i) \
;         __builtin_amdgcn_global_load_lds((const unsigned*)((const char*)(gbase) + (voff)[_i]), (LAS unsigned*)(lds + (bufoff) + ldsw + _i * 8192), 16, 0, 0); } while (0)
; #define PG8_LDA(dst, b, h) do { _Pragma("unroll") for (int m = 0; m < 4; ++m) _Pragma("unroll") for (int k = 0; k < 2; ++k) dst[m][k] = *(const LAS bf16x8*)(lds + PG8_SA(b, h) + aoff + m * 2048 + k * 1024); } while (0)
; #define PG8_LDB(dst, b, h) do { _Pragma("unroll") for (int n = 0; n < 2; ++n) _Pragma("unroll") for (int k = 0; k < 2; ++k) dst[n][k] = *(const LAS bf16x8*)(lds + PG8_SB(b, h) + boff + n * 2048 + k * 1024); } while (0)
; #define PG8_MMA(ai, bj, At, Bt) do { __builtin_amdgcn_s_setprio(1); _Pragma("unroll") for (int m = 0; m < 4; ++m) _Pragma("unroll") for (int n = 0; n < 2; ++n) _Pragma("unroll") for (int k = 0; k < 2; ++k) \
;         acc[ai][bj][m][n] = __builtin_amdgcn_mfma_f32_16x16x32_bf16(Bt[n][k], At[m][k], acc[ai][bj][m][n], 0, 0, 0); __builtin_amdgcn_s_setprio(0); } while (0)
; #define PG8_WAIT_V(n) asm volatile("s_waitcnt vmcnt(" #n ")" ::: "memory")
; #define PG8_WAIT_L(n) asm volatile("s_waitcnt lgkmcnt(" #n ")" ::: "memory")
; #define PG8_BAR __builtin_amdgcn_s_barrier()
; #define PG8_SCHED __builtin_amdgcn_sched_barrier(0)
; template <class Epi>
; __device__ __forceinline__ void gemm_phase(LAS unsigned char* lds, const Gemm g, const StaticOrder& S, const Epi& E, const int tid) {
;     ...
;             PG8_WAIT_V(8); PG8_WAIT_L(0); PG8_BAR; PG8_MMA(0, 0, At, B0); PG8_MMA(0, 1, At, B1); PG8_BAR; PG8_SCHED;
;             PG8_LDA(At, 0, 1); PG8_STAGE(PG8_SB(0, 0), b2, voffB); PG8_STAGE(PG8_SB(0, 1), b2 + bhs, voffB); PG8_STAGE(PG8_SA(0, 0), a2, voffA);
;             PG8_WAIT_V(8); PG8_WAIT_L(0); PG8_BAR; PG8_MMA(1, 0, At, B0); PG8_MMA(1, 1, At, B1); PG8_BAR; PG8_SCHED;
;             PG8_LDB(B0, 1, 0); PG8_LDB(B1, 1, 1); PG8_SCHED; PG8_LDA(At, 1, 0); PG8_STAGE(PG8_SA(0, 1), a2 + hstep, voffA);
;             PG8_WAIT_V(8); PG8_WAIT_L(0); PG8_BAR; PG8_MMA(0, 0, At, B0); PG8_MMA(0, 1, At, B1); PG8_BAR; PG8_SCHED;
	s_setprio 1
	s_waitcnt lgkmcnt(0)
	v_mfma_f32_16x16x32_bf16 v[62:65], v[150:153], v[216:219], v[62:65]
	v_mfma_f32_16x16x32_bf16 v[58:61], v[158:161], v[216:219], v[58:61]
	v_mfma_f32_16x16x32_bf16 v[46:49], v[150:153], v[224:227], v[46:49]
	v_mfma_f32_16x16x32_bf16 v[42:45], v[158:161], v[224:227], v[42:45]
	v_mfma_f32_16x16x32_bf16 v[30:33], v[150:153], v[232:235], v[30:33]
	v_mfma_f32_16x16x32_bf16 v[26:29], v[158:161], v[232:235], v[26:29]
	v_mfma_f32_16x16x32_bf16 v[14:17], v[150:153], v[240:243], v[14:17]
	v_mfma_f32_16x16x32_bf16 v[10:13], v[158:161], v[240:243], v[10:13]
	v_mfma_f32_16x16x32_bf16 v[62:65], v[154:157], v[220:223], v[62:65]
	v_mfma_f32_16x16x32_bf16 v[58:61], v[186:189], v[220:223], v[58:61]
	v_mfma_f32_16x16x32_bf16 v[46:49], v[154:157], v[228:231], v[46:49]
	v_mfma_f32_16x16x32_bf16 v[42:45], v[186:189], v[228:231], v[42:45]
	v_mfma_f32_16x16x32_bf16 v[30:33], v[154:157], v[236:239], v[30:33]
	v_mfma_f32_16x16x32_bf16 v[26:29], v[186:189], v[236:239], v[26:29]
	v_mfma_f32_16x16x32_bf16 v[14:17], v[154:157], v[244:247], v[14:17]
	v_mfma_f32_16x16x32_bf16 v[10:13], v[186:189], v[244:247], v[10:13]
	s_setprio 0
	s_setprio 1
	v_mfma_f32_16x16x32_bf16 v[54:57], v[190:193], v[216:219], v[54:57]
	v_mfma_f32_16x16x32_bf16 v[50:53], v[198:201], v[216:219], v[50:53]
	v_mfma_f32_16x16x32_bf16 v[38:41], v[190:193], v[224:227], v[38:41]
	v_mfma_f32_16x16x32_bf16 v[34:37], v[198:201], v[224:227], v[34:37]
	v_mfma_f32_16x16x32_bf16 v[22:25], v[190:193], v[232:235], v[22:25]
	v_mfma_f32_16x16x32_bf16 v[18:21], v[198:201], v[232:235], v[18:21]
	v_mfma_f32_16x16x32_bf16 v[6:9], v[190:193], v[240:243], v[6:9]
	v_mfma_f32_16x16x32_bf16 v[2:5], v[198:201], v[240:243], v[2:5]
	v_mfma_f32_16x16x32_bf16 v[54:57], v[194:197], v[220:223], v[54:57]
	v_mfma_f32_16x16x32_bf16 v[50:53], v[212:215], v[220:223], v[50:53]
	v_mfma_f32_16x16x32_bf16 v[38:41], v[194:197], v[228:231], v[38:41]
	v_mfma_f32_16x16x32_bf16 v[34:37], v[212:215], v[228:231], v[34:37]
	v_mfma_f32_16x16x32_bf16 v[22:25], v[194:197], v[236:239], v[22:25]
	v_mfma_f32_16x16x32_bf16 v[18:21], v[212:215], v[236:239], v[18:21]
	v_mfma_f32_16x16x32_bf16 v[6:9], v[194:197], v[244:247], v[6:9]
	v_mfma_f32_16x16x32_bf16 v[2:5], v[212:215], v[244:247], v[2:5]
	s_setprio 0
	s_barrier
	s_add_i32 s44, 0, 0x18000
	v_add_u32_e32 v0, s44, v149
	s_add_i32 s45, 0, 0x1c000
	ds_read_b128 v[150:153], v0
	ds_read_b128 v[154:157], v0 offset:1024
	ds_read_b128 v[158:161], v0 offset:2048
	ds_read_b128 v[186:189], v0 offset:3072
	v_add_u32_e32 v0, s45, v149
	ds_read_b128 v[190:193], v0
	ds_read_b128 v[194:197], v0 offset:1024
	ds_read_b128 v[198:201], v0 offset:2048
	ds_read_b128 v[212:215], v0 offset:3072
	s_add_u32 s34, s34, 0x80000
	s_addc_u32 s35, s35, 0
	s_mov_b32 m0, s59
	v_lshl_add_u64 v[176:177], s[34:35], 0, v[130:131]
	ds_read_b128 v[216:219], v184 offset:32768
	global_load_lds_dwordx4 v[176:177], off
	ds_read_b128 v[220:223], v184 offset:33792
	ds_read_b128 v[224:227], v184 offset:34816
	s_mov_b32 m0, s60
	v_lshl_add_u64 v[176:177], s[34:35], 0, v[134:135]
	global_load_lds_dwordx4 v[176:177], off
	ds_read_b128 v[228:231], v184 offset:35840
	ds_read_b128 v[232:235], v184 offset:36864
	ds_read_b128 v[236:239], v184 offset:37888
	ds_read_b128 v[240:243], v184 offset:38912
	ds_read_b128 v[244:247], v184 offset:39936
	s_waitcnt vmcnt(8)
	s_waitcnt lgkmcnt(0)
	s_barrier
	s_setprio 1
	s_waitcnt lgkmcnt(0)
	v_mfma_f32_16x16x32_bf16 v[126:129], v[150:153], v[216:219], v[126:129]
	v_mfma_f32_16x16x32_bf16 v[122:125], v[158:161], v[216:219], v[122:125]
	v_mfma_f32_16x16x32_bf16 v[110:113], v[150:153], v[224:227], v[110:113]
	v_mfma_f32_16x16x32_bf16 v[106:109], v[158:161], v[224:227], v[106:109]
	v_mfma_f32_16x16x32_bf16 v[94:97], v[150:153], v[232:235], v[94:97]
	v_mfma_f32_16x16x32_bf16 v[90:93], v[158:161], v[232:235], v[90:93]
	v_mfma_f32_16x16x32_bf16 v[78:81], v[150:153], v[240:243], v[78:81]
	v_mfma_f32_16x16x32_bf16 v[74:77], v[158:161], v[240:243], v[74:77]
	v_mfma_f32_16x16x32_bf16 v[126:129], v[154:157], v[220:223], v[126:129]
	v_mfma_f32_16x16x32_bf16 v[122:125], v[186:189], v[220:223], v[122:125]
	v_mfma_f32_16x16x32_bf16 v[110:113], v[154:157], v[228:231], v[110:113]
	v_mfma_f32_16x16x32_bf16 v[106:109], v[186:189], v[228:231], v[106:109]
	v_mfma_f32_16x16x32_bf16 v[94:97], v[154:157], v[236:239], v[94:97]
	v_mfma_f32_16x16x32_bf16 v[90:93], v[186:189], v[236:239], v[90:93]
	v_mfma_f32_16x16x32_bf16 v[78:81], v[154:157], v[244:247], v[78:81]
	v_mfma_f32_16x16x32_bf16 v[74:77], v[186:189], v[244:247], v[74:77]
	s_setprio 0
	s_setprio 1
	v_mfma_f32_16x16x32_bf16 v[118:121], v[190:193], v[216:219], v[118:121]
	v_mfma_f32_16x16x32_bf16 v[114:117], v[198:201], v[216:219], v[114:117]
	v_mfma_f32_16x16x32_bf16 v[102:105], v[190:193], v[224:227], v[102:105]
	v_mfma_f32_16x16x32_bf16 v[98:101], v[198:201], v[224:227], v[98:101]
	v_mfma_f32_16x16x32_bf16 v[86:89], v[190:193], v[232:235], v[86:89]
	v_mfma_f32_16x16x32_bf16 v[82:85], v[198:201], v[232:235], v[82:85]
	v_mfma_f32_16x16x32_bf16 v[70:73], v[190:193], v[240:243], v[70:73]
	v_mfma_f32_16x16x32_bf16 v[66:69], v[198:201], v[240:243], v[66:69]
	v_mfma_f32_16x16x32_bf16 v[118:121], v[194:197], v[220:223], v[118:121]
	v_mfma_f32_16x16x32_bf16 v[114:117], v[212:215], v[220:223], v[114:117]
	v_mfma_f32_16x16x32_bf16 v[102:105], v[194:197], v[228:231], v[102:105]
	v_mfma_f32_16x16x32_bf16 v[98:101], v[212:215], v[228:231], v[98:101]
	v_mfma_f32_16x16x32_bf16 v[86:89], v[194:197], v[236:239], v[86:89]
	v_mfma_f32_16x16x32_bf16 v[82:85], v[212:215], v[236:239], v[82:85]
	v_mfma_f32_16x16x32_bf16 v[70:73], v[194:197], v[244:247], v[70:73]
	v_mfma_f32_16x16x32_bf16 v[66:69], v[212:215], v[244:247], v[66:69]
	s_setprio 0
	s_barrier
; #define PG8_STAGE(bufoff, gbase, voff) do { _Pragma("unroll") for (int _i = 0; _i < 2; ++_i) \
;         __builtin_amdgcn_global_load_lds((const unsigned*)((const char*)(gbase) + (voff)[_i]), (LAS unsigned*)(lds + (bufoff) + ldsw + _i * 8192), 16, 0, 0); } while (0)
; #define PG8_LDA(dst, b, h) do { _Pragma("unroll") for (int m = 0; m < 4; ++m) _Pragma("unroll") for (int k = 0; k < 2; ++k) dst[m][k] = *(const LAS bf16x8*)(lds + PG8_SA(b, h) + aoff + m * 2048 + k * 1024); } while (0)
; #define PG8_MMA(ai, bj, At, Bt) do { __builtin_amdgcn_s_setprio(1); _Pragma("unroll") for (int m = 0; m < 4; ++m) _Pragma("unroll") for (int n = 0; n < 2; ++n) _Pragma("unroll") for (int k = 0; k < 2; ++k) \
;         acc[ai][bj][m][n] = __builtin_amdgcn_mfma_f32_16x16x32_bf16(Bt[n][k], At[m][k], acc[ai][bj][m][n], 0, 0, 0); __builtin_amdgcn_s_setprio(0); } while (0)
; #define PG8_WAIT_V(n) asm volatile("s_waitcnt vmcnt(" #n ")" ::: "memory")
; #define PG8_WAIT_L(n) asm volatile("s_waitcnt lgkmcnt(" #n ")" ::: "memory")
; #define PG8_BAR __builtin_amdgcn_s_barrier()
; #define PG8_SCHED __builtin_amdgcn_sched_barrier(0)
; template <class Epi>
; __device__ __forceinline__ void gemm_phase(LAS unsigned char* lds, const Gemm g, const StaticOrder& S, const Epi& E, const int tid) {
;     ...
;         for (int t = 0; t < ntt; t += 2) {
;             const bool last = (t == ntt - 2);
;             const bool s1 = Epi::TWO && (t >= nt), s2 = Epi::TWO && (t + 2 >= nt);
;     ...
;             PG8_LDA(At, 1, 1); PG8_STAGE(PG8_SB(1, 0), b3, voffB); PG8_STAGE(PG8_SB(1, 1), b3 + bhs, voffB); PG8_STAGE(PG8_SA(1, 0), a3, voffA);
;             PG8_WAIT_V(8); PG8_WAIT_L(0); PG8_BAR; PG8_MMA(1, 0, At, B0); PG8_MMA(1, 1, At, B1); PG8_BAR; PG8_SCHED;
	s_add_i32 s34, s44, s56
	v_lshl_add_u64 v[162:163], v[162:163], 0, s[70:71]
	s_mov_b32 m0, s34
	ds_read_b128 v[216:219], v184 offset:49152
	global_load_lds_dwordx4 v[162:163], off
	ds_read_b128 v[220:223], v184 offset:50176
	ds_read_b128 v[224:227], v184 offset:51200
	s_add_i32 m0, s34, 0x2000
	s_add_u32 s28, s28, 0x8080
	v_lshl_add_u64 v[162:163], v[248:249], 0, s[70:71]
	s_addc_u32 s29, s29, 0
	s_add_i32 s34, s45, s56
	global_load_lds_dwordx4 v[162:163], off
	ds_read_b128 v[228:231], v184 offset:52224
	ds_read_b128 v[232:235], v184 offset:53248
	s_mov_b32 m0, s34
	v_lshl_add_u64 v[162:163], s[28:29], 0, v[132:133]
	global_load_lds_dwordx4 v[162:163], off
	ds_read_b128 v[236:239], v184 offset:54272
	ds_read_b128 v[240:243], v184 offset:55296
	s_add_i32 m0, s34, 0x2000
	v_lshl_add_u64 v[162:163], s[28:29], 0, v[136:137]
	global_load_lds_dwordx4 v[162:163], off
	ds_read_b128 v[244:247], v184 offset:56320
	s_mov_b32 m0, s61
	v_lshl_add_u64 v[162:163], v[172:173], 0, s[70:71]
	global_load_lds_dwordx4 v[162:163], off
	s_mov_b32 m0, s62
	v_lshl_add_u64 v[162:163], v[174:175], 0, s[70:71]
	global_load_lds_dwordx4 v[162:163], off
	s_waitcnt vmcnt(8)
	s_waitcnt lgkmcnt(0)
	s_barrier
	s_setprio 1
	s_waitcnt lgkmcnt(0)
	v_mfma_f32_16x16x32_bf16 v[62:65], v[150:153], v[216:219], v[62:65]
	v_mfma_f32_16x16x32_bf16 v[58:61], v[158:161], v[216:219], v[58:61]
	v_mfma_f32_16x16x32_bf16 v[46:49], v[150:153], v[224:227], v[46:49]
	v_mfma_f32_16x16x32_bf16 v[42:45], v[158:161], v[224:227], v[42:45]
	v_mfma_f32_16x16x32_bf16 v[30:33], v[150:153], v[232:235], v[30:33]
	v_mfma_f32_16x16x32_bf16 v[26:29], v[158:161], v[232:235], v[26:29]
	v_mfma_f32_16x16x32_bf16 v[14:17], v[150:153], v[240:243], v[14:17]
	v_mfma_f32_16x16x32_bf16 v[10:13], v[158:161], v[240:243], v[10:13]
	v_mfma_f32_16x16x32_bf16 v[62:65], v[154:157], v[220:223], v[62:65]
	v_mfma_f32_16x16x32_bf16 v[58:61], v[186:189], v[220:223], v[58:61]
	v_mfma_f32_16x16x32_bf16 v[46:49], v[154:157], v[228:231], v[46:49]
	v_mfma_f32_16x16x32_bf16 v[42:45], v[186:189], v[228:231], v[42:45]
	v_mfma_f32_16x16x32_bf16 v[30:33], v[154:157], v[236:239], v[30:33]
	v_mfma_f32_16x16x32_bf16 v[26:29], v[186:189], v[236:239], v[26:29]
	v_mfma_f32_16x16x32_bf16 v[14:17], v[154:157], v[244:247], v[14:17]
	v_mfma_f32_16x16x32_bf16 v[10:13], v[186:189], v[244:247], v[10:13]
	s_setprio 0
	s_setprio 1
	v_mfma_f32_16x16x32_bf16 v[54:57], v[190:193], v[216:219], v[54:57]
	v_mfma_f32_16x16x32_bf16 v[50:53], v[198:201], v[216:219], v[50:53]
	v_mfma_f32_16x16x32_bf16 v[38:41], v[190:193], v[224:227], v[38:41]
	v_mfma_f32_16x16x32_bf16 v[34:37], v[198:201], v[224:227], v[34:37]
	v_mfma_f32_16x16x32_bf16 v[22:25], v[190:193], v[232:235], v[22:25]
	v_mfma_f32_16x16x32_bf16 v[18:21], v[198:201], v[232:235], v[18:21]
	v_mfma_f32_16x16x32_bf16 v[6:9], v[190:193], v[240:243], v[6:9]
	v_mfma_f32_16x16x32_bf16 v[2:5], v[198:201], v[240:243], v[2:5]
	v_mfma_f32_16x16x32_bf16 v[54:57], v[194:197], v[220:223], v[54:57]
	v_mfma_f32_16x16x32_bf16 v[50:53], v[212:215], v[220:223], v[50:53]
	v_mfma_f32_16x16x32_bf16 v[38:41], v[194:197], v[228:231], v[38:41]
	v_mfma_f32_16x16x32_bf16 v[34:37], v[212:215], v[228:231], v[34:37]
	v_mfma_f32_16x16x32_bf16 v[22:25], v[194:197], v[236:239], v[22:25]
	v_mfma_f32_16x16x32_bf16 v[18:21], v[212:215], v[236:239], v[18:21]
	v_mfma_f32_16x16x32_bf16 v[6:9], v[194:197], v[244:247], v[6:9]
	v_mfma_f32_16x16x32_bf16 v[2:5], v[212:215], v[244:247], v[2:5]
	s_setprio 0
	s_barrier
	s_add_i32 s39, s39, 2
	s_add_u32 s37, s37, 0x100
	s_addc_u32 s38, s38, 0
	s_add_u32 s26, s26, 0x100
	s_addc_u32 s27, s27, 0
	s_cmp_gt_u32 s39, 29
	s_cbranch_scc0 .LBB0_546
	s_and_b64 vcc, exec, s[14:15]
	s_cbranch_vccz .LBB0_549
	s_barrier

; #define PG8_STAGE(bufoff, gbase, voff) do { _Pragma("unroll") for (int _i = 0; _i < 2; ++_i) \
;         __builtin_amdgcn_global_load_lds((const unsigned*)((const char*)(gbase) + (voff)[_i]), (LAS unsigned*)(lds + (bufoff) + ldsw + _i * 8192), 16, 0, 0); } while (0)
; #define PG8_LDA(dst, b, h) do { _Pragma("unroll") for (int m = 0; m < 4; ++m) _Pragma("unroll") for (int k = 0; k < 2; ++k) dst[m][k] = *(const LAS bf16x8*)(lds + PG8_SA(b, h) + aoff + m * 2048 + k * 1024); } while (0)
; #define PG8_LDB(dst, b, h) do { _Pragma("unroll") for (int n = 0; n < 2; ++n) _Pragma("unroll") for (int k = 0; k < 2; ++k) dst[n][k] = *(const LAS bf16x8*)(lds + PG8_SB(b, h) + boff + n * 2048 + k * 1024); } while (0)
; #define PG8_MMA(ai, bj, At, Bt) do { __builtin_amdgcn_s_setprio(1); _Pragma("unroll") for (int m = 0; m < 4; ++m) _Pragma("unroll") for (int n = 0; n < 2; ++n) _Pragma("unroll") for (int k = 0; k < 2; ++k) \
;         acc[ai][bj][m][n] = __builtin_amdgcn_mfma_f32_16x16x32_bf16(Bt[n][k], At[m][k], acc[ai][bj][m][n], 0, 0, 0); __builtin_amdgcn_s_setprio(0); } while (0)
; #define PG8_WAIT_V(n) asm volatile("s_waitcnt vmcnt(" #n ")" ::: "memory")
; #define PG8_WAIT_L(n) asm volatile("s_waitcnt lgkmcnt(" #n ")" ::: "memory")
; #define PG8_BAR __builtin_amdgcn_s_barrier()
; #define PG8_SCHED __builtin_amdgcn_sched_barrier(0)
; template <class Epi>
; __device__ __forceinline__ void gemm_phase(LAS unsigned char* lds, const Gemm g, const StaticOrder& S, const Epi& E, const int tid) {
;     ...
;             PG8_LDB(B0, 0, 0); PG8_LDB(B1, 0, 1); PG8_SCHED; PG8_LDA(At, 0, 0); PG8_STAGE(PG8_SA(1, 1), a1 + hstep, voffA);
;             PG8_WAIT_V(8); PG8_WAIT_L(0); PG8_BAR; PG8_MMA(0, 0, At, B0); PG8_MMA(0, 1, At, B1); PG8_BAR; PG8_SCHED;
;             PG8_LDA(At, 0, 1); PG8_STAGE(PG8_SB(0, 0), b2, voffB); PG8_STAGE(PG8_SB(0, 1), b2 + bhs, voffB); PG8_STAGE(PG8_SA(0, 0), a2, voffA);
;             PG8_WAIT_V(8); PG8_WAIT_L(0); PG8_BAR; PG8_MMA(1, 0, At, B0); PG8_MMA(1, 1, At, B1); PG8_BAR; PG8_SCHED;
.LBB0_844:
	s_add_u32 s28, s26, 0xfff80080
	s_addc_u32 s29, s27, -1
	s_add_i32 s48, 0, 0x10000
	s_cmp_eq_u32 s47, 28
	s_cselect_b32 s31, s15, s29
	s_cselect_b32 s30, s43, s28
	v_add_u32_e32 v145, s48, v142
	s_cselect_b32 s29, s13, s46
	s_cselect_b32 s28, s44, s45
	s_add_i32 s50, 0, 0x14000
	ds_read_b128 v[146:149], v145
	ds_read_b128 v[150:153], v145 offset:1024
	ds_read_b128 v[154:157], v145 offset:2048
	ds_read_b128 v[158:161], v145 offset:3072
	v_add_u32_e32 v145, s50, v142
	ds_read_b128 v[162:165], v145
	ds_read_b128 v[166:169], v145 offset:1024
	ds_read_b128 v[178:181], v145 offset:2048
	ds_read_b128 v[182:185], v145 offset:3072
	v_lshl_add_u64 v[172:173], s[26:27], 0, v[138:139]
	s_add_i32 m0, s23, 0xc000
	ds_read_b128 v[186:189], v144
	global_load_lds_dwordx4 v[172:173], off
	ds_read_b128 v[190:193], v144 offset:1024
	ds_read_b128 v[194:197], v144 offset:2048
	s_add_i32 m0, s23, 0xe000
	v_lshl_add_u64 v[172:173], s[26:27], 0, v[136:137]
	global_load_lds_dwordx4 v[172:173], off
	ds_read_b128 v[198:201], v144 offset:3072
	ds_read_b128 v[212:215], v144 offset:4096
	ds_read_b128 v[216:219], v144 offset:5120
	ds_read_b128 v[220:223], v144 offset:6144
	ds_read_b128 v[224:227], v144 offset:7168
	s_waitcnt vmcnt(8)
	s_waitcnt lgkmcnt(0)
	s_barrier
	s_setprio 1
	s_waitcnt lgkmcnt(0)
	v_mfma_f32_16x16x32_bf16 v[126:129], v[146:149], v[186:189], v[126:129]
	v_mfma_f32_16x16x32_bf16 v[122:125], v[154:157], v[186:189], v[122:125]
	v_mfma_f32_16x16x32_bf16 v[118:121], v[146:149], v[194:197], v[118:121]
	v_mfma_f32_16x16x32_bf16 v[110:113], v[154:157], v[194:197], v[110:113]
	v_mfma_f32_16x16x32_bf16 v[102:105], v[146:149], v[212:215], v[102:105]
	v_mfma_f32_16x16x32_bf16 v[94:97], v[154:157], v[212:215], v[94:97]
	v_mfma_f32_16x16x32_bf16 v[86:89], v[146:149], v[220:223], v[86:89]
	v_mfma_f32_16x16x32_bf16 v[78:81], v[154:157], v[220:223], v[78:81]
	v_mfma_f32_16x16x32_bf16 v[126:129], v[150:153], v[190:193], v[126:129]
	v_mfma_f32_16x16x32_bf16 v[122:125], v[158:161], v[190:193], v[122:125]
	v_mfma_f32_16x16x32_bf16 v[118:121], v[150:153], v[198:201], v[118:121]
	v_mfma_f32_16x16x32_bf16 v[110:113], v[158:161], v[198:201], v[110:113]
	v_mfma_f32_16x16x32_bf16 v[102:105], v[150:153], v[216:219], v[102:105]
	v_mfma_f32_16x16x32_bf16 v[94:97], v[158:161], v[216:219], v[94:97]
	v_mfma_f32_16x16x32_bf16 v[86:89], v[150:153], v[224:227], v[86:89]
	v_mfma_f32_16x16x32_bf16 v[78:81], v[158:161], v[224:227], v[78:81]
	s_setprio 0
	s_setprio 1
	v_mfma_f32_16x16x32_bf16 v[114:117], v[162:165], v[186:189], v[114:117]
	v_mfma_f32_16x16x32_bf16 v[106:109], v[178:181], v[186:189], v[106:109]
	v_mfma_f32_16x16x32_bf16 v[98:101], v[162:165], v[194:197], v[98:101]
	v_mfma_f32_16x16x32_bf16 v[90:93], v[178:181], v[194:197], v[90:93]
	v_mfma_f32_16x16x32_bf16 v[82:85], v[162:165], v[212:215], v[82:85]
	v_mfma_f32_16x16x32_bf16 v[74:77], v[178:181], v[212:215], v[74:77]
	v_mfma_f32_16x16x32_bf16 v[70:73], v[162:165], v[220:223], v[70:73]
	v_mfma_f32_16x16x32_bf16 v[66:69], v[178:181], v[220:223], v[66:69]
	v_mfma_f32_16x16x32_bf16 v[114:117], v[166:169], v[190:193], v[114:117]
	v_mfma_f32_16x16x32_bf16 v[106:109], v[182:185], v[190:193], v[106:109]
	v_mfma_f32_16x16x32_bf16 v[98:101], v[166:169], v[198:201], v[98:101]
	v_mfma_f32_16x16x32_bf16 v[90:93], v[182:185], v[198:201], v[90:93]
	v_mfma_f32_16x16x32_bf16 v[82:85], v[166:169], v[216:219], v[82:85]
	v_mfma_f32_16x16x32_bf16 v[74:77], v[182:185], v[216:219], v[74:77]
	v_mfma_f32_16x16x32_bf16 v[70:73], v[166:169], v[224:227], v[70:73]
	v_mfma_f32_16x16x32_bf16 v[66:69], v[182:185], v[224:227], v[66:69]
	s_setprio 0
	s_barrier
	s_add_i32 s48, s48, s37
	v_lshl_add_u64 v[172:173], s[28:29], 0, v[0:1]
	s_mov_b32 m0, s48
	ds_read_b128 v[186:189], v144 offset:16384
	global_load_lds_dwordx4 v[172:173], off
	ds_read_b128 v[190:193], v144 offset:17408
	ds_read_b128 v[194:197], v144 offset:18432
	s_add_i32 m0, s48, 0x2000
	s_add_u32 s48, s28, 0x8000
	v_lshl_add_u64 v[174:175], s[28:29], 0, v[134:135]
	s_addc_u32 s49, s29, 0
	s_add_i32 s50, s50, s37
	global_load_lds_dwordx4 v[174:175], off
	ds_read_b128 v[198:201], v144 offset:19456
	ds_read_b128 v[212:215], v144 offset:20480
	v_lshl_add_u64 v[176:177], s[48:49], 0, v[0:1]
	s_mov_b32 m0, s50
	v_lshl_add_u64 v[228:229], s[30:31], 0, v[132:133]
	global_load_lds_dwordx4 v[176:177], off
	ds_read_b128 v[216:219], v144 offset:21504
	ds_read_b128 v[220:223], v144 offset:22528
	s_add_i32 m0, s50, 0x2000
	v_lshl_add_u64 v[176:177], s[48:49], 0, v[134:135]
	global_load_lds_dwordx4 v[176:177], off
	ds_read_b128 v[224:227], v144 offset:23552
	s_mov_b32 m0, s23
	v_lshl_add_u64 v[176:177], s[30:31], 0, v[130:131]
	global_load_lds_dwordx4 v[176:177], off
	s_mov_b32 m0, s25
	s_nop 0
	global_load_lds_dwordx4 v[228:229], off
	s_waitcnt vmcnt(8)
	s_waitcnt lgkmcnt(0)
	s_barrier
; #define PG8_STAGE(bufoff, gbase, voff) do { _Pragma("unroll") for (int _i = 0; _i < 2; ++_i) \
;         __builtin_amdgcn_global_load_lds((const unsigned*)((const char*)(gbase) + (voff)[_i]), (LAS unsigned*)(lds + (bufoff) + ldsw + _i * 8192), 16, 0, 0); } while (0)
; #define PG8_LDA(dst, b, h) do { _Pragma("unroll") for (int m = 0; m < 4; ++m) _Pragma("unroll") for (int k = 0; k < 2; ++k) dst[m][k] = *(const LAS bf16x8*)(lds + PG8_SA(b, h) + aoff + m * 2048 + k * 1024); } while (0)
; #define PG8_LDB(dst, b, h) do { _Pragma("unroll") for (int n = 0; n < 2; ++n) _Pragma("unroll") for (int k = 0; k < 2; ++k) dst[n][k] = *(const LAS bf16x8*)(lds + PG8_SB(b, h) + boff + n * 2048 + k * 1024); } while (0)
; #define PG8_MMA(ai, bj, At, Bt) do { __builtin_amdgcn_s_setprio(1); _Pragma("unroll") for (int m = 0; m < 4; ++m) _Pragma("unroll") for (int n = 0; n < 2; ++n) _Pragma("unroll") for (int k = 0; k < 2; ++k) \
;         acc[ai][bj][m][n] = __builtin_amdgcn_mfma_f32_16x16x32_bf16(Bt[n][k], At[m][k], acc[ai][bj][m][n], 0, 0, 0); __builtin_amdgcn_s_setprio(0); } while (0)
; #define PG8_WAIT_V(n) asm volatile("s_waitcnt vmcnt(" #n ")" ::: "memory")
; #define PG8_WAIT_L(n) asm volatile("s_waitcnt lgkmcnt(" #n ")" ::: "memory")
; #define PG8_BAR __builtin_amdgcn_s_barrier()
; #define PG8_SCHED __builtin_amdgcn_sched_barrier(0)
; template <class Epi>
; __device__ __forceinline__ void gemm_phase(LAS unsigned char* lds, const Gemm g, const StaticOrder& S, const Epi& E, const int tid) {
;     ...
;             PG8_WAIT_V(8); PG8_WAIT_L(0); PG8_BAR; PG8_MMA(0, 0, At, B0); PG8_MMA(0, 1, At, B1); PG8_BAR; PG8_SCHED;
;             PG8_LDA(At, 0, 1); PG8_STAGE(PG8_SB(0, 0), b2, voffB); PG8_STAGE(PG8_SB(0, 1), b2 + bhs, voffB); PG8_STAGE(PG8_SA(0, 0), a2, voffA);
;             PG8_WAIT_V(8); PG8_WAIT_L(0); PG8_BAR; PG8_MMA(1, 0, At, B0); PG8_MMA(1, 1, At, B1); PG8_BAR; PG8_SCHED;
;             PG8_LDB(B0, 1, 0); PG8_LDB(B1, 1, 1); PG8_SCHED; PG8_LDA(At, 1, 0); PG8_STAGE(PG8_SA(0, 1), a2 + hstep, voffA);
;             PG8_WAIT_V(8); PG8_WAIT_L(0); PG8_BAR; PG8_MMA(0, 0, At, B0); PG8_MMA(0, 1, At, B1); PG8_BAR; PG8_SCHED;
	s_setprio 1
	s_waitcnt lgkmcnt(0)
	v_mfma_f32_16x16x32_bf16 v[62:65], v[146:149], v[186:189], v[62:65]
	v_mfma_f32_16x16x32_bf16 v[58:61], v[154:157], v[186:189], v[58:61]
	v_mfma_f32_16x16x32_bf16 v[54:57], v[146:149], v[194:197], v[54:57]
	v_mfma_f32_16x16x32_bf16 v[46:49], v[154:157], v[194:197], v[46:49]
	v_mfma_f32_16x16x32_bf16 v[38:41], v[146:149], v[212:215], v[38:41]
	v_mfma_f32_16x16x32_bf16 v[30:33], v[154:157], v[212:215], v[30:33]
	v_mfma_f32_16x16x32_bf16 v[22:25], v[146:149], v[220:223], v[22:25]
	v_mfma_f32_16x16x32_bf16 v[14:17], v[154:157], v[220:223], v[14:17]
	v_mfma_f32_16x16x32_bf16 v[62:65], v[150:153], v[190:193], v[62:65]
	v_mfma_f32_16x16x32_bf16 v[58:61], v[158:161], v[190:193], v[58:61]
	v_mfma_f32_16x16x32_bf16 v[54:57], v[150:153], v[198:201], v[54:57]
	v_mfma_f32_16x16x32_bf16 v[46:49], v[158:161], v[198:201], v[46:49]
	v_mfma_f32_16x16x32_bf16 v[38:41], v[150:153], v[216:219], v[38:41]
	v_mfma_f32_16x16x32_bf16 v[30:33], v[158:161], v[216:219], v[30:33]
	v_mfma_f32_16x16x32_bf16 v[22:25], v[150:153], v[224:227], v[22:25]
	v_mfma_f32_16x16x32_bf16 v[14:17], v[158:161], v[224:227], v[14:17]
	s_setprio 0
	s_setprio 1
	v_mfma_f32_16x16x32_bf16 v[50:53], v[162:165], v[186:189], v[50:53]
	v_mfma_f32_16x16x32_bf16 v[42:45], v[178:181], v[186:189], v[42:45]
	v_mfma_f32_16x16x32_bf16 v[34:37], v[162:165], v[194:197], v[34:37]
	v_mfma_f32_16x16x32_bf16 v[26:29], v[178:181], v[194:197], v[26:29]
	v_mfma_f32_16x16x32_bf16 v[18:21], v[162:165], v[212:215], v[18:21]
	v_mfma_f32_16x16x32_bf16 v[10:13], v[178:181], v[212:215], v[10:13]
	v_mfma_f32_16x16x32_bf16 v[6:9], v[162:165], v[220:223], v[6:9]
	v_mfma_f32_16x16x32_bf16 v[2:5], v[178:181], v[220:223], v[2:5]
	v_mfma_f32_16x16x32_bf16 v[50:53], v[166:169], v[190:193], v[50:53]
	v_mfma_f32_16x16x32_bf16 v[42:45], v[182:185], v[190:193], v[42:45]
	v_mfma_f32_16x16x32_bf16 v[34:37], v[166:169], v[198:201], v[34:37]
	v_mfma_f32_16x16x32_bf16 v[26:29], v[182:185], v[198:201], v[26:29]
	v_mfma_f32_16x16x32_bf16 v[18:21], v[166:169], v[216:219], v[18:21]
	v_mfma_f32_16x16x32_bf16 v[10:13], v[182:185], v[216:219], v[10:13]
	v_mfma_f32_16x16x32_bf16 v[6:9], v[166:169], v[224:227], v[6:9]
	v_mfma_f32_16x16x32_bf16 v[2:5], v[182:185], v[224:227], v[2:5]
	s_setprio 0
	s_barrier
	s_add_i32 s48, 0, 0x18000
	v_add_u32_e32 v145, s48, v142
	s_add_i32 s49, 0, 0x1c000
	ds_read_b128 v[146:149], v145
	ds_read_b128 v[150:153], v145 offset:1024
	ds_read_b128 v[154:157], v145 offset:2048
	ds_read_b128 v[158:161], v145 offset:3072
	v_add_u32_e32 v145, s49, v142
	ds_read_b128 v[162:165], v145
	ds_read_b128 v[166:169], v145 offset:1024
	ds_read_b128 v[178:181], v145 offset:2048
	ds_read_b128 v[182:185], v145 offset:3072
	s_add_u32 s30, s30, 0x80000
	s_addc_u32 s31, s31, 0
	s_mov_b32 m0, s38
	v_lshl_add_u64 v[230:231], s[30:31], 0, v[130:131]
	ds_read_b128 v[186:189], v144 offset:32768
	global_load_lds_dwordx4 v[230:231], off
	ds_read_b128 v[190:193], v144 offset:33792
	ds_read_b128 v[194:197], v144 offset:34816
	s_mov_b32 m0, s39
	v_lshl_add_u64 v[230:231], s[30:31], 0, v[132:133]
	global_load_lds_dwordx4 v[230:231], off
	ds_read_b128 v[198:201], v144 offset:35840
	ds_read_b128 v[212:215], v144 offset:36864
	ds_read_b128 v[216:219], v144 offset:37888
	ds_read_b128 v[220:223], v144 offset:38912
	ds_read_b128 v[224:227], v144 offset:39936
	s_waitcnt vmcnt(8)
	s_waitcnt lgkmcnt(0)
	s_barrier
	s_setprio 1
	s_waitcnt lgkmcnt(0)
	v_mfma_f32_16x16x32_bf16 v[126:129], v[146:149], v[186:189], v[126:129]
	v_mfma_f32_16x16x32_bf16 v[122:125], v[154:157], v[186:189], v[122:125]
	v_mfma_f32_16x16x32_bf16 v[118:121], v[146:149], v[194:197], v[118:121]
	v_mfma_f32_16x16x32_bf16 v[110:113], v[154:157], v[194:197], v[110:113]
	v_mfma_f32_16x16x32_bf16 v[102:105], v[146:149], v[212:215], v[102:105]
	v_mfma_f32_16x16x32_bf16 v[94:97], v[154:157], v[212:215], v[94:97]
	v_mfma_f32_16x16x32_bf16 v[86:89], v[146:149], v[220:223], v[86:89]
	v_mfma_f32_16x16x32_bf16 v[78:81], v[154:157], v[220:223], v[78:81]
	v_mfma_f32_16x16x32_bf16 v[126:129], v[150:153], v[190:193], v[126:129]
	v_mfma_f32_16x16x32_bf16 v[122:125], v[158:161], v[190:193], v[122:125]
	v_mfma_f32_16x16x32_bf16 v[118:121], v[150:153], v[198:201], v[118:121]
	v_mfma_f32_16x16x32_bf16 v[110:113], v[158:161], v[198:201], v[110:113]
	v_mfma_f32_16x16x32_bf16 v[102:105], v[150:153], v[216:219], v[102:105]
	v_mfma_f32_16x16x32_bf16 v[94:97], v[158:161], v[216:219], v[94:97]
	v_mfma_f32_16x16x32_bf16 v[86:89], v[150:153], v[224:227], v[86:89]
	v_mfma_f32_16x16x32_bf16 v[78:81], v[158:161], v[224:227], v[78:81]
	s_setprio 0
	s_setprio 1
	v_mfma_f32_16x16x32_bf16 v[114:117], v[162:165], v[186:189], v[114:117]
	v_mfma_f32_16x16x32_bf16 v[106:109], v[178:181], v[186:189], v[106:109]
	v_mfma_f32_16x16x32_bf16 v[98:101], v[162:165], v[194:197], v[98:101]
	v_mfma_f32_16x16x32_bf16 v[90:93], v[178:181], v[194:197], v[90:93]
	v_mfma_f32_16x16x32_bf16 v[82:85], v[162:165], v[212:215], v[82:85]
	v_mfma_f32_16x16x32_bf16 v[74:77], v[178:181], v[212:215], v[74:77]
	v_mfma_f32_16x16x32_bf16 v[70:73], v[162:165], v[220:223], v[70:73]
	v_mfma_f32_16x16x32_bf16 v[66:69], v[178:181], v[220:223], v[66:69]
	v_mfma_f32_16x16x32_bf16 v[114:117], v[166:169], v[190:193], v[114:117]
	v_mfma_f32_16x16x32_bf16 v[106:109], v[182:185], v[190:193], v[106:109]
	v_mfma_f32_16x16x32_bf16 v[98:101], v[166:169], v[198:201], v[98:101]
	v_mfma_f32_16x16x32_bf16 v[90:93], v[182:185], v[198:201], v[90:93]
	v_mfma_f32_16x16x32_bf16 v[82:85], v[166:169], v[216:219], v[82:85]
	v_mfma_f32_16x16x32_bf16 v[74:77], v[182:185], v[216:219], v[74:77]
	v_mfma_f32_16x16x32_bf16 v[70:73], v[166:169], v[224:227], v[70:73]
	v_mfma_f32_16x16x32_bf16 v[66:69], v[182:185], v[224:227], v[66:69]
	s_setprio 0
	s_barrier
; #define PG8_STAGE(bufoff, gbase, voff) do { _Pragma("unroll") for (int _i = 0; _i < 2; ++_i) \
;         __builtin_amdgcn_global_load_lds((const unsigned*)((const char*)(gbase) + (voff)[_i]), (LAS unsigned*)(lds + (bufoff) + ldsw + _i * 8192), 16, 0, 0); } while (0)
; #define PG8_LDA(dst, b, h) do { _Pragma("unroll") for (int m = 0; m < 4; ++m) _Pragma("unroll") for (int k = 0; k < 2; ++k) dst[m][k] = *(const LAS bf16x8*)(lds + PG8_SA(b, h) + aoff + m * 2048 + k * 1024); } while (0)
; #define PG8_MMA(ai, bj, At, Bt) do { __builtin_amdgcn_s_setprio(1); _Pragma("unroll") for (int m = 0; m < 4; ++m) _Pragma("unroll") for (int n = 0; n < 2; ++n) _Pragma("unroll") for (int k = 0; k < 2; ++k) \
;         acc[ai][bj][m][n] = __builtin_amdgcn_mfma_f32_16x16x32_bf16(Bt[n][k], At[m][k], acc[ai][bj][m][n], 0, 0, 0); __builtin_amdgcn_s_setprio(0); } while (0)
; #define PG8_WAIT_V(n) asm volatile("s_waitcnt vmcnt(" #n ")" ::: "memory")
; #define PG8_WAIT_L(n) asm volatile("s_waitcnt lgkmcnt(" #n ")" ::: "memory")
; #define PG8_BAR __builtin_amdgcn_s_barrier()
; #define PG8_SCHED __builtin_amdgcn_sched_barrier(0)
; template <class Epi>
; __device__ __forceinline__ void gemm_phase(LAS unsigned char* lds, const Gemm g, const StaticOrder& S, const Epi& E, const int tid) {
;     ...
;         for (int t = 0; t < ntt; t += 2) {
;             const bool last = (t == ntt - 2);
;             const bool s1 = Epi::TWO && (t >= nt), s2 = Epi::TWO && (t + 2 >= nt);
;     ...
;             PG8_LDA(At, 1, 1); PG8_STAGE(PG8_SB(1, 0), b3, voffB); PG8_STAGE(PG8_SB(1, 1), b3 + bhs, voffB); PG8_STAGE(PG8_SA(1, 0), a3, voffA);
;             PG8_WAIT_V(8); PG8_WAIT_L(0); PG8_BAR; PG8_MMA(1, 0, At, B0); PG8_MMA(1, 1, At, B1); PG8_BAR; PG8_SCHED;
	s_add_i32 s30, s48, s37
	v_lshl_add_u64 v[172:173], v[172:173], 0, s[70:71]
	s_mov_b32 m0, s30
	ds_read_b128 v[186:189], v144 offset:49152
	global_load_lds_dwordx4 v[172:173], off
	ds_read_b128 v[190:193], v144 offset:50176
	ds_read_b128 v[194:197], v144 offset:51200
	s_add_i32 m0, s30, 0x2000
	s_add_u32 s28, s28, 0x8080
	v_lshl_add_u64 v[172:173], v[174:175], 0, s[70:71]
	s_addc_u32 s29, s29, 0
	s_add_i32 s30, s49, s37
	global_load_lds_dwordx4 v[172:173], off
	ds_read_b128 v[198:201], v144 offset:52224
	ds_read_b128 v[212:215], v144 offset:53248
	s_mov_b32 m0, s30
	v_lshl_add_u64 v[172:173], s[28:29], 0, v[0:1]
	global_load_lds_dwordx4 v[172:173], off
	ds_read_b128 v[216:219], v144 offset:54272
	ds_read_b128 v[220:223], v144 offset:55296
	s_add_i32 m0, s30, 0x2000
	v_lshl_add_u64 v[172:173], s[28:29], 0, v[134:135]
	global_load_lds_dwordx4 v[172:173], off
	ds_read_b128 v[224:227], v144 offset:56320
	s_mov_b32 m0, s40
	v_lshl_add_u64 v[172:173], v[176:177], 0, s[70:71]
	global_load_lds_dwordx4 v[172:173], off
	s_mov_b32 m0, s41
	v_lshl_add_u64 v[172:173], v[228:229], 0, s[70:71]
	global_load_lds_dwordx4 v[172:173], off
	s_waitcnt vmcnt(8)
	s_waitcnt lgkmcnt(0)
	s_barrier
	s_setprio 1
	s_waitcnt lgkmcnt(0)
	v_mfma_f32_16x16x32_bf16 v[62:65], v[146:149], v[186:189], v[62:65]
	v_mfma_f32_16x16x32_bf16 v[58:61], v[154:157], v[186:189], v[58:61]
	v_mfma_f32_16x16x32_bf16 v[54:57], v[146:149], v[194:197], v[54:57]
	v_mfma_f32_16x16x32_bf16 v[46:49], v[154:157], v[194:197], v[46:49]
	v_mfma_f32_16x16x32_bf16 v[38:41], v[146:149], v[212:215], v[38:41]
	v_mfma_f32_16x16x32_bf16 v[30:33], v[154:157], v[212:215], v[30:33]
	v_mfma_f32_16x16x32_bf16 v[22:25], v[146:149], v[220:223], v[22:25]
	v_mfma_f32_16x16x32_bf16 v[14:17], v[154:157], v[220:223], v[14:17]
	v_mfma_f32_16x16x32_bf16 v[62:65], v[150:153], v[190:193], v[62:65]
	v_mfma_f32_16x16x32_bf16 v[58:61], v[158:161], v[190:193], v[58:61]
	v_mfma_f32_16x16x32_bf16 v[54:57], v[150:153], v[198:201], v[54:57]
	v_mfma_f32_16x16x32_bf16 v[46:49], v[158:161], v[198:201], v[46:49]
	v_mfma_f32_16x16x32_bf16 v[38:41], v[150:153], v[216:219], v[38:41]
	v_mfma_f32_16x16x32_bf16 v[30:33], v[158:161], v[216:219], v[30:33]
	v_mfma_f32_16x16x32_bf16 v[22:25], v[150:153], v[224:227], v[22:25]
	v_mfma_f32_16x16x32_bf16 v[14:17], v[158:161], v[224:227], v[14:17]
	s_setprio 0
	s_setprio 1
	v_mfma_f32_16x16x32_bf16 v[50:53], v[162:165], v[186:189], v[50:53]
	v_mfma_f32_16x16x32_bf16 v[42:45], v[178:181], v[186:189], v[42:45]
	v_mfma_f32_16x16x32_bf16 v[34:37], v[162:165], v[194:197], v[34:37]
	v_mfma_f32_16x16x32_bf16 v[26:29], v[178:181], v[194:197], v[26:29]
	v_mfma_f32_16x16x32_bf16 v[18:21], v[162:165], v[212:215], v[18:21]
	v_mfma_f32_16x16x32_bf16 v[10:13], v[178:181], v[212:215], v[10:13]
	v_mfma_f32_16x16x32_bf16 v[6:9], v[162:165], v[220:223], v[6:9]
	v_mfma_f32_16x16x32_bf16 v[2:5], v[178:181], v[220:223], v[2:5]
	v_mfma_f32_16x16x32_bf16 v[50:53], v[166:169], v[190:193], v[50:53]
	v_mfma_f32_16x16x32_bf16 v[42:45], v[182:185], v[190:193], v[42:45]
	v_mfma_f32_16x16x32_bf16 v[34:37], v[166:169], v[198:201], v[34:37]
	v_mfma_f32_16x16x32_bf16 v[26:29], v[182:185], v[198:201], v[26:29]
	v_mfma_f32_16x16x32_bf16 v[18:21], v[166:169], v[216:219], v[18:21]
	v_mfma_f32_16x16x32_bf16 v[10:13], v[182:185], v[216:219], v[10:13]
	v_mfma_f32_16x16x32_bf16 v[6:9], v[166:169], v[224:227], v[6:9]
	v_mfma_f32_16x16x32_bf16 v[2:5], v[182:185], v[224:227], v[2:5]
	s_setprio 0
	s_barrier
	s_add_i32 s47, s47, 2
	s_add_u32 s45, s45, 0x100
	s_addc_u32 s46, s46, 0
	s_add_u32 s26, s26, 0x100
	s_addc_u32 s27, s27, 0
	s_cmp_gt_u32 s47, 29
	s_cbranch_scc0 .LBB0_844
	s_and_b64 vcc, exec, s[10:11]
	s_cbranch_vccz .LBB0_847
	s_barrier

; #define PG8_STAGE(bufoff, gbase, voff) do { _Pragma("unroll") for (int _i = 0; _i < 2; ++_i) \
;         __builtin_amdgcn_global_load_lds((const unsigned*)((const char*)(gbase) + (voff)[_i]), (LAS unsigned*)(lds + (bufoff) + ldsw + _i * 8192), 16, 0, 0); } while (0)
; #define PG8_LDA(dst, b, h) do { _Pragma("unroll") for (int m = 0; m < 4; ++m) _Pragma("unroll") for (int k = 0; k < 2; ++k) dst[m][k] = *(const LAS bf16x8*)(lds + PG8_SA(b, h) + aoff + m * 2048 + k * 1024); } while (0)
; #define PG8_LDB(dst, b, h) do { _Pragma("unroll") for (int n = 0; n < 2; ++n) _Pragma("unroll") for (int k = 0; k < 2; ++k) dst[n][k] = *(const LAS bf16x8*)(lds + PG8_SB(b, h) + boff + n * 2048 + k * 1024); } while (0)
; #define PG8_MMA(ai, bj, At, Bt) do { __builtin_amdgcn_s_setprio(1); _Pragma("unroll") for (int m = 0; m < 4; ++m) _Pragma("unroll") for (int n = 0; n < 2; ++n) _Pragma("unroll") for (int k = 0; k < 2; ++k) \
;         acc[ai][bj][m][n] = __builtin_amdgcn_mfma_f32_16x16x32_bf16(Bt[n][k], At[m][k], acc[ai][bj][m][n], 0, 0, 0); __builtin_amdgcn_s_setprio(0); } while (0)
; #define PG8_WAIT_V(n) asm volatile("s_waitcnt vmcnt(" #n ")" ::: "memory")
; #define PG8_WAIT_L(n) asm volatile("s_waitcnt lgkmcnt(" #n ")" ::: "memory")
; #define PG8_BAR __builtin_amdgcn_s_barrier()
; #define PG8_SCHED __builtin_amdgcn_sched_barrier(0)
; template <class Epi>
; __device__ __forceinline__ void gemm_phase(LAS unsigned char* lds, const Gemm g, const StaticOrder& S, const Epi& E, const int tid) {
;     ...
;             PG8_LDB(B0, 0, 0); PG8_LDB(B1, 0, 1); PG8_SCHED; PG8_LDA(At, 0, 0); PG8_STAGE(PG8_SA(1, 1), a1 + hstep, voffA);
;             PG8_WAIT_V(8); PG8_WAIT_L(0); PG8_BAR; PG8_MMA(0, 0, At, B0); PG8_MMA(0, 1, At, B1); PG8_BAR; PG8_SCHED;
;             PG8_LDA(At, 0, 1); PG8_STAGE(PG8_SB(0, 0), b2, voffB); PG8_STAGE(PG8_SB(0, 1), b2 + bhs, voffB); PG8_STAGE(PG8_SA(0, 0), a2, voffA);
;             PG8_WAIT_V(8); PG8_WAIT_L(0); PG8_BAR; PG8_MMA(1, 0, At, B0); PG8_MMA(1, 1, At, B1); PG8_BAR; PG8_SCHED;
.LBB0_861:
	s_add_u32 s30, s28, 0xfff80080
	s_addc_u32 s31, s29, -1
	s_add_i32 s51, 0, 0x10000
	s_cmp_eq_u32 s50, 28
	s_cselect_b32 s35, s17, s31
	s_cselect_b32 s34, s46, s30
	v_add_u32_e32 v145, s51, v142
	s_cselect_b32 s31, s15, s49
	s_cselect_b32 s30, s47, s48
	s_add_i32 s54, 0, 0x14000
	ds_read_b128 v[146:149], v145
	ds_read_b128 v[150:153], v145 offset:1024
	ds_read_b128 v[154:157], v145 offset:2048
	ds_read_b128 v[158:161], v145 offset:3072
	v_add_u32_e32 v145, s54, v142
	ds_read_b128 v[162:165], v145
	ds_read_b128 v[166:169], v145 offset:1024
	ds_read_b128 v[178:181], v145 offset:2048
	ds_read_b128 v[182:185], v145 offset:3072
	v_lshl_add_u64 v[172:173], s[28:29], 0, v[138:139]
	s_add_i32 m0, s25, 0xc000
	ds_read_b128 v[186:189], v144
	global_load_lds_dwordx4 v[172:173], off
	ds_read_b128 v[190:193], v144 offset:1024
	ds_read_b128 v[194:197], v144 offset:2048
	s_add_i32 m0, s25, 0xe000
	v_lshl_add_u64 v[172:173], s[28:29], 0, v[136:137]
	global_load_lds_dwordx4 v[172:173], off
	ds_read_b128 v[198:201], v144 offset:3072
	ds_read_b128 v[212:215], v144 offset:4096
	ds_read_b128 v[216:219], v144 offset:5120
	ds_read_b128 v[220:223], v144 offset:6144
	ds_read_b128 v[224:227], v144 offset:7168
	s_waitcnt vmcnt(8)
	s_waitcnt lgkmcnt(0)
	s_barrier
	s_setprio 1
	s_waitcnt lgkmcnt(0)
	v_mfma_f32_16x16x32_bf16 v[126:129], v[146:149], v[186:189], v[126:129]
	v_mfma_f32_16x16x32_bf16 v[122:125], v[154:157], v[186:189], v[122:125]
	v_mfma_f32_16x16x32_bf16 v[118:121], v[146:149], v[194:197], v[118:121]
	v_mfma_f32_16x16x32_bf16 v[110:113], v[154:157], v[194:197], v[110:113]
	v_mfma_f32_16x16x32_bf16 v[102:105], v[146:149], v[212:215], v[102:105]
	v_mfma_f32_16x16x32_bf16 v[94:97], v[154:157], v[212:215], v[94:97]
	v_mfma_f32_16x16x32_bf16 v[86:89], v[146:149], v[220:223], v[86:89]
	v_mfma_f32_16x16x32_bf16 v[78:81], v[154:157], v[220:223], v[78:81]
	v_mfma_f32_16x16x32_bf16 v[126:129], v[150:153], v[190:193], v[126:129]
	v_mfma_f32_16x16x32_bf16 v[122:125], v[158:161], v[190:193], v[122:125]
	v_mfma_f32_16x16x32_bf16 v[118:121], v[150:153], v[198:201], v[118:121]
	v_mfma_f32_16x16x32_bf16 v[110:113], v[158:161], v[198:201], v[110:113]
	v_mfma_f32_16x16x32_bf16 v[102:105], v[150:153], v[216:219], v[102:105]
	v_mfma_f32_16x16x32_bf16 v[94:97], v[158:161], v[216:219], v[94:97]
	v_mfma_f32_16x16x32_bf16 v[86:89], v[150:153], v[224:227], v[86:89]
	v_mfma_f32_16x16x32_bf16 v[78:81], v[158:161], v[224:227], v[78:81]
	s_setprio 0
	s_setprio 1
	v_mfma_f32_16x16x32_bf16 v[114:117], v[162:165], v[186:189], v[114:117]
	v_mfma_f32_16x16x32_bf16 v[106:109], v[178:181], v[186:189], v[106:109]
	v_mfma_f32_16x16x32_bf16 v[98:101], v[162:165], v[194:197], v[98:101]
	v_mfma_f32_16x16x32_bf16 v[90:93], v[178:181], v[194:197], v[90:93]
	v_mfma_f32_16x16x32_bf16 v[82:85], v[162:165], v[212:215], v[82:85]
	v_mfma_f32_16x16x32_bf16 v[74:77], v[178:181], v[212:215], v[74:77]
	v_mfma_f32_16x16x32_bf16 v[70:73], v[162:165], v[220:223], v[70:73]
	v_mfma_f32_16x16x32_bf16 v[66:69], v[178:181], v[220:223], v[66:69]
	v_mfma_f32_16x16x32_bf16 v[114:117], v[166:169], v[190:193], v[114:117]
	v_mfma_f32_16x16x32_bf16 v[106:109], v[182:185], v[190:193], v[106:109]
	v_mfma_f32_16x16x32_bf16 v[98:101], v[166:169], v[198:201], v[98:101]
	v_mfma_f32_16x16x32_bf16 v[90:93], v[182:185], v[198:201], v[90:93]
	v_mfma_f32_16x16x32_bf16 v[82:85], v[166:169], v[216:219], v[82:85]
	v_mfma_f32_16x16x32_bf16 v[74:77], v[182:185], v[216:219], v[74:77]
	v_mfma_f32_16x16x32_bf16 v[70:73], v[166:169], v[224:227], v[70:73]
	v_mfma_f32_16x16x32_bf16 v[66:69], v[182:185], v[224:227], v[66:69]
	s_setprio 0
	s_barrier
	s_add_i32 s51, s51, s40
	v_lshl_add_u64 v[172:173], s[30:31], 0, v[0:1]
	s_mov_b32 m0, s51
	ds_read_b128 v[186:189], v144 offset:16384
	global_load_lds_dwordx4 v[172:173], off
	ds_read_b128 v[190:193], v144 offset:17408
	ds_read_b128 v[194:197], v144 offset:18432
	s_add_i32 m0, s51, 0x2000
	s_add_u32 s52, s30, 0x8000
	v_lshl_add_u64 v[174:175], s[30:31], 0, v[134:135]
	s_addc_u32 s53, s31, 0
	s_add_i32 s51, s54, s40
	global_load_lds_dwordx4 v[174:175], off
	ds_read_b128 v[198:201], v144 offset:19456
	ds_read_b128 v[212:215], v144 offset:20480
	v_lshl_add_u64 v[176:177], s[52:53], 0, v[0:1]
	s_mov_b32 m0, s51
	v_lshl_add_u64 v[228:229], s[34:35], 0, v[132:133]
	global_load_lds_dwordx4 v[176:177], off
	ds_read_b128 v[216:219], v144 offset:21504
	ds_read_b128 v[220:223], v144 offset:22528
	s_add_i32 m0, s51, 0x2000
	v_lshl_add_u64 v[176:177], s[52:53], 0, v[134:135]
	global_load_lds_dwordx4 v[176:177], off
	ds_read_b128 v[224:227], v144 offset:23552
	s_mov_b32 m0, s25
	v_lshl_add_u64 v[176:177], s[34:35], 0, v[130:131]
	global_load_lds_dwordx4 v[176:177], off
	s_mov_b32 m0, s27
	s_nop 0
	global_load_lds_dwordx4 v[228:229], off
	s_waitcnt vmcnt(8)
	s_waitcnt lgkmcnt(0)
	s_barrier
; #define PG8_STAGE(bufoff, gbase, voff) do { _Pragma("unroll") for (int _i = 0; _i < 2; ++_i) \
;         __builtin_amdgcn_global_load_lds((const unsigned*)((const char*)(gbase) + (voff)[_i]), (LAS unsigned*)(lds + (bufoff) + ldsw + _i * 8192), 16, 0, 0); } while (0)
; #define PG8_LDA(dst, b, h) do { _Pragma("unroll") for (int m = 0; m < 4; ++m) _Pragma("unroll") for (int k = 0; k < 2; ++k) dst[m][k] = *(const LAS bf16x8*)(lds + PG8_SA(b, h) + aoff + m * 2048 + k * 1024); } while (0)
; #define PG8_LDB(dst, b, h) do { _Pragma("unroll") for (int n = 0; n < 2; ++n) _Pragma("unroll") for (int k = 0; k < 2; ++k) dst[n][k] = *(const LAS bf16x8*)(lds + PG8_SB(b, h) + boff + n * 2048 + k * 1024); } while (0)
; #define PG8_MMA(ai, bj, At, Bt) do { __builtin_amdgcn_s_setprio(1); _Pragma("unroll") for (int m = 0; m < 4; ++m) _Pragma("unroll") for (int n = 0; n < 2; ++n) _Pragma("unroll") for (int k = 0; k < 2; ++k) \
;         acc[ai][bj][m][n] = __builtin_amdgcn_mfma_f32_16x16x32_bf16(Bt[n][k], At[m][k], acc[ai][bj][m][n], 0, 0, 0); __builtin_amdgcn_s_setprio(0); } while (0)
; #define PG8_WAIT_V(n) asm volatile("s_waitcnt vmcnt(" #n ")" ::: "memory")
; #define PG8_WAIT_L(n) asm volatile("s_waitcnt lgkmcnt(" #n ")" ::: "memory")
; #define PG8_BAR __builtin_amdgcn_s_barrier()
; #define PG8_SCHED __builtin_amdgcn_sched_barrier(0)
; template <class Epi>
; __device__ __forceinline__ void gemm_phase(LAS unsigned char* lds, const Gemm g, const StaticOrder& S, const Epi& E, const int tid) {
;     ...
;             PG8_WAIT_V(8); PG8_WAIT_L(0); PG8_BAR; PG8_MMA(0, 0, At, B0); PG8_MMA(0, 1, At, B1); PG8_BAR; PG8_SCHED;
;             PG8_LDA(At, 0, 1); PG8_STAGE(PG8_SB(0, 0), b2, voffB); PG8_STAGE(PG8_SB(0, 1), b2 + bhs, voffB); PG8_STAGE(PG8_SA(0, 0), a2, voffA);
;             PG8_WAIT_V(8); PG8_WAIT_L(0); PG8_BAR; PG8_MMA(1, 0, At, B0); PG8_MMA(1, 1, At, B1); PG8_BAR; PG8_SCHED;
;             PG8_LDB(B0, 1, 0); PG8_LDB(B1, 1, 1); PG8_SCHED; PG8_LDA(At, 1, 0); PG8_STAGE(PG8_SA(0, 1), a2 + hstep, voffA);
;             PG8_WAIT_V(8); PG8_WAIT_L(0); PG8_BAR; PG8_MMA(0, 0, At, B0); PG8_MMA(0, 1, At, B1); PG8_BAR; PG8_SCHED;
	s_setprio 1
	s_waitcnt lgkmcnt(0)
	v_mfma_f32_16x16x32_bf16 v[62:65], v[146:149], v[186:189], v[62:65]
	v_mfma_f32_16x16x32_bf16 v[58:61], v[154:157], v[186:189], v[58:61]
	v_mfma_f32_16x16x32_bf16 v[54:57], v[146:149], v[194:197], v[54:57]
	v_mfma_f32_16x16x32_bf16 v[46:49], v[154:157], v[194:197], v[46:49]
	v_mfma_f32_16x16x32_bf16 v[38:41], v[146:149], v[212:215], v[38:41]
	v_mfma_f32_16x16x32_bf16 v[30:33], v[154:157], v[212:215], v[30:33]
	v_mfma_f32_16x16x32_bf16 v[22:25], v[146:149], v[220:223], v[22:25]
	v_mfma_f32_16x16x32_bf16 v[14:17], v[154:157], v[220:223], v[14:17]
	v_mfma_f32_16x16x32_bf16 v[62:65], v[150:153], v[190:193], v[62:65]
	v_mfma_f32_16x16x32_bf16 v[58:61], v[158:161], v[190:193], v[58:61]
	v_mfma_f32_16x16x32_bf16 v[54:57], v[150:153], v[198:201], v[54:57]
	v_mfma_f32_16x16x32_bf16 v[46:49], v[158:161], v[198:201], v[46:49]
	v_mfma_f32_16x16x32_bf16 v[38:41], v[150:153], v[216:219], v[38:41]
	v_mfma_f32_16x16x32_bf16 v[30:33], v[158:161], v[216:219], v[30:33]
	v_mfma_f32_16x16x32_bf16 v[22:25], v[150:153], v[224:227], v[22:25]
	v_mfma_f32_16x16x32_bf16 v[14:17], v[158:161], v[224:227], v[14:17]
	s_setprio 0
	s_setprio 1
	v_mfma_f32_16x16x32_bf16 v[50:53], v[162:165], v[186:189], v[50:53]
	v_mfma_f32_16x16x32_bf16 v[42:45], v[178:181], v[186:189], v[42:45]
	v_mfma_f32_16x16x32_bf16 v[34:37], v[162:165], v[194:197], v[34:37]
	v_mfma_f32_16x16x32_bf16 v[26:29], v[178:181], v[194:197], v[26:29]
	v_mfma_f32_16x16x32_bf16 v[18:21], v[162:165], v[212:215], v[18:21]
	v_mfma_f32_16x16x32_bf16 v[10:13], v[178:181], v[212:215], v[10:13]
	v_mfma_f32_16x16x32_bf16 v[6:9], v[162:165], v[220:223], v[6:9]
	v_mfma_f32_16x16x32_bf16 v[2:5], v[178:181], v[220:223], v[2:5]
	v_mfma_f32_16x16x32_bf16 v[50:53], v[166:169], v[190:193], v[50:53]
	v_mfma_f32_16x16x32_bf16 v[42:45], v[182:185], v[190:193], v[42:45]
	v_mfma_f32_16x16x32_bf16 v[34:37], v[166:169], v[198:201], v[34:37]
	v_mfma_f32_16x16x32_bf16 v[26:29], v[182:185], v[198:201], v[26:29]
	v_mfma_f32_16x16x32_bf16 v[18:21], v[166:169], v[216:219], v[18:21]
	v_mfma_f32_16x16x32_bf16 v[10:13], v[182:185], v[216:219], v[10:13]
	v_mfma_f32_16x16x32_bf16 v[6:9], v[166:169], v[224:227], v[6:9]
	v_mfma_f32_16x16x32_bf16 v[2:5], v[182:185], v[224:227], v[2:5]
	s_setprio 0
	s_barrier
	s_add_i32 s51, 0, 0x18000
	v_add_u32_e32 v145, s51, v142
	s_add_i32 s52, 0, 0x1c000
	ds_read_b128 v[146:149], v145
	ds_read_b128 v[150:153], v145 offset:1024
	ds_read_b128 v[154:157], v145 offset:2048
	ds_read_b128 v[158:161], v145 offset:3072
	v_add_u32_e32 v145, s52, v142
	ds_read_b128 v[162:165], v145
	ds_read_b128 v[166:169], v145 offset:1024
	ds_read_b128 v[178:181], v145 offset:2048
	ds_read_b128 v[182:185], v145 offset:3072
	s_add_u32 s34, s34, 0x80000
	s_addc_u32 s35, s35, 0
	s_mov_b32 m0, s41
	v_lshl_add_u64 v[230:231], s[34:35], 0, v[130:131]
	ds_read_b128 v[186:189], v144 offset:32768
	global_load_lds_dwordx4 v[230:231], off
	ds_read_b128 v[190:193], v144 offset:33792
	ds_read_b128 v[194:197], v144 offset:34816
	s_mov_b32 m0, s42
	v_lshl_add_u64 v[230:231], s[34:35], 0, v[132:133]
	global_load_lds_dwordx4 v[230:231], off
	ds_read_b128 v[198:201], v144 offset:35840
	ds_read_b128 v[212:215], v144 offset:36864
	ds_read_b128 v[216:219], v144 offset:37888
	ds_read_b128 v[220:223], v144 offset:38912
	ds_read_b128 v[224:227], v144 offset:39936
	s_waitcnt vmcnt(8)
	s_waitcnt lgkmcnt(0)
	s_barrier
	s_setprio 1
	s_waitcnt lgkmcnt(0)
	v_mfma_f32_16x16x32_bf16 v[126:129], v[146:149], v[186:189], v[126:129]
	v_mfma_f32_16x16x32_bf16 v[122:125], v[154:157], v[186:189], v[122:125]
	v_mfma_f32_16x16x32_bf16 v[118:121], v[146:149], v[194:197], v[118:121]
	v_mfma_f32_16x16x32_bf16 v[110:113], v[154:157], v[194:197], v[110:113]
	v_mfma_f32_16x16x32_bf16 v[102:105], v[146:149], v[212:215], v[102:105]
	v_mfma_f32_16x16x32_bf16 v[94:97], v[154:157], v[212:215], v[94:97]
	v_mfma_f32_16x16x32_bf16 v[86:89], v[146:149], v[220:223], v[86:89]
	v_mfma_f32_16x16x32_bf16 v[78:81], v[154:157], v[220:223], v[78:81]
	v_mfma_f32_16x16x32_bf16 v[126:129], v[150:153], v[190:193], v[126:129]
	v_mfma_f32_16x16x32_bf16 v[122:125], v[158:161], v[190:193], v[122:125]
	v_mfma_f32_16x16x32_bf16 v[118:121], v[150:153], v[198:201], v[118:121]
	v_mfma_f32_16x16x32_bf16 v[110:113], v[158:161], v[198:201], v[110:113]
	v_mfma_f32_16x16x32_bf16 v[102:105], v[150:153], v[216:219], v[102:105]
	v_mfma_f32_16x16x32_bf16 v[94:97], v[158:161], v[216:219], v[94:97]
	v_mfma_f32_16x16x32_bf16 v[86:89], v[150:153], v[224:227], v[86:89]
	v_mfma_f32_16x16x32_bf16 v[78:81], v[158:161], v[224:227], v[78:81]
	s_setprio 0
	s_setprio 1
	v_mfma_f32_16x16x32_bf16 v[114:117], v[162:165], v[186:189], v[114:117]
	v_mfma_f32_16x16x32_bf16 v[106:109], v[178:181], v[186:189], v[106:109]
	v_mfma_f32_16x16x32_bf16 v[98:101], v[162:165], v[194:197], v[98:101]
	v_mfma_f32_16x16x32_bf16 v[90:93], v[178:181], v[194:197], v[90:93]
	v_mfma_f32_16x16x32_bf16 v[82:85], v[162:165], v[212:215], v[82:85]
	v_mfma_f32_16x16x32_bf16 v[74:77], v[178:181], v[212:215], v[74:77]
	v_mfma_f32_16x16x32_bf16 v[70:73], v[162:165], v[220:223], v[70:73]
	v_mfma_f32_16x16x32_bf16 v[66:69], v[178:181], v[220:223], v[66:69]
	v_mfma_f32_16x16x32_bf16 v[114:117], v[166:169], v[190:193], v[114:117]
	v_mfma_f32_16x16x32_bf16 v[106:109], v[182:185], v[190:193], v[106:109]
	v_mfma_f32_16x16x32_bf16 v[98:101], v[166:169], v[198:201], v[98:101]
	v_mfma_f32_16x16x32_bf16 v[90:93], v[182:185], v[198:201], v[90:93]
	v_mfma_f32_16x16x32_bf16 v[82:85], v[166:169], v[216:219], v[82:85]
	v_mfma_f32_16x16x32_bf16 v[74:77], v[182:185], v[216:219], v[74:77]
	v_mfma_f32_16x16x32_bf16 v[70:73], v[166:169], v[224:227], v[70:73]
	v_mfma_f32_16x16x32_bf16 v[66:69], v[182:185], v[224:227], v[66:69]
	s_setprio 0
	s_barrier
; #define PG8_STAGE(bufoff, gbase, voff) do { _Pragma("unroll") for (int _i = 0; _i < 2; ++_i) \
;         __builtin_amdgcn_global_load_lds((const unsigned*)((const char*)(gbase) + (voff)[_i]), (LAS unsigned*)(lds + (bufoff) + ldsw + _i * 8192), 16, 0, 0); } while (0)
; #define PG8_LDA(dst, b, h) do { _Pragma("unroll") for (int m = 0; m < 4; ++m) _Pragma("unroll") for (int k = 0; k < 2; ++k) dst[m][k] = *(const LAS bf16x8*)(lds + PG8_SA(b, h) + aoff + m * 2048 + k * 1024); } while (0)
; #define PG8_MMA(ai, bj, At, Bt) do { __builtin_amdgcn_s_setprio(1); _Pragma("unroll") for (int m = 0; m < 4; ++m) _Pragma("unroll") for (int n = 0; n < 2; ++n) _Pragma("unroll") for (int k = 0; k < 2; ++k) \
;         acc[ai][bj][m][n] = __builtin_amdgcn_mfma_f32_16x16x32_bf16(Bt[n][k], At[m][k], acc[ai][bj][m][n], 0, 0, 0); __builtin_amdgcn_s_setprio(0); } while (0)
; #define PG8_WAIT_V(n) asm volatile("s_waitcnt vmcnt(" #n ")" ::: "memory")
; #define PG8_WAIT_L(n) asm volatile("s_waitcnt lgkmcnt(" #n ")" ::: "memory")
; #define PG8_BAR __builtin_amdgcn_s_barrier()
; #define PG8_SCHED __builtin_amdgcn_sched_barrier(0)
; template <class Epi>
; __device__ __forceinline__ void gemm_phase(LAS unsigned char* lds, const Gemm g, const StaticOrder& S, const Epi& E, const int tid) {
;     ...
;         for (int t = 0; t < ntt; t += 2) {
;             const bool last = (t == ntt - 2);
;             const bool s1 = Epi::TWO && (t >= nt), s2 = Epi::TWO && (t + 2 >= nt);
;     ...
;             PG8_LDA(At, 1, 1); PG8_STAGE(PG8_SB(1, 0), b3, voffB); PG8_STAGE(PG8_SB(1, 1), b3 + bhs, voffB); PG8_STAGE(PG8_SA(1, 0), a3, voffA);
;             PG8_WAIT_V(8); PG8_WAIT_L(0); PG8_BAR; PG8_MMA(1, 0, At, B0); PG8_MMA(1, 1, At, B1); PG8_BAR; PG8_SCHED;
	s_add_i32 s34, s51, s40
	v_lshl_add_u64 v[172:173], v[172:173], 0, s[70:71]
	s_mov_b32 m0, s34
	ds_read_b128 v[186:189], v144 offset:49152
	global_load_lds_dwordx4 v[172:173], off
	ds_read_b128 v[190:193], v144 offset:50176
	ds_read_b128 v[194:197], v144 offset:51200
	s_add_i32 m0, s34, 0x2000
	s_add_u32 s30, s30, 0x8080
	v_lshl_add_u64 v[172:173], v[174:175], 0, s[70:71]
	s_addc_u32 s31, s31, 0
	s_add_i32 s34, s52, s40
	global_load_lds_dwordx4 v[172:173], off
	ds_read_b128 v[198:201], v144 offset:52224
	ds_read_b128 v[212:215], v144 offset:53248
	s_mov_b32 m0, s34
	v_lshl_add_u64 v[172:173], s[30:31], 0, v[0:1]
	global_load_lds_dwordx4 v[172:173], off
	ds_read_b128 v[216:219], v144 offset:54272
	ds_read_b128 v[220:223], v144 offset:55296
	s_add_i32 m0, s34, 0x2000
	v_lshl_add_u64 v[172:173], s[30:31], 0, v[134:135]
	global_load_lds_dwordx4 v[172:173], off
	ds_read_b128 v[224:227], v144 offset:56320
	s_mov_b32 m0, s43
	v_lshl_add_u64 v[172:173], v[176:177], 0, s[70:71]
	global_load_lds_dwordx4 v[172:173], off
	s_mov_b32 m0, s44
	v_lshl_add_u64 v[172:173], v[228:229], 0, s[70:71]
	global_load_lds_dwordx4 v[172:173], off
	s_waitcnt vmcnt(8)
	s_waitcnt lgkmcnt(0)
	s_barrier
	s_setprio 1
	s_waitcnt lgkmcnt(0)
	v_mfma_f32_16x16x32_bf16 v[62:65], v[146:149], v[186:189], v[62:65]
	v_mfma_f32_16x16x32_bf16 v[58:61], v[154:157], v[186:189], v[58:61]
	v_mfma_f32_16x16x32_bf16 v[54:57], v[146:149], v[194:197], v[54:57]
	v_mfma_f32_16x16x32_bf16 v[46:49], v[154:157], v[194:197], v[46:49]
	v_mfma_f32_16x16x32_bf16 v[38:41], v[146:149], v[212:215], v[38:41]
	v_mfma_f32_16x16x32_bf16 v[30:33], v[154:157], v[212:215], v[30:33]
	v_mfma_f32_16x16x32_bf16 v[22:25], v[146:149], v[220:223], v[22:25]
	v_mfma_f32_16x16x32_bf16 v[14:17], v[154:157], v[220:223], v[14:17]
	v_mfma_f32_16x16x32_bf16 v[62:65], v[150:153], v[190:193], v[62:65]
	v_mfma_f32_16x16x32_bf16 v[58:61], v[158:161], v[190:193], v[58:61]
	v_mfma_f32_16x16x32_bf16 v[54:57], v[150:153], v[198:201], v[54:57]
	v_mfma_f32_16x16x32_bf16 v[46:49], v[158:161], v[198:201], v[46:49]
	v_mfma_f32_16x16x32_bf16 v[38:41], v[150:153], v[216:219], v[38:41]
	v_mfma_f32_16x16x32_bf16 v[30:33], v[158:161], v[216:219], v[30:33]
	v_mfma_f32_16x16x32_bf16 v[22:25], v[150:153], v[224:227], v[22:25]
	v_mfma_f32_16x16x32_bf16 v[14:17], v[158:161], v[224:227], v[14:17]
	s_setprio 0
	s_setprio 1
	v_mfma_f32_16x16x32_bf16 v[50:53], v[162:165], v[186:189], v[50:53]
	v_mfma_f32_16x16x32_bf16 v[42:45], v[178:181], v[186:189], v[42:45]
	v_mfma_f32_16x16x32_bf16 v[34:37], v[162:165], v[194:197], v[34:37]
	v_mfma_f32_16x16x32_bf16 v[26:29], v[178:181], v[194:197], v[26:29]
	v_mfma_f32_16x16x32_bf16 v[18:21], v[162:165], v[212:215], v[18:21]
	v_mfma_f32_16x16x32_bf16 v[10:13], v[178:181], v[212:215], v[10:13]
	v_mfma_f32_16x16x32_bf16 v[6:9], v[162:165], v[220:223], v[6:9]
	v_mfma_f32_16x16x32_bf16 v[2:5], v[178:181], v[220:223], v[2:5]
	v_mfma_f32_16x16x32_bf16 v[50:53], v[166:169], v[190:193], v[50:53]
	v_mfma_f32_16x16x32_bf16 v[42:45], v[182:185], v[190:193], v[42:45]
	v_mfma_f32_16x16x32_bf16 v[34:37], v[166:169], v[198:201], v[34:37]
	v_mfma_f32_16x16x32_bf16 v[26:29], v[182:185], v[198:201], v[26:29]
	v_mfma_f32_16x16x32_bf16 v[18:21], v[166:169], v[216:219], v[18:21]
	v_mfma_f32_16x16x32_bf16 v[10:13], v[182:185], v[216:219], v[10:13]
	v_mfma_f32_16x16x32_bf16 v[6:9], v[166:169], v[224:227], v[6:9]
	v_mfma_f32_16x16x32_bf16 v[2:5], v[182:185], v[224:227], v[2:5]
	s_setprio 0
	s_barrier
	s_add_i32 s50, s50, 2
	s_add_u32 s48, s48, 0x100
	s_addc_u32 s49, s49, 0
	s_add_u32 s28, s28, 0x100
	s_addc_u32 s29, s29, 0
	s_cmp_gt_u32 s50, 29
	s_cbranch_scc0 .LBB0_861
	s_and_b64 vcc, exec, s[12:13]
	s_cbranch_vccz .LBB0_864
	s_barrier
